# v9 plus accumulator zeroing removed: first K iteration of each tile uses inline 0 as MFMA SrcC through an out-of-line copy selected before the pre-MMA barrier
# speedup vs baseline: 1.0043x; 1.0043x over previous
.LBB0_202:
	s_add_u32 s73, s16, 0x8000
	s_addc_u32 s74, s17, 0
	s_add_u32 s50, s18, 0x80080
	s_addc_u32 s51, s19, 0
	s_mov_b32 s75, -2
	s_mov_b64 s[16:17], s[54:55]
	s_mov_b64 s[18:19], s[52:53]
	s_branch .LBB0_204
.LBB0_203:
	v_add_u32_e32 v162, s69, v147
	v_add_u32_e32 v178, s70, v147
	ds_read_b128 v[148:151], v162
	ds_read_b128 v[152:155], v162 offset:1024
	ds_read_b128 v[158:161], v162 offset:2048
	ds_read_b128 v[162:165], v162 offset:3072
	ds_read_b128 v[166:169], v178
	ds_read_b128 v[170:173], v178 offset:1024
	ds_read_b128 v[174:177], v178 offset:2048
	ds_read_b128 v[178:181], v178 offset:3072
	s_add_u32 s45, s50, 0xfff80080
	s_addc_u32 s47, s51, -1
	s_and_b64 s[52:53], s[52:53], exec
	s_cselect_b32 s55, s19, s47
	s_cselect_b32 s54, s18, s45
	s_cselect_b32 s53, s17, s74
	s_cselect_b32 s52, s16, s73
	v_lshl_add_u64 v[214:215], s[50:51], 0, v[138:139]
	s_add_i32 m0, s49, 0xc000
	ds_read_b128 v[182:185], v157
	ds_read_b128 v[186:189], v157 offset:1024
	ds_read_b128 v[190:193], v157 offset:2048
	ds_read_b128 v[194:197], v157 offset:3072
	ds_read_b128 v[198:201], v157 offset:4096
	ds_read_b128 v[202:205], v157 offset:5120
	ds_read_b128 v[206:209], v157 offset:6144
	ds_read_b128 v[210:213], v157 offset:7168
	global_load_lds_dwordx4 v[214:215], off
	v_lshl_add_u64 v[214:215], s[50:51], 0, v[140:141]
	s_add_i32 m0, s49, 0xe000
	s_nop 0
	global_load_lds_dwordx4 v[214:215], off
	s_waitcnt vmcnt(8)
	s_waitcnt lgkmcnt(0)
	s_cmp_eq_i32 s75, -2
	s_cbranch_scc1 .Lzf_0_0
	s_barrier
	s_setprio 3
	s_waitcnt lgkmcnt(0)
	v_mfma_i32_16x16x64_i8 v[126:129], v[148:151], v[182:185], v[126:129]
	v_mfma_i32_16x16x64_i8 v[118:121], v[158:161], v[182:185], v[118:121]
	v_mfma_i32_16x16x64_i8 v[102:105], v[158:161], v[190:193], v[102:105]
	v_mfma_i32_16x16x64_i8 v[110:113], v[148:151], v[190:193], v[110:113]
	v_mfma_i32_16x16x64_i8 v[94:97], v[148:151], v[198:201], v[94:97]
	v_mfma_i32_16x16x64_i8 v[86:89], v[158:161], v[198:201], v[86:89]
	v_mfma_i32_16x16x64_i8 v[70:73], v[158:161], v[206:209], v[70:73]
	v_mfma_i32_16x16x64_i8 v[78:81], v[148:151], v[206:209], v[78:81]
	v_mfma_i32_16x16x64_i8 v[126:129], v[152:155], v[186:189], v[126:129]
	v_mfma_i32_16x16x64_i8 v[118:121], v[162:165], v[186:189], v[118:121]
	v_mfma_i32_16x16x64_i8 v[102:105], v[162:165], v[194:197], v[102:105]
	v_mfma_i32_16x16x64_i8 v[110:113], v[152:155], v[194:197], v[110:113]
	v_mfma_i32_16x16x64_i8 v[94:97], v[152:155], v[202:205], v[94:97]
	v_mfma_i32_16x16x64_i8 v[86:89], v[162:165], v[202:205], v[86:89]
	v_mfma_i32_16x16x64_i8 v[70:73], v[162:165], v[210:213], v[70:73]
	v_mfma_i32_16x16x64_i8 v[78:81], v[152:155], v[210:213], v[78:81]
	s_setprio 0
	s_setprio 3
	v_mfma_i32_16x16x64_i8 v[122:125], v[166:169], v[182:185], v[122:125]
	v_mfma_i32_16x16x64_i8 v[114:117], v[174:177], v[182:185], v[114:117]
	v_mfma_i32_16x16x64_i8 v[98:101], v[174:177], v[190:193], v[98:101]
	v_mfma_i32_16x16x64_i8 v[106:109], v[166:169], v[190:193], v[106:109]
	v_mfma_i32_16x16x64_i8 v[90:93], v[166:169], v[198:201], v[90:93]
	v_mfma_i32_16x16x64_i8 v[82:85], v[174:177], v[198:201], v[82:85]
	v_mfma_i32_16x16x64_i8 v[66:69], v[174:177], v[206:209], v[66:69]
	v_mfma_i32_16x16x64_i8 v[74:77], v[166:169], v[206:209], v[74:77]
	v_mfma_i32_16x16x64_i8 v[122:125], v[170:173], v[186:189], v[122:125]
	v_mfma_i32_16x16x64_i8 v[114:117], v[178:181], v[186:189], v[114:117]
	v_mfma_i32_16x16x64_i8 v[98:101], v[178:181], v[194:197], v[98:101]
	v_mfma_i32_16x16x64_i8 v[106:109], v[170:173], v[194:197], v[106:109]
	v_mfma_i32_16x16x64_i8 v[90:93], v[170:173], v[202:205], v[90:93]
	v_mfma_i32_16x16x64_i8 v[82:85], v[178:181], v[202:205], v[82:85]
	v_mfma_i32_16x16x64_i8 v[66:69], v[178:181], v[210:213], v[66:69]
	v_mfma_i32_16x16x64_i8 v[74:77], v[170:173], v[210:213], v[74:77]
	s_setprio 0
.Lzb_0_0:
	s_barrier
	s_add_i32 s45, s69, s43
	v_lshl_add_u64 v[214:215], s[52:53], 0, v[130:131]
	s_mov_b32 m0, s45
	ds_read_b128 v[182:185], v157 offset:16384
	ds_read_b128 v[186:189], v157 offset:17408
	ds_read_b128 v[190:193], v157 offset:18432
	ds_read_b128 v[194:197], v157 offset:19456
	ds_read_b128 v[198:201], v157 offset:20480
	ds_read_b128 v[202:205], v157 offset:21504
	ds_read_b128 v[206:209], v157 offset:22528
	ds_read_b128 v[210:213], v157 offset:23552
	global_load_lds_dwordx4 v[214:215], off
	s_add_i32 m0, s45, 0x2000
	s_add_u32 s76, s52, 0x80000
	v_lshl_add_u64 v[214:215], s[52:53], 0, v[132:133]
	s_addc_u32 s77, s53, 0
	s_add_i32 s45, s70, s43
	global_load_lds_dwordx4 v[214:215], off
	v_lshl_add_u64 v[214:215], s[76:77], 0, v[130:131]
	s_mov_b32 m0, s45
	v_lshl_add_u64 v[216:217], s[54:55], 0, v[134:135]
	global_load_lds_dwordx4 v[214:215], off
	v_lshl_add_u64 v[214:215], s[76:77], 0, v[132:133]
	s_add_i32 m0, s45, 0x2000
	s_nop 0
	global_load_lds_dwordx4 v[214:215], off
	v_lshl_add_u64 v[214:215], s[54:55], 0, v[136:137]
	s_mov_b32 m0, s49
	s_nop 0
	global_load_lds_dwordx4 v[214:215], off
	s_mov_b32 m0, s58
	s_nop 0
	global_load_lds_dwordx4 v[216:217], off
	s_waitcnt vmcnt(8)
	s_waitcnt lgkmcnt(0)
	s_cmp_eq_i32 s75, -2
	s_cbranch_scc1 .Lzf_0_1
	s_barrier
	s_setprio 3
	s_waitcnt lgkmcnt(0)
	v_mfma_i32_16x16x64_i8 v[62:65], v[148:151], v[182:185], v[62:65]
	v_mfma_i32_16x16x64_i8 v[54:57], v[158:161], v[182:185], v[54:57]
	v_mfma_i32_16x16x64_i8 v[38:41], v[158:161], v[190:193], v[38:41]
	v_mfma_i32_16x16x64_i8 v[46:49], v[148:151], v[190:193], v[46:49]
	v_mfma_i32_16x16x64_i8 v[30:33], v[148:151], v[198:201], v[30:33]
	v_mfma_i32_16x16x64_i8 v[22:25], v[158:161], v[198:201], v[22:25]
	v_mfma_i32_16x16x64_i8 v[6:9], v[158:161], v[206:209], v[6:9]
	v_mfma_i32_16x16x64_i8 v[14:17], v[148:151], v[206:209], v[14:17]
	v_mfma_i32_16x16x64_i8 v[62:65], v[152:155], v[186:189], v[62:65]
	v_mfma_i32_16x16x64_i8 v[54:57], v[162:165], v[186:189], v[54:57]
	v_mfma_i32_16x16x64_i8 v[38:41], v[162:165], v[194:197], v[38:41]
	v_mfma_i32_16x16x64_i8 v[46:49], v[152:155], v[194:197], v[46:49]
	v_mfma_i32_16x16x64_i8 v[30:33], v[152:155], v[202:205], v[30:33]
	v_mfma_i32_16x16x64_i8 v[22:25], v[162:165], v[202:205], v[22:25]
	v_mfma_i32_16x16x64_i8 v[6:9], v[162:165], v[210:213], v[6:9]
	v_mfma_i32_16x16x64_i8 v[14:17], v[152:155], v[210:213], v[14:17]
	s_setprio 0
	s_setprio 3
	v_mfma_i32_16x16x64_i8 v[58:61], v[166:169], v[182:185], v[58:61]
	v_mfma_i32_16x16x64_i8 v[50:53], v[174:177], v[182:185], v[50:53]
	v_mfma_i32_16x16x64_i8 v[34:37], v[174:177], v[190:193], v[34:37]
	v_mfma_i32_16x16x64_i8 v[42:45], v[166:169], v[190:193], v[42:45]
	v_mfma_i32_16x16x64_i8 v[26:29], v[166:169], v[198:201], v[26:29]
	v_mfma_i32_16x16x64_i8 v[18:21], v[174:177], v[198:201], v[18:21]
	v_mfma_i32_16x16x64_i8 v[2:5], v[174:177], v[206:209], v[2:5]
	v_mfma_i32_16x16x64_i8 v[10:13], v[166:169], v[206:209], v[10:13]
	v_mfma_i32_16x16x64_i8 v[58:61], v[170:173], v[186:189], v[58:61]
	v_mfma_i32_16x16x64_i8 v[50:53], v[178:181], v[186:189], v[50:53]
	v_mfma_i32_16x16x64_i8 v[34:37], v[178:181], v[194:197], v[34:37]
	v_mfma_i32_16x16x64_i8 v[42:45], v[170:173], v[194:197], v[42:45]
	v_mfma_i32_16x16x64_i8 v[26:29], v[170:173], v[202:205], v[26:29]
	v_mfma_i32_16x16x64_i8 v[18:21], v[178:181], v[202:205], v[18:21]
	v_mfma_i32_16x16x64_i8 v[2:5], v[178:181], v[210:213], v[2:5]
	v_mfma_i32_16x16x64_i8 v[10:13], v[170:173], v[210:213], v[10:13]
	s_setprio 0
.Lzb_0_1:
	s_barrier
	s_add_i32 s45, 0, 0x18000
	s_add_i32 s47, 0, 0x1c000
	v_add_u32_e32 v162, s45, v147
	v_add_u32_e32 v178, s47, v147
	ds_read_b128 v[148:151], v162
	ds_read_b128 v[152:155], v162 offset:1024
	ds_read_b128 v[158:161], v162 offset:2048
	ds_read_b128 v[162:165], v162 offset:3072
	ds_read_b128 v[166:169], v178
	ds_read_b128 v[170:173], v178 offset:1024
	ds_read_b128 v[174:177], v178 offset:2048
	ds_read_b128 v[178:181], v178 offset:3072
	s_add_u32 s54, s54, 0x80000
	s_addc_u32 s55, s55, 0
	s_mov_b32 m0, s59
	v_lshl_add_u64 v[218:219], s[54:55], 0, v[136:137]
	ds_read_b128 v[182:185], v157 offset:32768
	ds_read_b128 v[186:189], v157 offset:33792
	ds_read_b128 v[190:193], v157 offset:34816
	ds_read_b128 v[194:197], v157 offset:35840
	ds_read_b128 v[198:201], v157 offset:36864
	ds_read_b128 v[202:205], v157 offset:37888
	ds_read_b128 v[206:209], v157 offset:38912
	ds_read_b128 v[210:213], v157 offset:39936
	global_load_lds_dwordx4 v[218:219], off
	v_lshl_add_u64 v[218:219], s[54:55], 0, v[134:135]
	s_mov_b32 m0, s60
	s_nop 0
	global_load_lds_dwordx4 v[218:219], off
	s_waitcnt vmcnt(8)
	s_waitcnt lgkmcnt(0)
	s_barrier
	s_setprio 3
	s_waitcnt lgkmcnt(0)
	v_mfma_i32_16x16x64_i8 v[126:129], v[148:151], v[182:185], v[126:129]
	v_mfma_i32_16x16x64_i8 v[118:121], v[158:161], v[182:185], v[118:121]
	v_mfma_i32_16x16x64_i8 v[102:105], v[158:161], v[190:193], v[102:105]
	v_mfma_i32_16x16x64_i8 v[110:113], v[148:151], v[190:193], v[110:113]
	v_mfma_i32_16x16x64_i8 v[94:97], v[148:151], v[198:201], v[94:97]
	v_mfma_i32_16x16x64_i8 v[86:89], v[158:161], v[198:201], v[86:89]
	v_mfma_i32_16x16x64_i8 v[70:73], v[158:161], v[206:209], v[70:73]
	v_mfma_i32_16x16x64_i8 v[78:81], v[148:151], v[206:209], v[78:81]
	v_mfma_i32_16x16x64_i8 v[126:129], v[152:155], v[186:189], v[126:129]
	v_mfma_i32_16x16x64_i8 v[118:121], v[162:165], v[186:189], v[118:121]
	v_mfma_i32_16x16x64_i8 v[102:105], v[162:165], v[194:197], v[102:105]
	v_mfma_i32_16x16x64_i8 v[110:113], v[152:155], v[194:197], v[110:113]
	v_mfma_i32_16x16x64_i8 v[94:97], v[152:155], v[202:205], v[94:97]
	v_mfma_i32_16x16x64_i8 v[86:89], v[162:165], v[202:205], v[86:89]
	v_mfma_i32_16x16x64_i8 v[70:73], v[162:165], v[210:213], v[70:73]
	v_mfma_i32_16x16x64_i8 v[78:81], v[152:155], v[210:213], v[78:81]
	s_setprio 0
	s_setprio 3
	v_mfma_i32_16x16x64_i8 v[122:125], v[166:169], v[182:185], v[122:125]
	v_mfma_i32_16x16x64_i8 v[114:117], v[174:177], v[182:185], v[114:117]
	v_mfma_i32_16x16x64_i8 v[98:101], v[174:177], v[190:193], v[98:101]
	v_mfma_i32_16x16x64_i8 v[106:109], v[166:169], v[190:193], v[106:109]
	v_mfma_i32_16x16x64_i8 v[90:93], v[166:169], v[198:201], v[90:93]
	v_mfma_i32_16x16x64_i8 v[82:85], v[174:177], v[198:201], v[82:85]
	v_mfma_i32_16x16x64_i8 v[66:69], v[174:177], v[206:209], v[66:69]
	v_mfma_i32_16x16x64_i8 v[74:77], v[166:169], v[206:209], v[74:77]
	v_mfma_i32_16x16x64_i8 v[122:125], v[170:173], v[186:189], v[122:125]
	v_mfma_i32_16x16x64_i8 v[114:117], v[178:181], v[186:189], v[114:117]
	v_mfma_i32_16x16x64_i8 v[98:101], v[178:181], v[194:197], v[98:101]
	v_mfma_i32_16x16x64_i8 v[106:109], v[170:173], v[194:197], v[106:109]
	v_mfma_i32_16x16x64_i8 v[90:93], v[170:173], v[202:205], v[90:93]
	v_mfma_i32_16x16x64_i8 v[82:85], v[178:181], v[202:205], v[82:85]
	v_mfma_i32_16x16x64_i8 v[66:69], v[178:181], v[210:213], v[66:69]
	v_mfma_i32_16x16x64_i8 v[74:77], v[170:173], v[210:213], v[74:77]
	s_setprio 0
	s_barrier
	s_add_u32 s54, s52, 0x4000
	s_addc_u32 s55, s53, 0
	s_add_i32 s45, s45, s43
	v_lshl_add_u64 v[218:219], s[54:55], 0, v[130:131]
	s_mov_b32 m0, s45
	ds_read_b128 v[182:185], v157 offset:49152
	ds_read_b128 v[186:189], v157 offset:50176
	ds_read_b128 v[190:193], v157 offset:51200
	ds_read_b128 v[194:197], v157 offset:52224
	ds_read_b128 v[198:201], v157 offset:53248
	ds_read_b128 v[202:205], v157 offset:54272
	ds_read_b128 v[206:209], v157 offset:55296
	ds_read_b128 v[210:213], v157 offset:56320
	global_load_lds_dwordx4 v[218:219], off
	s_add_i32 m0, s45, 0x2000
	s_add_u32 s52, s52, 0x84000
	v_lshl_add_u64 v[218:219], s[54:55], 0, v[132:133]
	s_addc_u32 s53, s53, 0
	s_add_i32 s45, s47, s43
	global_load_lds_dwordx4 v[218:219], off
	v_lshl_add_u64 v[218:219], s[52:53], 0, v[130:131]
	s_mov_b32 m0, s45
	v_lshl_add_u64 v[214:215], v[214:215], 0, s[38:39]
	global_load_lds_dwordx4 v[218:219], off
	v_lshl_add_u64 v[218:219], s[52:53], 0, v[132:133]
	s_add_i32 m0, s45, 0x2000
	s_nop 0
	global_load_lds_dwordx4 v[218:219], off
	s_mov_b32 m0, s64
	s_nop 0
	global_load_lds_dwordx4 v[214:215], off
	v_lshl_add_u64 v[214:215], v[216:217], 0, s[38:39]
	s_mov_b32 m0, s65
	s_nop 0
	global_load_lds_dwordx4 v[214:215], off
	s_waitcnt vmcnt(8)
	s_waitcnt lgkmcnt(0)
	s_barrier
	s_setprio 3
	s_waitcnt lgkmcnt(0)
	v_mfma_i32_16x16x64_i8 v[62:65], v[148:151], v[182:185], v[62:65]
	v_mfma_i32_16x16x64_i8 v[54:57], v[158:161], v[182:185], v[54:57]
	v_mfma_i32_16x16x64_i8 v[38:41], v[158:161], v[190:193], v[38:41]
	v_mfma_i32_16x16x64_i8 v[46:49], v[148:151], v[190:193], v[46:49]
	v_mfma_i32_16x16x64_i8 v[30:33], v[148:151], v[198:201], v[30:33]
	v_mfma_i32_16x16x64_i8 v[22:25], v[158:161], v[198:201], v[22:25]
	v_mfma_i32_16x16x64_i8 v[6:9], v[158:161], v[206:209], v[6:9]
	v_mfma_i32_16x16x64_i8 v[14:17], v[148:151], v[206:209], v[14:17]
	v_mfma_i32_16x16x64_i8 v[62:65], v[152:155], v[186:189], v[62:65]
	v_mfma_i32_16x16x64_i8 v[54:57], v[162:165], v[186:189], v[54:57]
	v_mfma_i32_16x16x64_i8 v[38:41], v[162:165], v[194:197], v[38:41]
	v_mfma_i32_16x16x64_i8 v[46:49], v[152:155], v[194:197], v[46:49]
	v_mfma_i32_16x16x64_i8 v[30:33], v[152:155], v[202:205], v[30:33]
	v_mfma_i32_16x16x64_i8 v[22:25], v[162:165], v[202:205], v[22:25]
	v_mfma_i32_16x16x64_i8 v[6:9], v[162:165], v[210:213], v[6:9]
	v_mfma_i32_16x16x64_i8 v[14:17], v[152:155], v[210:213], v[14:17]
	s_setprio 0
	s_setprio 3
	v_mfma_i32_16x16x64_i8 v[58:61], v[166:169], v[182:185], v[58:61]
	v_mfma_i32_16x16x64_i8 v[50:53], v[174:177], v[182:185], v[50:53]
	v_mfma_i32_16x16x64_i8 v[34:37], v[174:177], v[190:193], v[34:37]
	v_mfma_i32_16x16x64_i8 v[42:45], v[166:169], v[190:193], v[42:45]
	v_mfma_i32_16x16x64_i8 v[26:29], v[166:169], v[198:201], v[26:29]
	v_mfma_i32_16x16x64_i8 v[18:21], v[174:177], v[198:201], v[18:21]
	v_mfma_i32_16x16x64_i8 v[2:5], v[174:177], v[206:209], v[2:5]
	v_mfma_i32_16x16x64_i8 v[10:13], v[166:169], v[206:209], v[10:13]
	v_mfma_i32_16x16x64_i8 v[58:61], v[170:173], v[186:189], v[58:61]
	v_mfma_i32_16x16x64_i8 v[50:53], v[178:181], v[186:189], v[50:53]
	v_mfma_i32_16x16x64_i8 v[34:37], v[178:181], v[194:197], v[34:37]
	v_mfma_i32_16x16x64_i8 v[42:45], v[170:173], v[194:197], v[42:45]
	v_mfma_i32_16x16x64_i8 v[26:29], v[170:173], v[202:205], v[26:29]
	v_mfma_i32_16x16x64_i8 v[18:21], v[178:181], v[202:205], v[18:21]
	v_mfma_i32_16x16x64_i8 v[2:5], v[178:181], v[210:213], v[2:5]
	v_mfma_i32_16x16x64_i8 v[10:13], v[170:173], v[210:213], v[10:13]
	s_setprio 0
	s_barrier
	s_add_i32 s75, s75, 2
	s_add_u32 s73, s73, 0x8000
	s_addc_u32 s74, s74, 0
	s_add_u32 s50, s50, 0x100
	s_addc_u32 s51, s51, 0
	s_cmp_gt_u32 s75, 29
	s_cbranch_scc1 .LBB0_209

.Lzf_0_0:
	s_barrier
	s_setprio 3
	s_waitcnt lgkmcnt(0)
	v_mfma_i32_16x16x64_i8 v[126:129], v[148:151], v[182:185], 0
	v_mfma_i32_16x16x64_i8 v[118:121], v[158:161], v[182:185], 0
	v_mfma_i32_16x16x64_i8 v[102:105], v[158:161], v[190:193], 0
	v_mfma_i32_16x16x64_i8 v[110:113], v[148:151], v[190:193], 0
	v_mfma_i32_16x16x64_i8 v[94:97], v[148:151], v[198:201], 0
	v_mfma_i32_16x16x64_i8 v[86:89], v[158:161], v[198:201], 0
	v_mfma_i32_16x16x64_i8 v[70:73], v[158:161], v[206:209], 0
	v_mfma_i32_16x16x64_i8 v[78:81], v[148:151], v[206:209], 0
	v_mfma_i32_16x16x64_i8 v[126:129], v[152:155], v[186:189], v[126:129]
	v_mfma_i32_16x16x64_i8 v[118:121], v[162:165], v[186:189], v[118:121]
	v_mfma_i32_16x16x64_i8 v[102:105], v[162:165], v[194:197], v[102:105]
	v_mfma_i32_16x16x64_i8 v[110:113], v[152:155], v[194:197], v[110:113]
	v_mfma_i32_16x16x64_i8 v[94:97], v[152:155], v[202:205], v[94:97]
	v_mfma_i32_16x16x64_i8 v[86:89], v[162:165], v[202:205], v[86:89]
	v_mfma_i32_16x16x64_i8 v[70:73], v[162:165], v[210:213], v[70:73]
	v_mfma_i32_16x16x64_i8 v[78:81], v[152:155], v[210:213], v[78:81]
	s_setprio 0
	s_setprio 3
	v_mfma_i32_16x16x64_i8 v[122:125], v[166:169], v[182:185], 0
	v_mfma_i32_16x16x64_i8 v[114:117], v[174:177], v[182:185], 0
	v_mfma_i32_16x16x64_i8 v[98:101], v[174:177], v[190:193], 0
	v_mfma_i32_16x16x64_i8 v[106:109], v[166:169], v[190:193], 0
	v_mfma_i32_16x16x64_i8 v[90:93], v[166:169], v[198:201], 0
	v_mfma_i32_16x16x64_i8 v[82:85], v[174:177], v[198:201], 0
	v_mfma_i32_16x16x64_i8 v[66:69], v[174:177], v[206:209], 0
	v_mfma_i32_16x16x64_i8 v[74:77], v[166:169], v[206:209], 0
	v_mfma_i32_16x16x64_i8 v[122:125], v[170:173], v[186:189], v[122:125]
	v_mfma_i32_16x16x64_i8 v[114:117], v[178:181], v[186:189], v[114:117]
	v_mfma_i32_16x16x64_i8 v[98:101], v[178:181], v[194:197], v[98:101]
	v_mfma_i32_16x16x64_i8 v[106:109], v[170:173], v[194:197], v[106:109]
	v_mfma_i32_16x16x64_i8 v[90:93], v[170:173], v[202:205], v[90:93]
	v_mfma_i32_16x16x64_i8 v[82:85], v[178:181], v[202:205], v[82:85]
	v_mfma_i32_16x16x64_i8 v[66:69], v[178:181], v[210:213], v[66:69]
	v_mfma_i32_16x16x64_i8 v[74:77], v[170:173], v[210:213], v[74:77]
	s_setprio 0
	s_branch .Lzb_0_0
.Lzf_0_1:
	s_barrier
	s_setprio 3
	s_waitcnt lgkmcnt(0)
	v_mfma_i32_16x16x64_i8 v[62:65], v[148:151], v[182:185], 0
	v_mfma_i32_16x16x64_i8 v[54:57], v[158:161], v[182:185], 0
	v_mfma_i32_16x16x64_i8 v[38:41], v[158:161], v[190:193], 0
	v_mfma_i32_16x16x64_i8 v[46:49], v[148:151], v[190:193], 0
	v_mfma_i32_16x16x64_i8 v[30:33], v[148:151], v[198:201], 0
	v_mfma_i32_16x16x64_i8 v[22:25], v[158:161], v[198:201], 0
	v_mfma_i32_16x16x64_i8 v[6:9], v[158:161], v[206:209], 0
	v_mfma_i32_16x16x64_i8 v[14:17], v[148:151], v[206:209], 0
	v_mfma_i32_16x16x64_i8 v[62:65], v[152:155], v[186:189], v[62:65]
	v_mfma_i32_16x16x64_i8 v[54:57], v[162:165], v[186:189], v[54:57]
	v_mfma_i32_16x16x64_i8 v[38:41], v[162:165], v[194:197], v[38:41]
	v_mfma_i32_16x16x64_i8 v[46:49], v[152:155], v[194:197], v[46:49]
	v_mfma_i32_16x16x64_i8 v[30:33], v[152:155], v[202:205], v[30:33]
	v_mfma_i32_16x16x64_i8 v[22:25], v[162:165], v[202:205], v[22:25]
	v_mfma_i32_16x16x64_i8 v[6:9], v[162:165], v[210:213], v[6:9]
	v_mfma_i32_16x16x64_i8 v[14:17], v[152:155], v[210:213], v[14:17]
	s_setprio 0
	s_setprio 3
	v_mfma_i32_16x16x64_i8 v[58:61], v[166:169], v[182:185], 0
	v_mfma_i32_16x16x64_i8 v[50:53], v[174:177], v[182:185], 0
	v_mfma_i32_16x16x64_i8 v[34:37], v[174:177], v[190:193], 0
	v_mfma_i32_16x16x64_i8 v[42:45], v[166:169], v[190:193], 0
	v_mfma_i32_16x16x64_i8 v[26:29], v[166:169], v[198:201], 0
	v_mfma_i32_16x16x64_i8 v[18:21], v[174:177], v[198:201], 0
	v_mfma_i32_16x16x64_i8 v[2:5], v[174:177], v[206:209], 0
	v_mfma_i32_16x16x64_i8 v[10:13], v[166:169], v[206:209], 0
	v_mfma_i32_16x16x64_i8 v[58:61], v[170:173], v[186:189], v[58:61]
	v_mfma_i32_16x16x64_i8 v[50:53], v[178:181], v[186:189], v[50:53]
	v_mfma_i32_16x16x64_i8 v[34:37], v[178:181], v[194:197], v[34:37]
	v_mfma_i32_16x16x64_i8 v[42:45], v[170:173], v[194:197], v[42:45]
	v_mfma_i32_16x16x64_i8 v[26:29], v[170:173], v[202:205], v[26:29]
	v_mfma_i32_16x16x64_i8 v[18:21], v[178:181], v[202:205], v[18:21]
	v_mfma_i32_16x16x64_i8 v[2:5], v[178:181], v[210:213], v[2:5]
	v_mfma_i32_16x16x64_i8 v[10:13], v[170:173], v[210:213], v[10:13]
	s_setprio 0
	s_branch .Lzb_0_1

.LBB0_408:
	s_add_u32 s75, s48, 0x8000
	s_addc_u32 s76, s49, 0
	s_mov_b32 s77, -2
.LBB0_409:
	ds_read_b128 v[148:151], v157
	ds_read_b128 v[152:155], v157 offset:1024
	ds_read_b128 v[160:163], v157 offset:2048
	ds_read_b128 v[164:167], v157 offset:3072
	ds_read_b128 v[168:171], v158
	ds_read_b128 v[172:175], v158 offset:1024
	ds_read_b128 v[176:179], v158 offset:2048
	ds_read_b128 v[180:183], v158 offset:3072
	s_add_u32 s48, s0, 0x100
	s_addc_u32 s49, s1, 0
	s_cmpk_eq_i32 s77, 0x52
	s_cselect_b32 s53, s7, s49
	s_cselect_b32 s52, s6, s48
	s_cselect_b32 s51, s47, s76
	s_cselect_b32 s50, s46, s75
	v_lshl_add_u64 v[216:217], s[0:1], 0, v[138:139]
	s_add_i32 m0, s55, 0xc000
	ds_read_b128 v[184:187], v159
	ds_read_b128 v[188:191], v159 offset:1024
	ds_read_b128 v[192:195], v159 offset:2048
	ds_read_b128 v[196:199], v159 offset:3072
	ds_read_b128 v[200:203], v159 offset:4096
	ds_read_b128 v[204:207], v159 offset:5120
	ds_read_b128 v[208:211], v159 offset:6144
	ds_read_b128 v[212:215], v159 offset:7168
	global_load_lds_dwordx4 v[216:217], off
	v_lshl_add_u64 v[216:217], s[0:1], 0, v[140:141]
	s_add_i32 m0, s55, 0xe000
	s_nop 0
	global_load_lds_dwordx4 v[216:217], off
	s_waitcnt vmcnt(8)
	s_waitcnt lgkmcnt(0)
	s_cmp_eq_i32 s77, -2
	s_cbranch_scc1 .Lzf_1_0
	s_barrier
	s_setprio 3
	s_waitcnt lgkmcnt(0)
	v_mfma_i32_16x16x64_i8 v[126:129], v[148:151], v[184:187], v[126:129]
	v_mfma_i32_16x16x64_i8 v[122:125], v[160:163], v[184:187], v[122:125]
	v_mfma_i32_16x16x64_i8 v[114:117], v[160:163], v[192:195], v[114:117]
	v_mfma_i32_16x16x64_i8 v[118:121], v[148:151], v[192:195], v[118:121]
	v_mfma_i32_16x16x64_i8 v[110:113], v[148:151], v[200:203], v[110:113]
	v_mfma_i32_16x16x64_i8 v[106:109], v[160:163], v[200:203], v[106:109]
	v_mfma_i32_16x16x64_i8 v[98:101], v[160:163], v[208:211], v[98:101]
	v_mfma_i32_16x16x64_i8 v[102:105], v[148:151], v[208:211], v[102:105]
	v_mfma_i32_16x16x64_i8 v[126:129], v[152:155], v[188:191], v[126:129]
	v_mfma_i32_16x16x64_i8 v[122:125], v[164:167], v[188:191], v[122:125]
	v_mfma_i32_16x16x64_i8 v[114:117], v[164:167], v[196:199], v[114:117]
	v_mfma_i32_16x16x64_i8 v[118:121], v[152:155], v[196:199], v[118:121]
	v_mfma_i32_16x16x64_i8 v[110:113], v[152:155], v[204:207], v[110:113]
	v_mfma_i32_16x16x64_i8 v[106:109], v[164:167], v[204:207], v[106:109]
	v_mfma_i32_16x16x64_i8 v[98:101], v[164:167], v[212:215], v[98:101]
	v_mfma_i32_16x16x64_i8 v[102:105], v[152:155], v[212:215], v[102:105]
	s_setprio 0
	s_setprio 3
	v_mfma_i32_16x16x64_i8 v[62:65], v[168:171], v[184:187], v[62:65]
	v_mfma_i32_16x16x64_i8 v[58:61], v[176:179], v[184:187], v[58:61]
	v_mfma_i32_16x16x64_i8 v[50:53], v[176:179], v[192:195], v[50:53]
	v_mfma_i32_16x16x64_i8 v[54:57], v[168:171], v[192:195], v[54:57]
	v_mfma_i32_16x16x64_i8 v[46:49], v[168:171], v[200:203], v[46:49]
	v_mfma_i32_16x16x64_i8 v[42:45], v[176:179], v[200:203], v[42:45]
	v_mfma_i32_16x16x64_i8 v[34:37], v[176:179], v[208:211], v[34:37]
	v_mfma_i32_16x16x64_i8 v[38:41], v[168:171], v[208:211], v[38:41]
	v_mfma_i32_16x16x64_i8 v[62:65], v[172:175], v[188:191], v[62:65]
	v_mfma_i32_16x16x64_i8 v[58:61], v[180:183], v[188:191], v[58:61]
	v_mfma_i32_16x16x64_i8 v[50:53], v[180:183], v[196:199], v[50:53]
	v_mfma_i32_16x16x64_i8 v[54:57], v[172:175], v[196:199], v[54:57]
	v_mfma_i32_16x16x64_i8 v[46:49], v[172:175], v[204:207], v[46:49]
	v_mfma_i32_16x16x64_i8 v[42:45], v[180:183], v[204:207], v[42:45]
	v_mfma_i32_16x16x64_i8 v[34:37], v[180:183], v[212:215], v[34:37]
	v_mfma_i32_16x16x64_i8 v[38:41], v[172:175], v[212:215], v[38:41]
	s_setprio 0
.Lzb_1_0:
	s_barrier
	s_add_i32 s0, s63, s54
	v_lshl_add_u64 v[216:217], s[50:51], 0, v[130:131]
	s_mov_b32 m0, s0
	ds_read_b128 v[184:187], v159 offset:16384
	ds_read_b128 v[188:191], v159 offset:17408
	ds_read_b128 v[192:195], v159 offset:18432
	ds_read_b128 v[196:199], v159 offset:19456
	ds_read_b128 v[200:203], v159 offset:20480
	ds_read_b128 v[204:207], v159 offset:21504
	ds_read_b128 v[208:211], v159 offset:22528
	ds_read_b128 v[212:215], v159 offset:23552
	global_load_lds_dwordx4 v[216:217], off
	s_add_i32 m0, s0, 0x2000
	s_add_u32 s0, s50, 0x158000
	v_lshl_add_u64 v[216:217], s[50:51], 0, v[134:135]
	s_addc_u32 s1, s51, 0
	s_add_i32 s78, s64, s54
	global_load_lds_dwordx4 v[216:217], off
	v_lshl_add_u64 v[216:217], s[0:1], 0, v[130:131]
	s_mov_b32 m0, s78
	v_lshl_add_u64 v[218:219], s[52:53], 0, v[136:137]
	global_load_lds_dwordx4 v[216:217], off
	v_lshl_add_u64 v[216:217], s[0:1], 0, v[134:135]
	s_add_i32 m0, s78, 0x2000
	s_nop 0
	global_load_lds_dwordx4 v[216:217], off
	v_lshl_add_u64 v[216:217], s[52:53], 0, v[132:133]
	s_mov_b32 m0, s55
	s_nop 0
	global_load_lds_dwordx4 v[216:217], off
	s_mov_b32 m0, s56
	s_nop 0
	global_load_lds_dwordx4 v[218:219], off
	s_waitcnt vmcnt(8)
	s_waitcnt lgkmcnt(0)
	s_cmp_eq_i32 s77, -2
	s_cbranch_scc1 .Lzf_1_1
	s_barrier
	s_setprio 3
	s_waitcnt lgkmcnt(0)
	v_mfma_i32_16x16x64_i8 v[94:97], v[148:151], v[184:187], v[94:97]
	v_mfma_i32_16x16x64_i8 v[90:93], v[160:163], v[184:187], v[90:93]
	v_mfma_i32_16x16x64_i8 v[82:85], v[160:163], v[192:195], v[82:85]
	v_mfma_i32_16x16x64_i8 v[86:89], v[148:151], v[192:195], v[86:89]
	v_mfma_i32_16x16x64_i8 v[78:81], v[148:151], v[200:203], v[78:81]
	v_mfma_i32_16x16x64_i8 v[74:77], v[160:163], v[200:203], v[74:77]
	v_mfma_i32_16x16x64_i8 v[66:69], v[160:163], v[208:211], v[66:69]
	v_mfma_i32_16x16x64_i8 v[70:73], v[148:151], v[208:211], v[70:73]
	v_mfma_i32_16x16x64_i8 v[94:97], v[152:155], v[188:191], v[94:97]
	v_mfma_i32_16x16x64_i8 v[90:93], v[164:167], v[188:191], v[90:93]
	v_mfma_i32_16x16x64_i8 v[82:85], v[164:167], v[196:199], v[82:85]
	v_mfma_i32_16x16x64_i8 v[86:89], v[152:155], v[196:199], v[86:89]
	v_mfma_i32_16x16x64_i8 v[78:81], v[152:155], v[204:207], v[78:81]
	v_mfma_i32_16x16x64_i8 v[74:77], v[164:167], v[204:207], v[74:77]
	v_mfma_i32_16x16x64_i8 v[66:69], v[164:167], v[212:215], v[66:69]
	v_mfma_i32_16x16x64_i8 v[70:73], v[152:155], v[212:215], v[70:73]
	s_setprio 0
	s_setprio 3
	v_mfma_i32_16x16x64_i8 v[30:33], v[168:171], v[184:187], v[30:33]
	v_mfma_i32_16x16x64_i8 v[26:29], v[176:179], v[184:187], v[26:29]
	v_mfma_i32_16x16x64_i8 v[18:21], v[176:179], v[192:195], v[18:21]
	v_mfma_i32_16x16x64_i8 v[22:25], v[168:171], v[192:195], v[22:25]
	v_mfma_i32_16x16x64_i8 v[14:17], v[168:171], v[200:203], v[14:17]
	v_mfma_i32_16x16x64_i8 v[10:13], v[176:179], v[200:203], v[10:13]
	v_mfma_i32_16x16x64_i8 v[2:5], v[176:179], v[208:211], v[2:5]
	v_mfma_i32_16x16x64_i8 v[6:9], v[168:171], v[208:211], v[6:9]
	v_mfma_i32_16x16x64_i8 v[30:33], v[172:175], v[188:191], v[30:33]
	v_mfma_i32_16x16x64_i8 v[26:29], v[180:183], v[188:191], v[26:29]
	v_mfma_i32_16x16x64_i8 v[18:21], v[180:183], v[196:199], v[18:21]
	v_mfma_i32_16x16x64_i8 v[22:25], v[172:175], v[196:199], v[22:25]
	v_mfma_i32_16x16x64_i8 v[14:17], v[172:175], v[204:207], v[14:17]
	v_mfma_i32_16x16x64_i8 v[10:13], v[180:183], v[204:207], v[10:13]
	v_mfma_i32_16x16x64_i8 v[2:5], v[180:183], v[212:215], v[2:5]
	v_mfma_i32_16x16x64_i8 v[6:9], v[172:175], v[212:215], v[6:9]
	s_setprio 0
.Lzb_1_1:
	s_barrier
	s_add_i32 s78, 0, 0x18000
	s_add_i32 s79, 0, 0x1c000
	v_add_u32_e32 v164, s78, v147
	v_add_u32_e32 v180, s79, v147
	ds_read_b128 v[148:151], v164
	ds_read_b128 v[152:155], v164 offset:1024
	ds_read_b128 v[160:163], v164 offset:2048
	ds_read_b128 v[164:167], v164 offset:3072
	ds_read_b128 v[168:171], v180
	ds_read_b128 v[172:175], v180 offset:1024
	ds_read_b128 v[176:179], v180 offset:2048
	ds_read_b128 v[180:183], v180 offset:3072
	s_add_u32 s0, s52, 0x158000
	s_addc_u32 s1, s53, 0
	s_mov_b32 m0, s57
	v_lshl_add_u64 v[220:221], s[0:1], 0, v[132:133]
	ds_read_b128 v[184:187], v159 offset:32768
	ds_read_b128 v[188:191], v159 offset:33792
	ds_read_b128 v[192:195], v159 offset:34816
	ds_read_b128 v[196:199], v159 offset:35840
	ds_read_b128 v[200:203], v159 offset:36864
	ds_read_b128 v[204:207], v159 offset:37888
	ds_read_b128 v[208:211], v159 offset:38912
	ds_read_b128 v[212:215], v159 offset:39936
	global_load_lds_dwordx4 v[220:221], off
	v_lshl_add_u64 v[220:221], s[0:1], 0, v[136:137]
	s_mov_b32 m0, s58
	s_nop 0
	global_load_lds_dwordx4 v[220:221], off
	s_waitcnt vmcnt(8)
	s_waitcnt lgkmcnt(0)
	s_barrier
	s_setprio 3
	s_waitcnt lgkmcnt(0)
	v_mfma_i32_16x16x64_i8 v[126:129], v[148:151], v[184:187], v[126:129]
	v_mfma_i32_16x16x64_i8 v[122:125], v[160:163], v[184:187], v[122:125]
	v_mfma_i32_16x16x64_i8 v[114:117], v[160:163], v[192:195], v[114:117]
	v_mfma_i32_16x16x64_i8 v[118:121], v[148:151], v[192:195], v[118:121]
	v_mfma_i32_16x16x64_i8 v[110:113], v[148:151], v[200:203], v[110:113]
	v_mfma_i32_16x16x64_i8 v[106:109], v[160:163], v[200:203], v[106:109]
	v_mfma_i32_16x16x64_i8 v[98:101], v[160:163], v[208:211], v[98:101]
	v_mfma_i32_16x16x64_i8 v[102:105], v[148:151], v[208:211], v[102:105]
	v_mfma_i32_16x16x64_i8 v[126:129], v[152:155], v[188:191], v[126:129]
	v_mfma_i32_16x16x64_i8 v[122:125], v[164:167], v[188:191], v[122:125]
	v_mfma_i32_16x16x64_i8 v[114:117], v[164:167], v[196:199], v[114:117]
	v_mfma_i32_16x16x64_i8 v[118:121], v[152:155], v[196:199], v[118:121]
	v_mfma_i32_16x16x64_i8 v[110:113], v[152:155], v[204:207], v[110:113]
	v_mfma_i32_16x16x64_i8 v[106:109], v[164:167], v[204:207], v[106:109]
	v_mfma_i32_16x16x64_i8 v[98:101], v[164:167], v[212:215], v[98:101]
	v_mfma_i32_16x16x64_i8 v[102:105], v[152:155], v[212:215], v[102:105]
	s_setprio 0
	s_setprio 3
	v_mfma_i32_16x16x64_i8 v[62:65], v[168:171], v[184:187], v[62:65]
	v_mfma_i32_16x16x64_i8 v[58:61], v[176:179], v[184:187], v[58:61]
	v_mfma_i32_16x16x64_i8 v[50:53], v[176:179], v[192:195], v[50:53]
	v_mfma_i32_16x16x64_i8 v[54:57], v[168:171], v[192:195], v[54:57]
	v_mfma_i32_16x16x64_i8 v[46:49], v[168:171], v[200:203], v[46:49]
	v_mfma_i32_16x16x64_i8 v[42:45], v[176:179], v[200:203], v[42:45]
	v_mfma_i32_16x16x64_i8 v[34:37], v[176:179], v[208:211], v[34:37]
	v_mfma_i32_16x16x64_i8 v[38:41], v[168:171], v[208:211], v[38:41]
	v_mfma_i32_16x16x64_i8 v[62:65], v[172:175], v[188:191], v[62:65]
	v_mfma_i32_16x16x64_i8 v[58:61], v[180:183], v[188:191], v[58:61]
	v_mfma_i32_16x16x64_i8 v[50:53], v[180:183], v[196:199], v[50:53]
	v_mfma_i32_16x16x64_i8 v[54:57], v[172:175], v[196:199], v[54:57]
	v_mfma_i32_16x16x64_i8 v[46:49], v[172:175], v[204:207], v[46:49]
	v_mfma_i32_16x16x64_i8 v[42:45], v[180:183], v[204:207], v[42:45]
	v_mfma_i32_16x16x64_i8 v[34:37], v[180:183], v[212:215], v[34:37]
	v_mfma_i32_16x16x64_i8 v[38:41], v[172:175], v[212:215], v[38:41]
	s_setprio 0
	s_barrier
	s_add_u32 s0, s50, 0x4000
	s_addc_u32 s1, s51, 0
	s_add_i32 s52, s78, s54
	v_lshl_add_u64 v[220:221], s[0:1], 0, v[130:131]
	s_mov_b32 m0, s52
	ds_read_b128 v[184:187], v159 offset:49152
	ds_read_b128 v[188:191], v159 offset:50176
	ds_read_b128 v[192:195], v159 offset:51200
	ds_read_b128 v[196:199], v159 offset:52224
	ds_read_b128 v[200:203], v159 offset:53248
	ds_read_b128 v[204:207], v159 offset:54272
	ds_read_b128 v[208:211], v159 offset:55296
	ds_read_b128 v[212:215], v159 offset:56320
	global_load_lds_dwordx4 v[220:221], off
	s_add_i32 m0, s52, 0x2000
	v_lshl_add_u64 v[220:221], s[0:1], 0, v[134:135]
	s_add_u32 s0, s50, 0x15c000
	s_addc_u32 s1, s51, 0
	s_add_i32 s50, s79, s54
	global_load_lds_dwordx4 v[220:221], off
	v_lshl_add_u64 v[220:221], s[0:1], 0, v[130:131]
	s_mov_b32 m0, s50
	v_lshl_add_u64 v[216:217], v[216:217], 0, s[18:19]
	global_load_lds_dwordx4 v[220:221], off
	v_lshl_add_u64 v[220:221], s[0:1], 0, v[134:135]
	s_add_i32 m0, s50, 0x2000
	s_nop 0
	global_load_lds_dwordx4 v[220:221], off
	s_mov_b32 m0, s60
	s_nop 0
	global_load_lds_dwordx4 v[216:217], off
	v_lshl_add_u64 v[216:217], v[218:219], 0, s[18:19]
	s_mov_b32 m0, s61
	s_nop 0
	global_load_lds_dwordx4 v[216:217], off
	s_waitcnt vmcnt(8)
	s_waitcnt lgkmcnt(0)
	s_barrier
	s_setprio 3
	s_waitcnt lgkmcnt(0)
	v_mfma_i32_16x16x64_i8 v[94:97], v[148:151], v[184:187], v[94:97]
	v_mfma_i32_16x16x64_i8 v[90:93], v[160:163], v[184:187], v[90:93]
	v_mfma_i32_16x16x64_i8 v[82:85], v[160:163], v[192:195], v[82:85]
	v_mfma_i32_16x16x64_i8 v[86:89], v[148:151], v[192:195], v[86:89]
	v_mfma_i32_16x16x64_i8 v[78:81], v[148:151], v[200:203], v[78:81]
	v_mfma_i32_16x16x64_i8 v[74:77], v[160:163], v[200:203], v[74:77]
	v_mfma_i32_16x16x64_i8 v[66:69], v[160:163], v[208:211], v[66:69]
	v_mfma_i32_16x16x64_i8 v[70:73], v[148:151], v[208:211], v[70:73]
	v_mfma_i32_16x16x64_i8 v[94:97], v[152:155], v[188:191], v[94:97]
	v_mfma_i32_16x16x64_i8 v[90:93], v[164:167], v[188:191], v[90:93]
	v_mfma_i32_16x16x64_i8 v[82:85], v[164:167], v[196:199], v[82:85]
	v_mfma_i32_16x16x64_i8 v[86:89], v[152:155], v[196:199], v[86:89]
	v_mfma_i32_16x16x64_i8 v[78:81], v[152:155], v[204:207], v[78:81]
	v_mfma_i32_16x16x64_i8 v[74:77], v[164:167], v[204:207], v[74:77]
	v_mfma_i32_16x16x64_i8 v[66:69], v[164:167], v[212:215], v[66:69]
	v_mfma_i32_16x16x64_i8 v[70:73], v[152:155], v[212:215], v[70:73]
	s_setprio 0
	s_setprio 3
	v_mfma_i32_16x16x64_i8 v[30:33], v[168:171], v[184:187], v[30:33]
	v_mfma_i32_16x16x64_i8 v[26:29], v[176:179], v[184:187], v[26:29]
	v_mfma_i32_16x16x64_i8 v[18:21], v[176:179], v[192:195], v[18:21]
	v_mfma_i32_16x16x64_i8 v[22:25], v[168:171], v[192:195], v[22:25]
	v_mfma_i32_16x16x64_i8 v[14:17], v[168:171], v[200:203], v[14:17]
	v_mfma_i32_16x16x64_i8 v[10:13], v[176:179], v[200:203], v[10:13]
	v_mfma_i32_16x16x64_i8 v[2:5], v[176:179], v[208:211], v[2:5]
	v_mfma_i32_16x16x64_i8 v[6:9], v[168:171], v[208:211], v[6:9]
	v_mfma_i32_16x16x64_i8 v[30:33], v[172:175], v[188:191], v[30:33]
	v_mfma_i32_16x16x64_i8 v[26:29], v[180:183], v[188:191], v[26:29]
	v_mfma_i32_16x16x64_i8 v[18:21], v[180:183], v[196:199], v[18:21]
	v_mfma_i32_16x16x64_i8 v[22:25], v[172:175], v[196:199], v[22:25]
	v_mfma_i32_16x16x64_i8 v[14:17], v[172:175], v[204:207], v[14:17]
	v_mfma_i32_16x16x64_i8 v[10:13], v[180:183], v[204:207], v[10:13]
	v_mfma_i32_16x16x64_i8 v[2:5], v[180:183], v[212:215], v[2:5]
	v_mfma_i32_16x16x64_i8 v[6:9], v[172:175], v[212:215], v[6:9]
	s_setprio 0
	s_barrier
	s_add_i32 s77, s77, 2
	s_add_u32 s75, s75, 0x8000
	s_addc_u32 s76, s76, 0
	s_cmpk_gt_u32 s77, 0x53
	s_mov_b64 s[0:1], s[48:49]
	s_cbranch_scc0 .LBB0_409
	s_and_b64 vcc, exec, s[20:21]
	s_cbranch_vccz .LBB0_412
	s_barrier

.Lzf_1_0:
	s_barrier
	s_setprio 3
	s_waitcnt lgkmcnt(0)
	v_mfma_i32_16x16x64_i8 v[126:129], v[148:151], v[184:187], 0
	v_mfma_i32_16x16x64_i8 v[122:125], v[160:163], v[184:187], 0
	v_mfma_i32_16x16x64_i8 v[114:117], v[160:163], v[192:195], 0
	v_mfma_i32_16x16x64_i8 v[118:121], v[148:151], v[192:195], 0
	v_mfma_i32_16x16x64_i8 v[110:113], v[148:151], v[200:203], 0
	v_mfma_i32_16x16x64_i8 v[106:109], v[160:163], v[200:203], 0
	v_mfma_i32_16x16x64_i8 v[98:101], v[160:163], v[208:211], 0
	v_mfma_i32_16x16x64_i8 v[102:105], v[148:151], v[208:211], 0
	v_mfma_i32_16x16x64_i8 v[126:129], v[152:155], v[188:191], v[126:129]
	v_mfma_i32_16x16x64_i8 v[122:125], v[164:167], v[188:191], v[122:125]
	v_mfma_i32_16x16x64_i8 v[114:117], v[164:167], v[196:199], v[114:117]
	v_mfma_i32_16x16x64_i8 v[118:121], v[152:155], v[196:199], v[118:121]
	v_mfma_i32_16x16x64_i8 v[110:113], v[152:155], v[204:207], v[110:113]
	v_mfma_i32_16x16x64_i8 v[106:109], v[164:167], v[204:207], v[106:109]
	v_mfma_i32_16x16x64_i8 v[98:101], v[164:167], v[212:215], v[98:101]
	v_mfma_i32_16x16x64_i8 v[102:105], v[152:155], v[212:215], v[102:105]
	s_setprio 0
	s_setprio 3
	v_mfma_i32_16x16x64_i8 v[62:65], v[168:171], v[184:187], 0
	v_mfma_i32_16x16x64_i8 v[58:61], v[176:179], v[184:187], 0
	v_mfma_i32_16x16x64_i8 v[50:53], v[176:179], v[192:195], 0
	v_mfma_i32_16x16x64_i8 v[54:57], v[168:171], v[192:195], 0
	v_mfma_i32_16x16x64_i8 v[46:49], v[168:171], v[200:203], 0
	v_mfma_i32_16x16x64_i8 v[42:45], v[176:179], v[200:203], 0
	v_mfma_i32_16x16x64_i8 v[34:37], v[176:179], v[208:211], 0
	v_mfma_i32_16x16x64_i8 v[38:41], v[168:171], v[208:211], 0
	v_mfma_i32_16x16x64_i8 v[62:65], v[172:175], v[188:191], v[62:65]
	v_mfma_i32_16x16x64_i8 v[58:61], v[180:183], v[188:191], v[58:61]
	v_mfma_i32_16x16x64_i8 v[50:53], v[180:183], v[196:199], v[50:53]
	v_mfma_i32_16x16x64_i8 v[54:57], v[172:175], v[196:199], v[54:57]
	v_mfma_i32_16x16x64_i8 v[46:49], v[172:175], v[204:207], v[46:49]
	v_mfma_i32_16x16x64_i8 v[42:45], v[180:183], v[204:207], v[42:45]
	v_mfma_i32_16x16x64_i8 v[34:37], v[180:183], v[212:215], v[34:37]
	v_mfma_i32_16x16x64_i8 v[38:41], v[172:175], v[212:215], v[38:41]
	s_setprio 0
	s_branch .Lzb_1_0
.Lzf_1_1:
	s_barrier
	s_setprio 3
	s_waitcnt lgkmcnt(0)
	v_mfma_i32_16x16x64_i8 v[94:97], v[148:151], v[184:187], 0
	v_mfma_i32_16x16x64_i8 v[90:93], v[160:163], v[184:187], 0
	v_mfma_i32_16x16x64_i8 v[82:85], v[160:163], v[192:195], 0
	v_mfma_i32_16x16x64_i8 v[86:89], v[148:151], v[192:195], 0
	v_mfma_i32_16x16x64_i8 v[78:81], v[148:151], v[200:203], 0
	v_mfma_i32_16x16x64_i8 v[74:77], v[160:163], v[200:203], 0
	v_mfma_i32_16x16x64_i8 v[66:69], v[160:163], v[208:211], 0
	v_mfma_i32_16x16x64_i8 v[70:73], v[148:151], v[208:211], 0
	v_mfma_i32_16x16x64_i8 v[94:97], v[152:155], v[188:191], v[94:97]
	v_mfma_i32_16x16x64_i8 v[90:93], v[164:167], v[188:191], v[90:93]
	v_mfma_i32_16x16x64_i8 v[82:85], v[164:167], v[196:199], v[82:85]
	v_mfma_i32_16x16x64_i8 v[86:89], v[152:155], v[196:199], v[86:89]
	v_mfma_i32_16x16x64_i8 v[78:81], v[152:155], v[204:207], v[78:81]
	v_mfma_i32_16x16x64_i8 v[74:77], v[164:167], v[204:207], v[74:77]
	v_mfma_i32_16x16x64_i8 v[66:69], v[164:167], v[212:215], v[66:69]
	v_mfma_i32_16x16x64_i8 v[70:73], v[152:155], v[212:215], v[70:73]
	s_setprio 0
	s_setprio 3
	v_mfma_i32_16x16x64_i8 v[30:33], v[168:171], v[184:187], 0
	v_mfma_i32_16x16x64_i8 v[26:29], v[176:179], v[184:187], 0
	v_mfma_i32_16x16x64_i8 v[18:21], v[176:179], v[192:195], 0
	v_mfma_i32_16x16x64_i8 v[22:25], v[168:171], v[192:195], 0
	v_mfma_i32_16x16x64_i8 v[14:17], v[168:171], v[200:203], 0
	v_mfma_i32_16x16x64_i8 v[10:13], v[176:179], v[200:203], 0
	v_mfma_i32_16x16x64_i8 v[2:5], v[176:179], v[208:211], 0
	v_mfma_i32_16x16x64_i8 v[6:9], v[168:171], v[208:211], 0
	v_mfma_i32_16x16x64_i8 v[30:33], v[172:175], v[188:191], v[30:33]
	v_mfma_i32_16x16x64_i8 v[26:29], v[180:183], v[188:191], v[26:29]
	v_mfma_i32_16x16x64_i8 v[18:21], v[180:183], v[196:199], v[18:21]
	v_mfma_i32_16x16x64_i8 v[22:25], v[172:175], v[196:199], v[22:25]
	v_mfma_i32_16x16x64_i8 v[14:17], v[172:175], v[204:207], v[14:17]
	v_mfma_i32_16x16x64_i8 v[10:13], v[180:183], v[204:207], v[10:13]
	v_mfma_i32_16x16x64_i8 v[2:5], v[180:183], v[212:215], v[2:5]
	v_mfma_i32_16x16x64_i8 v[6:9], v[172:175], v[212:215], v[6:9]
	s_setprio 0
	s_branch .Lzb_1_1

.LBB0_557:
	s_add_u32 s41, s48, 0x8000
	s_addc_u32 s43, s49, 0
	s_mov_b32 s67, -2
.LBB0_558:
	ds_read_b128 v[148:151], v163
	ds_read_b128 v[152:155], v163 offset:1024
	ds_read_b128 v[156:159], v163 offset:2048
	ds_read_b128 v[166:169], v163 offset:3072
	ds_read_b128 v[170:173], v164
	ds_read_b128 v[174:177], v164 offset:1024
	ds_read_b128 v[178:181], v164 offset:2048
	ds_read_b128 v[182:185], v164 offset:3072
	s_add_u32 s48, s0, 0x100
	s_addc_u32 s49, s1, 0
	s_cmp_eq_u32 s67, 28
	s_cselect_b32 s53, s7, s49
	s_cselect_b32 s52, s6, s48
	s_cselect_b32 s51, s45, s43
	s_cselect_b32 s50, s44, s41
	v_lshl_add_u64 v[160:161], s[0:1], 0, v[138:139]
	s_add_i32 m0, s47, 0xc000
	ds_read_b128 v[186:189], v165
	ds_read_b128 v[190:193], v165 offset:1024
	ds_read_b128 v[194:197], v165 offset:2048
	ds_read_b128 v[198:201], v165 offset:3072
	ds_read_b128 v[202:205], v165 offset:4096
	ds_read_b128 v[206:209], v165 offset:5120
	ds_read_b128 v[210:213], v165 offset:6144
	ds_read_b128 v[214:217], v165 offset:7168
	global_load_lds_dwordx4 v[160:161], off
	v_lshl_add_u64 v[160:161], s[0:1], 0, v[140:141]
	s_add_i32 m0, s47, 0xe000
	s_nop 0
	global_load_lds_dwordx4 v[160:161], off
	s_waitcnt vmcnt(8)
	s_waitcnt lgkmcnt(0)
	s_cmp_eq_i32 s67, -2
	s_cbranch_scc1 .Lzf_2_0
	s_barrier
	s_setprio 3
	s_waitcnt lgkmcnt(0)
	v_mfma_i32_16x16x64_i8 v[126:129], v[148:151], v[186:189], v[126:129]
	v_mfma_i32_16x16x64_i8 v[122:125], v[156:159], v[186:189], v[122:125]
	v_mfma_i32_16x16x64_i8 v[114:117], v[156:159], v[194:197], v[114:117]
	v_mfma_i32_16x16x64_i8 v[118:121], v[148:151], v[194:197], v[118:121]
	v_mfma_i32_16x16x64_i8 v[110:113], v[148:151], v[202:205], v[110:113]
	v_mfma_i32_16x16x64_i8 v[106:109], v[156:159], v[202:205], v[106:109]
	v_mfma_i32_16x16x64_i8 v[98:101], v[156:159], v[210:213], v[98:101]
	v_mfma_i32_16x16x64_i8 v[102:105], v[148:151], v[210:213], v[102:105]
	v_mfma_i32_16x16x64_i8 v[126:129], v[152:155], v[190:193], v[126:129]
	v_mfma_i32_16x16x64_i8 v[122:125], v[166:169], v[190:193], v[122:125]
	v_mfma_i32_16x16x64_i8 v[114:117], v[166:169], v[198:201], v[114:117]
	v_mfma_i32_16x16x64_i8 v[118:121], v[152:155], v[198:201], v[118:121]
	v_mfma_i32_16x16x64_i8 v[110:113], v[152:155], v[206:209], v[110:113]
	v_mfma_i32_16x16x64_i8 v[106:109], v[166:169], v[206:209], v[106:109]
	v_mfma_i32_16x16x64_i8 v[98:101], v[166:169], v[214:217], v[98:101]
	v_mfma_i32_16x16x64_i8 v[102:105], v[152:155], v[214:217], v[102:105]
	s_setprio 0
	s_setprio 3
	v_mfma_i32_16x16x64_i8 v[66:69], v[170:173], v[186:189], v[66:69]
	v_mfma_i32_16x16x64_i8 v[58:61], v[178:181], v[186:189], v[58:61]
	v_mfma_i32_16x16x64_i8 v[50:53], v[178:181], v[194:197], v[50:53]
	v_mfma_i32_16x16x64_i8 v[54:57], v[170:173], v[194:197], v[54:57]
	v_mfma_i32_16x16x64_i8 v[46:49], v[170:173], v[202:205], v[46:49]
	v_mfma_i32_16x16x64_i8 v[42:45], v[178:181], v[202:205], v[42:45]
	v_mfma_i32_16x16x64_i8 v[34:37], v[178:181], v[210:213], v[34:37]
	v_mfma_i32_16x16x64_i8 v[38:41], v[170:173], v[210:213], v[38:41]
	v_mfma_i32_16x16x64_i8 v[66:69], v[174:177], v[190:193], v[66:69]
	v_mfma_i32_16x16x64_i8 v[58:61], v[182:185], v[190:193], v[58:61]
	v_mfma_i32_16x16x64_i8 v[50:53], v[182:185], v[198:201], v[50:53]
	v_mfma_i32_16x16x64_i8 v[54:57], v[174:177], v[198:201], v[54:57]
	v_mfma_i32_16x16x64_i8 v[46:49], v[174:177], v[206:209], v[46:49]
	v_mfma_i32_16x16x64_i8 v[42:45], v[182:185], v[206:209], v[42:45]
	v_mfma_i32_16x16x64_i8 v[34:37], v[182:185], v[214:217], v[34:37]
	v_mfma_i32_16x16x64_i8 v[38:41], v[174:177], v[214:217], v[38:41]
	s_setprio 0
.Lzb_2_0:
	s_barrier
	s_add_i32 s0, s62, s3
	v_lshl_add_u64 v[160:161], s[50:51], 0, v[130:131]
	s_mov_b32 m0, s0
	ds_read_b128 v[186:189], v165 offset:16384
	ds_read_b128 v[190:193], v165 offset:17408
	ds_read_b128 v[194:197], v165 offset:18432
	ds_read_b128 v[198:201], v165 offset:19456
	ds_read_b128 v[202:205], v165 offset:20480
	ds_read_b128 v[206:209], v165 offset:21504
	ds_read_b128 v[210:213], v165 offset:22528
	ds_read_b128 v[214:217], v165 offset:23552
	global_load_lds_dwordx4 v[160:161], off
	s_add_i32 m0, s0, 0x2000
	s_add_u32 s0, s50, 0x80000
	v_lshl_add_u64 v[160:161], s[50:51], 0, v[132:133]
	s_addc_u32 s1, s51, 0
	s_add_i32 s68, s63, s3
	global_load_lds_dwordx4 v[160:161], off
	v_lshl_add_u64 v[160:161], s[0:1], 0, v[130:131]
	s_mov_b32 m0, s68
	v_lshl_add_u64 v[218:219], s[52:53], 0, v[134:135]
	global_load_lds_dwordx4 v[160:161], off
	v_lshl_add_u64 v[160:161], s[0:1], 0, v[132:133]
	s_add_i32 m0, s68, 0x2000
	s_nop 0
	global_load_lds_dwordx4 v[160:161], off
	v_lshl_add_u64 v[160:161], s[52:53], 0, v[136:137]
	s_mov_b32 m0, s47
	s_nop 0
	global_load_lds_dwordx4 v[160:161], off
	s_mov_b32 m0, s55
	s_nop 0
	global_load_lds_dwordx4 v[218:219], off
	s_waitcnt vmcnt(8)
	s_waitcnt lgkmcnt(0)
	s_cmp_eq_i32 s67, -2
	s_cbranch_scc1 .Lzf_2_1
	s_barrier
	s_setprio 3
	s_waitcnt lgkmcnt(0)
	v_mfma_i32_16x16x64_i8 v[94:97], v[148:151], v[186:189], v[94:97]
	v_mfma_i32_16x16x64_i8 v[90:93], v[156:159], v[186:189], v[90:93]
	v_mfma_i32_16x16x64_i8 v[82:85], v[156:159], v[194:197], v[82:85]
	v_mfma_i32_16x16x64_i8 v[86:89], v[148:151], v[194:197], v[86:89]
	v_mfma_i32_16x16x64_i8 v[78:81], v[148:151], v[202:205], v[78:81]
	v_mfma_i32_16x16x64_i8 v[74:77], v[156:159], v[202:205], v[74:77]
	v_mfma_i32_16x16x64_i8 v[62:65], v[156:159], v[210:213], v[62:65]
	v_mfma_i32_16x16x64_i8 v[70:73], v[148:151], v[210:213], v[70:73]
	v_mfma_i32_16x16x64_i8 v[94:97], v[152:155], v[190:193], v[94:97]
	v_mfma_i32_16x16x64_i8 v[90:93], v[166:169], v[190:193], v[90:93]
	v_mfma_i32_16x16x64_i8 v[82:85], v[166:169], v[198:201], v[82:85]
	v_mfma_i32_16x16x64_i8 v[86:89], v[152:155], v[198:201], v[86:89]
	v_mfma_i32_16x16x64_i8 v[78:81], v[152:155], v[206:209], v[78:81]
	v_mfma_i32_16x16x64_i8 v[74:77], v[166:169], v[206:209], v[74:77]
	v_mfma_i32_16x16x64_i8 v[62:65], v[166:169], v[214:217], v[62:65]
	v_mfma_i32_16x16x64_i8 v[70:73], v[152:155], v[214:217], v[70:73]
	s_setprio 0
	s_setprio 3
	v_mfma_i32_16x16x64_i8 v[30:33], v[170:173], v[186:189], v[30:33]
	v_mfma_i32_16x16x64_i8 v[26:29], v[178:181], v[186:189], v[26:29]
	v_mfma_i32_16x16x64_i8 v[18:21], v[178:181], v[194:197], v[18:21]
	v_mfma_i32_16x16x64_i8 v[22:25], v[170:173], v[194:197], v[22:25]
	v_mfma_i32_16x16x64_i8 v[14:17], v[170:173], v[202:205], v[14:17]
	v_mfma_i32_16x16x64_i8 v[10:13], v[178:181], v[202:205], v[10:13]
	v_mfma_i32_16x16x64_i8 v[2:5], v[178:181], v[210:213], v[2:5]
	v_mfma_i32_16x16x64_i8 v[6:9], v[170:173], v[210:213], v[6:9]
	v_mfma_i32_16x16x64_i8 v[30:33], v[174:177], v[190:193], v[30:33]
	v_mfma_i32_16x16x64_i8 v[26:29], v[182:185], v[190:193], v[26:29]
	v_mfma_i32_16x16x64_i8 v[18:21], v[182:185], v[198:201], v[18:21]
	v_mfma_i32_16x16x64_i8 v[22:25], v[174:177], v[198:201], v[22:25]
	v_mfma_i32_16x16x64_i8 v[14:17], v[174:177], v[206:209], v[14:17]
	v_mfma_i32_16x16x64_i8 v[10:13], v[182:185], v[206:209], v[10:13]
	v_mfma_i32_16x16x64_i8 v[2:5], v[182:185], v[214:217], v[2:5]
	v_mfma_i32_16x16x64_i8 v[6:9], v[174:177], v[214:217], v[6:9]
	s_setprio 0
.Lzb_2_1:
	s_barrier
	s_add_i32 s68, 0, 0x18000
	s_add_i32 s69, 0, 0x1c000
	v_add_u32_e32 v166, s68, v147
	v_add_u32_e32 v182, s69, v147
	ds_read_b128 v[148:151], v166
	ds_read_b128 v[152:155], v166 offset:1024
	ds_read_b128 v[156:159], v166 offset:2048
	ds_read_b128 v[166:169], v166 offset:3072
	ds_read_b128 v[170:173], v182
	ds_read_b128 v[174:177], v182 offset:1024
	ds_read_b128 v[178:181], v182 offset:2048
	ds_read_b128 v[182:185], v182 offset:3072
	s_add_u32 s0, s52, 0x80000
	s_addc_u32 s1, s53, 0
	s_mov_b32 m0, s56
	v_lshl_add_u64 v[220:221], s[0:1], 0, v[136:137]
	ds_read_b128 v[186:189], v165 offset:32768
	ds_read_b128 v[190:193], v165 offset:33792
	ds_read_b128 v[194:197], v165 offset:34816
	ds_read_b128 v[198:201], v165 offset:35840
	ds_read_b128 v[202:205], v165 offset:36864
	ds_read_b128 v[206:209], v165 offset:37888
	ds_read_b128 v[210:213], v165 offset:38912
	ds_read_b128 v[214:217], v165 offset:39936
	global_load_lds_dwordx4 v[220:221], off
	v_lshl_add_u64 v[220:221], s[0:1], 0, v[134:135]
	s_mov_b32 m0, s57
	s_nop 0
	global_load_lds_dwordx4 v[220:221], off
	s_waitcnt vmcnt(8)
	s_waitcnt lgkmcnt(0)
	s_barrier
	s_setprio 3
	s_waitcnt lgkmcnt(0)
	v_mfma_i32_16x16x64_i8 v[126:129], v[148:151], v[186:189], v[126:129]
	v_mfma_i32_16x16x64_i8 v[122:125], v[156:159], v[186:189], v[122:125]
	v_mfma_i32_16x16x64_i8 v[114:117], v[156:159], v[194:197], v[114:117]
	v_mfma_i32_16x16x64_i8 v[118:121], v[148:151], v[194:197], v[118:121]
	v_mfma_i32_16x16x64_i8 v[110:113], v[148:151], v[202:205], v[110:113]
	v_mfma_i32_16x16x64_i8 v[106:109], v[156:159], v[202:205], v[106:109]
	v_mfma_i32_16x16x64_i8 v[98:101], v[156:159], v[210:213], v[98:101]
	v_mfma_i32_16x16x64_i8 v[102:105], v[148:151], v[210:213], v[102:105]
	v_mfma_i32_16x16x64_i8 v[126:129], v[152:155], v[190:193], v[126:129]
	v_mfma_i32_16x16x64_i8 v[122:125], v[166:169], v[190:193], v[122:125]
	v_mfma_i32_16x16x64_i8 v[114:117], v[166:169], v[198:201], v[114:117]
	v_mfma_i32_16x16x64_i8 v[118:121], v[152:155], v[198:201], v[118:121]
	v_mfma_i32_16x16x64_i8 v[110:113], v[152:155], v[206:209], v[110:113]
	v_mfma_i32_16x16x64_i8 v[106:109], v[166:169], v[206:209], v[106:109]
	v_mfma_i32_16x16x64_i8 v[98:101], v[166:169], v[214:217], v[98:101]
	v_mfma_i32_16x16x64_i8 v[102:105], v[152:155], v[214:217], v[102:105]
	s_setprio 0
	s_setprio 3
	v_mfma_i32_16x16x64_i8 v[66:69], v[170:173], v[186:189], v[66:69]
	v_mfma_i32_16x16x64_i8 v[58:61], v[178:181], v[186:189], v[58:61]
	v_mfma_i32_16x16x64_i8 v[50:53], v[178:181], v[194:197], v[50:53]
	v_mfma_i32_16x16x64_i8 v[54:57], v[170:173], v[194:197], v[54:57]
	v_mfma_i32_16x16x64_i8 v[46:49], v[170:173], v[202:205], v[46:49]
	v_mfma_i32_16x16x64_i8 v[42:45], v[178:181], v[202:205], v[42:45]
	v_mfma_i32_16x16x64_i8 v[34:37], v[178:181], v[210:213], v[34:37]
	v_mfma_i32_16x16x64_i8 v[38:41], v[170:173], v[210:213], v[38:41]
	v_mfma_i32_16x16x64_i8 v[66:69], v[174:177], v[190:193], v[66:69]
	v_mfma_i32_16x16x64_i8 v[58:61], v[182:185], v[190:193], v[58:61]
	v_mfma_i32_16x16x64_i8 v[50:53], v[182:185], v[198:201], v[50:53]
	v_mfma_i32_16x16x64_i8 v[54:57], v[174:177], v[198:201], v[54:57]
	v_mfma_i32_16x16x64_i8 v[46:49], v[174:177], v[206:209], v[46:49]
	v_mfma_i32_16x16x64_i8 v[42:45], v[182:185], v[206:209], v[42:45]
	v_mfma_i32_16x16x64_i8 v[34:37], v[182:185], v[214:217], v[34:37]
	v_mfma_i32_16x16x64_i8 v[38:41], v[174:177], v[214:217], v[38:41]
	s_setprio 0
	s_barrier
	s_add_u32 s0, s50, 0x4000
	s_addc_u32 s1, s51, 0
	s_add_i32 s52, s68, s3
	v_lshl_add_u64 v[220:221], s[0:1], 0, v[130:131]
	s_mov_b32 m0, s52
	ds_read_b128 v[186:189], v165 offset:49152
	ds_read_b128 v[190:193], v165 offset:50176
	ds_read_b128 v[194:197], v165 offset:51200
	ds_read_b128 v[198:201], v165 offset:52224
	ds_read_b128 v[202:205], v165 offset:53248
	ds_read_b128 v[206:209], v165 offset:54272
	ds_read_b128 v[210:213], v165 offset:55296
	ds_read_b128 v[214:217], v165 offset:56320
	global_load_lds_dwordx4 v[220:221], off
	s_add_i32 m0, s52, 0x2000
	v_lshl_add_u64 v[220:221], s[0:1], 0, v[132:133]
	s_add_u32 s0, s50, 0x84000
	s_addc_u32 s1, s51, 0
	s_add_i32 s50, s69, s3
	global_load_lds_dwordx4 v[220:221], off
	v_lshl_add_u64 v[220:221], s[0:1], 0, v[130:131]
	s_mov_b32 m0, s50
	v_lshl_add_u64 v[160:161], v[160:161], 0, s[20:21]
	global_load_lds_dwordx4 v[220:221], off
	v_lshl_add_u64 v[220:221], s[0:1], 0, v[132:133]
	s_add_i32 m0, s50, 0x2000
	s_nop 0
	global_load_lds_dwordx4 v[220:221], off
	s_mov_b32 m0, s59
	s_nop 0
	global_load_lds_dwordx4 v[160:161], off
	v_lshl_add_u64 v[160:161], v[218:219], 0, s[20:21]
	s_mov_b32 m0, s60
	s_nop 0
	global_load_lds_dwordx4 v[160:161], off
	s_waitcnt vmcnt(8)
	s_waitcnt lgkmcnt(0)
	s_barrier
	s_setprio 3
	s_waitcnt lgkmcnt(0)
	v_mfma_i32_16x16x64_i8 v[94:97], v[148:151], v[186:189], v[94:97]
	v_mfma_i32_16x16x64_i8 v[90:93], v[156:159], v[186:189], v[90:93]
	v_mfma_i32_16x16x64_i8 v[82:85], v[156:159], v[194:197], v[82:85]
	v_mfma_i32_16x16x64_i8 v[86:89], v[148:151], v[194:197], v[86:89]
	v_mfma_i32_16x16x64_i8 v[78:81], v[148:151], v[202:205], v[78:81]
	v_mfma_i32_16x16x64_i8 v[74:77], v[156:159], v[202:205], v[74:77]
	v_mfma_i32_16x16x64_i8 v[62:65], v[156:159], v[210:213], v[62:65]
	v_mfma_i32_16x16x64_i8 v[70:73], v[148:151], v[210:213], v[70:73]
	v_mfma_i32_16x16x64_i8 v[94:97], v[152:155], v[190:193], v[94:97]
	v_mfma_i32_16x16x64_i8 v[90:93], v[166:169], v[190:193], v[90:93]
	v_mfma_i32_16x16x64_i8 v[82:85], v[166:169], v[198:201], v[82:85]
	v_mfma_i32_16x16x64_i8 v[86:89], v[152:155], v[198:201], v[86:89]
	v_mfma_i32_16x16x64_i8 v[78:81], v[152:155], v[206:209], v[78:81]
	v_mfma_i32_16x16x64_i8 v[74:77], v[166:169], v[206:209], v[74:77]
	v_mfma_i32_16x16x64_i8 v[62:65], v[166:169], v[214:217], v[62:65]
	v_mfma_i32_16x16x64_i8 v[70:73], v[152:155], v[214:217], v[70:73]
	s_setprio 0
	s_setprio 3
	v_mfma_i32_16x16x64_i8 v[30:33], v[170:173], v[186:189], v[30:33]
	v_mfma_i32_16x16x64_i8 v[26:29], v[178:181], v[186:189], v[26:29]
	v_mfma_i32_16x16x64_i8 v[18:21], v[178:181], v[194:197], v[18:21]
	v_mfma_i32_16x16x64_i8 v[22:25], v[170:173], v[194:197], v[22:25]
	v_mfma_i32_16x16x64_i8 v[14:17], v[170:173], v[202:205], v[14:17]
	v_mfma_i32_16x16x64_i8 v[10:13], v[178:181], v[202:205], v[10:13]
	v_mfma_i32_16x16x64_i8 v[2:5], v[178:181], v[210:213], v[2:5]
	v_mfma_i32_16x16x64_i8 v[6:9], v[170:173], v[210:213], v[6:9]
	v_mfma_i32_16x16x64_i8 v[30:33], v[174:177], v[190:193], v[30:33]
	v_mfma_i32_16x16x64_i8 v[26:29], v[182:185], v[190:193], v[26:29]
	v_mfma_i32_16x16x64_i8 v[18:21], v[182:185], v[198:201], v[18:21]
	v_mfma_i32_16x16x64_i8 v[22:25], v[174:177], v[198:201], v[22:25]
	v_mfma_i32_16x16x64_i8 v[14:17], v[174:177], v[206:209], v[14:17]
	v_mfma_i32_16x16x64_i8 v[10:13], v[182:185], v[206:209], v[10:13]
	v_mfma_i32_16x16x64_i8 v[2:5], v[182:185], v[214:217], v[2:5]
	v_mfma_i32_16x16x64_i8 v[6:9], v[174:177], v[214:217], v[6:9]
	s_setprio 0
	s_barrier
	s_add_i32 s67, s67, 2
	s_add_u32 s41, s41, 0x8000
	s_addc_u32 s43, s43, 0
	s_cmp_gt_u32 s67, 29
	s_mov_b64 s[0:1], s[48:49]
	s_cbranch_scc0 .LBB0_558
	s_and_b64 vcc, exec, s[24:25]
	s_cbranch_vccz .LBB0_561
	s_barrier

.Lzf_2_0:
	s_barrier
	s_setprio 3
	s_waitcnt lgkmcnt(0)
	v_mfma_i32_16x16x64_i8 v[126:129], v[148:151], v[186:189], 0
	v_mfma_i32_16x16x64_i8 v[122:125], v[156:159], v[186:189], 0
	v_mfma_i32_16x16x64_i8 v[114:117], v[156:159], v[194:197], 0
	v_mfma_i32_16x16x64_i8 v[118:121], v[148:151], v[194:197], 0
	v_mfma_i32_16x16x64_i8 v[110:113], v[148:151], v[202:205], 0
	v_mfma_i32_16x16x64_i8 v[106:109], v[156:159], v[202:205], 0
	v_mfma_i32_16x16x64_i8 v[98:101], v[156:159], v[210:213], 0
	v_mfma_i32_16x16x64_i8 v[102:105], v[148:151], v[210:213], 0
	v_mfma_i32_16x16x64_i8 v[126:129], v[152:155], v[190:193], v[126:129]
	v_mfma_i32_16x16x64_i8 v[122:125], v[166:169], v[190:193], v[122:125]
	v_mfma_i32_16x16x64_i8 v[114:117], v[166:169], v[198:201], v[114:117]
	v_mfma_i32_16x16x64_i8 v[118:121], v[152:155], v[198:201], v[118:121]
	v_mfma_i32_16x16x64_i8 v[110:113], v[152:155], v[206:209], v[110:113]
	v_mfma_i32_16x16x64_i8 v[106:109], v[166:169], v[206:209], v[106:109]
	v_mfma_i32_16x16x64_i8 v[98:101], v[166:169], v[214:217], v[98:101]
	v_mfma_i32_16x16x64_i8 v[102:105], v[152:155], v[214:217], v[102:105]
	s_setprio 0
	s_setprio 3
	v_mfma_i32_16x16x64_i8 v[66:69], v[170:173], v[186:189], 0
	v_mfma_i32_16x16x64_i8 v[58:61], v[178:181], v[186:189], 0
	v_mfma_i32_16x16x64_i8 v[50:53], v[178:181], v[194:197], 0
	v_mfma_i32_16x16x64_i8 v[54:57], v[170:173], v[194:197], 0
	v_mfma_i32_16x16x64_i8 v[46:49], v[170:173], v[202:205], 0
	v_mfma_i32_16x16x64_i8 v[42:45], v[178:181], v[202:205], 0
	v_mfma_i32_16x16x64_i8 v[34:37], v[178:181], v[210:213], 0
	v_mfma_i32_16x16x64_i8 v[38:41], v[170:173], v[210:213], 0
	v_mfma_i32_16x16x64_i8 v[66:69], v[174:177], v[190:193], v[66:69]
	v_mfma_i32_16x16x64_i8 v[58:61], v[182:185], v[190:193], v[58:61]
	v_mfma_i32_16x16x64_i8 v[50:53], v[182:185], v[198:201], v[50:53]
	v_mfma_i32_16x16x64_i8 v[54:57], v[174:177], v[198:201], v[54:57]
	v_mfma_i32_16x16x64_i8 v[46:49], v[174:177], v[206:209], v[46:49]
	v_mfma_i32_16x16x64_i8 v[42:45], v[182:185], v[206:209], v[42:45]
	v_mfma_i32_16x16x64_i8 v[34:37], v[182:185], v[214:217], v[34:37]
	v_mfma_i32_16x16x64_i8 v[38:41], v[174:177], v[214:217], v[38:41]
	s_setprio 0
	s_branch .Lzb_2_0
.Lzf_2_1:
	s_barrier
	s_setprio 3
	s_waitcnt lgkmcnt(0)
	v_mfma_i32_16x16x64_i8 v[94:97], v[148:151], v[186:189], 0
	v_mfma_i32_16x16x64_i8 v[90:93], v[156:159], v[186:189], 0
	v_mfma_i32_16x16x64_i8 v[82:85], v[156:159], v[194:197], 0
	v_mfma_i32_16x16x64_i8 v[86:89], v[148:151], v[194:197], 0
	v_mfma_i32_16x16x64_i8 v[78:81], v[148:151], v[202:205], 0
	v_mfma_i32_16x16x64_i8 v[74:77], v[156:159], v[202:205], 0
	v_mfma_i32_16x16x64_i8 v[62:65], v[156:159], v[210:213], 0
	v_mfma_i32_16x16x64_i8 v[70:73], v[148:151], v[210:213], 0
	v_mfma_i32_16x16x64_i8 v[94:97], v[152:155], v[190:193], v[94:97]
	v_mfma_i32_16x16x64_i8 v[90:93], v[166:169], v[190:193], v[90:93]
	v_mfma_i32_16x16x64_i8 v[82:85], v[166:169], v[198:201], v[82:85]
	v_mfma_i32_16x16x64_i8 v[86:89], v[152:155], v[198:201], v[86:89]
	v_mfma_i32_16x16x64_i8 v[78:81], v[152:155], v[206:209], v[78:81]
	v_mfma_i32_16x16x64_i8 v[74:77], v[166:169], v[206:209], v[74:77]
	v_mfma_i32_16x16x64_i8 v[62:65], v[166:169], v[214:217], v[62:65]
	v_mfma_i32_16x16x64_i8 v[70:73], v[152:155], v[214:217], v[70:73]
	s_setprio 0
	s_setprio 3
	v_mfma_i32_16x16x64_i8 v[30:33], v[170:173], v[186:189], 0
	v_mfma_i32_16x16x64_i8 v[26:29], v[178:181], v[186:189], 0
	v_mfma_i32_16x16x64_i8 v[18:21], v[178:181], v[194:197], 0
	v_mfma_i32_16x16x64_i8 v[22:25], v[170:173], v[194:197], 0
	v_mfma_i32_16x16x64_i8 v[14:17], v[170:173], v[202:205], 0
	v_mfma_i32_16x16x64_i8 v[10:13], v[178:181], v[202:205], 0
	v_mfma_i32_16x16x64_i8 v[2:5], v[178:181], v[210:213], 0
	v_mfma_i32_16x16x64_i8 v[6:9], v[170:173], v[210:213], 0
	v_mfma_i32_16x16x64_i8 v[30:33], v[174:177], v[190:193], v[30:33]
	v_mfma_i32_16x16x64_i8 v[26:29], v[182:185], v[190:193], v[26:29]
	v_mfma_i32_16x16x64_i8 v[18:21], v[182:185], v[198:201], v[18:21]
	v_mfma_i32_16x16x64_i8 v[22:25], v[174:177], v[198:201], v[22:25]
	v_mfma_i32_16x16x64_i8 v[14:17], v[174:177], v[206:209], v[14:17]
	v_mfma_i32_16x16x64_i8 v[10:13], v[182:185], v[206:209], v[10:13]
	v_mfma_i32_16x16x64_i8 v[2:5], v[182:185], v[214:217], v[2:5]
	v_mfma_i32_16x16x64_i8 v[6:9], v[174:177], v[214:217], v[6:9]
	s_setprio 0
	s_branch .Lzb_2_1

.LBB0_583:
	s_add_u32 s39, s0, 0x8000
	s_addc_u32 s41, s1, 0
	s_add_u32 s0, s46, 0x100080
	s_addc_u32 s1, s47, 0
	s_mov_b32 s64, -2
.LBB0_584:
	ds_read_b128 v[148:151], v157
	ds_read_b128 v[152:155], v157 offset:1024
	ds_read_b128 v[160:163], v157 offset:2048
	ds_read_b128 v[164:167], v157 offset:3072
	ds_read_b128 v[168:171], v158
	ds_read_b128 v[172:175], v158 offset:1024
	ds_read_b128 v[176:179], v158 offset:2048
	ds_read_b128 v[180:183], v158 offset:3072
	s_add_u32 s46, s0, 0xfff00080
	s_addc_u32 s47, s1, -1
	s_cmp_eq_u32 s64, 60
	s_cselect_b32 s49, s7, s47
	s_cselect_b32 s48, s6, s46
	s_cselect_b32 s47, s43, s41
	s_cselect_b32 s46, s42, s39
	v_lshl_add_u64 v[216:217], s[0:1], 0, v[138:139]
	s_add_i32 m0, s45, 0xc000
	ds_read_b128 v[184:187], v159
	ds_read_b128 v[188:191], v159 offset:1024
	ds_read_b128 v[192:195], v159 offset:2048
	ds_read_b128 v[196:199], v159 offset:3072
	ds_read_b128 v[200:203], v159 offset:4096
	ds_read_b128 v[204:207], v159 offset:5120
	ds_read_b128 v[208:211], v159 offset:6144
	ds_read_b128 v[212:215], v159 offset:7168
	global_load_lds_dwordx4 v[216:217], off
	v_lshl_add_u64 v[216:217], s[0:1], 0, v[140:141]
	s_add_i32 m0, s45, 0xe000
	s_nop 0
	global_load_lds_dwordx4 v[216:217], off
	s_waitcnt vmcnt(8)
	s_waitcnt lgkmcnt(0)
	s_cmp_eq_i32 s64, -2
	s_cbranch_scc1 .Lzf_3_0
	s_barrier
	s_setprio 3
	s_waitcnt lgkmcnt(0)
	v_mfma_f32_16x16x32_bf16 v[126:129], v[148:151], v[184:187], v[126:129]
	v_mfma_f32_16x16x32_bf16 v[122:125], v[160:163], v[184:187], v[122:125]
	v_mfma_f32_16x16x32_bf16 v[106:109], v[160:163], v[192:195], v[106:109]
	v_mfma_f32_16x16x32_bf16 v[110:113], v[148:151], v[192:195], v[110:113]
	v_mfma_f32_16x16x32_bf16 v[94:97], v[148:151], v[200:203], v[94:97]
	v_mfma_f32_16x16x32_bf16 v[90:93], v[160:163], v[200:203], v[90:93]
	v_mfma_f32_16x16x32_bf16 v[78:81], v[160:163], v[208:211], v[78:81]
	v_mfma_f32_16x16x32_bf16 v[86:89], v[148:151], v[208:211], v[86:89]
	v_mfma_f32_16x16x32_bf16 v[126:129], v[152:155], v[188:191], v[126:129]
	v_mfma_f32_16x16x32_bf16 v[122:125], v[164:167], v[188:191], v[122:125]
	v_mfma_f32_16x16x32_bf16 v[106:109], v[164:167], v[196:199], v[106:109]
	v_mfma_f32_16x16x32_bf16 v[110:113], v[152:155], v[196:199], v[110:113]
	v_mfma_f32_16x16x32_bf16 v[94:97], v[152:155], v[204:207], v[94:97]
	v_mfma_f32_16x16x32_bf16 v[90:93], v[164:167], v[204:207], v[90:93]
	v_mfma_f32_16x16x32_bf16 v[78:81], v[164:167], v[212:215], v[78:81]
	v_mfma_f32_16x16x32_bf16 v[86:89], v[152:155], v[212:215], v[86:89]
	s_setprio 0
	s_setprio 3
	v_mfma_f32_16x16x32_bf16 v[118:121], v[168:171], v[184:187], v[118:121]
	v_mfma_f32_16x16x32_bf16 v[114:117], v[176:179], v[184:187], v[114:117]
	v_mfma_f32_16x16x32_bf16 v[98:101], v[176:179], v[192:195], v[98:101]
	v_mfma_f32_16x16x32_bf16 v[102:105], v[168:171], v[192:195], v[102:105]
	v_mfma_f32_16x16x32_bf16 v[82:85], v[168:171], v[200:203], v[82:85]
	v_mfma_f32_16x16x32_bf16 v[74:77], v[176:179], v[200:203], v[74:77]
	v_mfma_f32_16x16x32_bf16 v[66:69], v[176:179], v[208:211], v[66:69]
	v_mfma_f32_16x16x32_bf16 v[70:73], v[168:171], v[208:211], v[70:73]
	v_mfma_f32_16x16x32_bf16 v[118:121], v[172:175], v[188:191], v[118:121]
	v_mfma_f32_16x16x32_bf16 v[114:117], v[180:183], v[188:191], v[114:117]
	v_mfma_f32_16x16x32_bf16 v[98:101], v[180:183], v[196:199], v[98:101]
	v_mfma_f32_16x16x32_bf16 v[102:105], v[172:175], v[196:199], v[102:105]
	v_mfma_f32_16x16x32_bf16 v[82:85], v[172:175], v[204:207], v[82:85]
	v_mfma_f32_16x16x32_bf16 v[74:77], v[180:183], v[204:207], v[74:77]
	v_mfma_f32_16x16x32_bf16 v[66:69], v[180:183], v[212:215], v[66:69]
	v_mfma_f32_16x16x32_bf16 v[70:73], v[172:175], v[212:215], v[70:73]
	s_setprio 0
.Lzb_3_0:
	s_barrier
	s_add_i32 s65, s60, s52
	v_lshl_add_u64 v[216:217], s[46:47], 0, v[130:131]
	s_mov_b32 m0, s65
	ds_read_b128 v[184:187], v159 offset:16384
	ds_read_b128 v[188:191], v159 offset:17408
	ds_read_b128 v[192:195], v159 offset:18432
	ds_read_b128 v[196:199], v159 offset:19456
	ds_read_b128 v[200:203], v159 offset:20480
	ds_read_b128 v[204:207], v159 offset:21504
	ds_read_b128 v[208:211], v159 offset:22528
	ds_read_b128 v[212:215], v159 offset:23552
	global_load_lds_dwordx4 v[216:217], off
	s_add_i32 m0, s65, 0x2000
	s_add_u32 s68, s46, 0x100000
	v_lshl_add_u64 v[216:217], s[46:47], 0, v[134:135]
	s_addc_u32 s69, s47, 0
	s_add_i32 s65, s61, s52
	global_load_lds_dwordx4 v[216:217], off
	v_lshl_add_u64 v[216:217], s[68:69], 0, v[130:131]
	s_mov_b32 m0, s65
	v_lshl_add_u64 v[218:219], s[48:49], 0, v[136:137]
	global_load_lds_dwordx4 v[216:217], off
	v_lshl_add_u64 v[216:217], s[68:69], 0, v[134:135]
	s_add_i32 m0, s65, 0x2000
	s_nop 0
	global_load_lds_dwordx4 v[216:217], off
	v_lshl_add_u64 v[216:217], s[48:49], 0, v[132:133]
	s_mov_b32 m0, s45
	s_nop 0
	global_load_lds_dwordx4 v[216:217], off
	s_mov_b32 m0, s53
	s_nop 0
	global_load_lds_dwordx4 v[218:219], off
	s_waitcnt vmcnt(8)
	s_waitcnt lgkmcnt(0)
	s_cmp_eq_i32 s64, -2
	s_cbranch_scc1 .Lzf_3_1
	s_barrier
	s_setprio 3
	s_waitcnt lgkmcnt(0)
	v_mfma_f32_16x16x32_bf16 v[62:65], v[148:151], v[184:187], v[62:65]
	v_mfma_f32_16x16x32_bf16 v[58:61], v[160:163], v[184:187], v[58:61]
	v_mfma_f32_16x16x32_bf16 v[42:45], v[160:163], v[192:195], v[42:45]
	v_mfma_f32_16x16x32_bf16 v[46:49], v[148:151], v[192:195], v[46:49]
	v_mfma_f32_16x16x32_bf16 v[30:33], v[148:151], v[200:203], v[30:33]
	v_mfma_f32_16x16x32_bf16 v[26:29], v[160:163], v[200:203], v[26:29]
	v_mfma_f32_16x16x32_bf16 v[10:13], v[160:163], v[208:211], v[10:13]
	v_mfma_f32_16x16x32_bf16 v[14:17], v[148:151], v[208:211], v[14:17]
	v_mfma_f32_16x16x32_bf16 v[62:65], v[152:155], v[188:191], v[62:65]
	v_mfma_f32_16x16x32_bf16 v[58:61], v[164:167], v[188:191], v[58:61]
	v_mfma_f32_16x16x32_bf16 v[42:45], v[164:167], v[196:199], v[42:45]
	v_mfma_f32_16x16x32_bf16 v[46:49], v[152:155], v[196:199], v[46:49]
	v_mfma_f32_16x16x32_bf16 v[30:33], v[152:155], v[204:207], v[30:33]
	v_mfma_f32_16x16x32_bf16 v[26:29], v[164:167], v[204:207], v[26:29]
	v_mfma_f32_16x16x32_bf16 v[10:13], v[164:167], v[212:215], v[10:13]
	v_mfma_f32_16x16x32_bf16 v[14:17], v[152:155], v[212:215], v[14:17]
	s_setprio 0
	s_setprio 3
	v_mfma_f32_16x16x32_bf16 v[54:57], v[168:171], v[184:187], v[54:57]
	v_mfma_f32_16x16x32_bf16 v[50:53], v[176:179], v[184:187], v[50:53]
	v_mfma_f32_16x16x32_bf16 v[34:37], v[176:179], v[192:195], v[34:37]
	v_mfma_f32_16x16x32_bf16 v[38:41], v[168:171], v[192:195], v[38:41]
	v_mfma_f32_16x16x32_bf16 v[22:25], v[168:171], v[200:203], v[22:25]
	v_mfma_f32_16x16x32_bf16 v[18:21], v[176:179], v[200:203], v[18:21]
	v_mfma_f32_16x16x32_bf16 v[2:5], v[176:179], v[208:211], v[2:5]
	v_mfma_f32_16x16x32_bf16 v[6:9], v[168:171], v[208:211], v[6:9]
	v_mfma_f32_16x16x32_bf16 v[54:57], v[172:175], v[188:191], v[54:57]
	v_mfma_f32_16x16x32_bf16 v[50:53], v[180:183], v[188:191], v[50:53]
	v_mfma_f32_16x16x32_bf16 v[34:37], v[180:183], v[196:199], v[34:37]
	v_mfma_f32_16x16x32_bf16 v[38:41], v[172:175], v[196:199], v[38:41]
	v_mfma_f32_16x16x32_bf16 v[22:25], v[172:175], v[204:207], v[22:25]
	v_mfma_f32_16x16x32_bf16 v[18:21], v[180:183], v[204:207], v[18:21]
	v_mfma_f32_16x16x32_bf16 v[2:5], v[180:183], v[212:215], v[2:5]
	v_mfma_f32_16x16x32_bf16 v[6:9], v[172:175], v[212:215], v[6:9]
	s_setprio 0
.Lzb_3_1:
	s_barrier
	s_add_i32 s65, 0, 0x18000
	s_add_i32 s67, 0, 0x1c000
	v_add_u32_e32 v164, s65, v147
	v_add_u32_e32 v180, s67, v147
	ds_read_b128 v[148:151], v164
	ds_read_b128 v[152:155], v164 offset:1024
	ds_read_b128 v[160:163], v164 offset:2048
	ds_read_b128 v[164:167], v164 offset:3072
	ds_read_b128 v[168:171], v180
	ds_read_b128 v[172:175], v180 offset:1024
	ds_read_b128 v[176:179], v180 offset:2048
	ds_read_b128 v[180:183], v180 offset:3072
	s_add_u32 s48, s48, 0x100000
	s_addc_u32 s49, s49, 0
	s_mov_b32 m0, s54
	v_lshl_add_u64 v[220:221], s[48:49], 0, v[132:133]
	ds_read_b128 v[184:187], v159 offset:32768
	ds_read_b128 v[188:191], v159 offset:33792
	ds_read_b128 v[192:195], v159 offset:34816
	ds_read_b128 v[196:199], v159 offset:35840
	ds_read_b128 v[200:203], v159 offset:36864
	ds_read_b128 v[204:207], v159 offset:37888
	ds_read_b128 v[208:211], v159 offset:38912
	ds_read_b128 v[212:215], v159 offset:39936
	global_load_lds_dwordx4 v[220:221], off
	v_lshl_add_u64 v[220:221], s[48:49], 0, v[136:137]
	s_mov_b32 m0, s55
	s_nop 0
	global_load_lds_dwordx4 v[220:221], off
	s_waitcnt vmcnt(8)
	s_waitcnt lgkmcnt(0)
	s_barrier
	s_setprio 3
	s_waitcnt lgkmcnt(0)
	v_mfma_f32_16x16x32_bf16 v[126:129], v[148:151], v[184:187], v[126:129]
	v_mfma_f32_16x16x32_bf16 v[122:125], v[160:163], v[184:187], v[122:125]
	v_mfma_f32_16x16x32_bf16 v[106:109], v[160:163], v[192:195], v[106:109]
	v_mfma_f32_16x16x32_bf16 v[110:113], v[148:151], v[192:195], v[110:113]
	v_mfma_f32_16x16x32_bf16 v[94:97], v[148:151], v[200:203], v[94:97]
	v_mfma_f32_16x16x32_bf16 v[90:93], v[160:163], v[200:203], v[90:93]
	v_mfma_f32_16x16x32_bf16 v[78:81], v[160:163], v[208:211], v[78:81]
	v_mfma_f32_16x16x32_bf16 v[86:89], v[148:151], v[208:211], v[86:89]
	v_mfma_f32_16x16x32_bf16 v[126:129], v[152:155], v[188:191], v[126:129]
	v_mfma_f32_16x16x32_bf16 v[122:125], v[164:167], v[188:191], v[122:125]
	v_mfma_f32_16x16x32_bf16 v[106:109], v[164:167], v[196:199], v[106:109]
	v_mfma_f32_16x16x32_bf16 v[110:113], v[152:155], v[196:199], v[110:113]
	v_mfma_f32_16x16x32_bf16 v[94:97], v[152:155], v[204:207], v[94:97]
	v_mfma_f32_16x16x32_bf16 v[90:93], v[164:167], v[204:207], v[90:93]
	v_mfma_f32_16x16x32_bf16 v[78:81], v[164:167], v[212:215], v[78:81]
	v_mfma_f32_16x16x32_bf16 v[86:89], v[152:155], v[212:215], v[86:89]
	s_setprio 0
	s_setprio 3
	v_mfma_f32_16x16x32_bf16 v[118:121], v[168:171], v[184:187], v[118:121]
	v_mfma_f32_16x16x32_bf16 v[114:117], v[176:179], v[184:187], v[114:117]
	v_mfma_f32_16x16x32_bf16 v[98:101], v[176:179], v[192:195], v[98:101]
	v_mfma_f32_16x16x32_bf16 v[102:105], v[168:171], v[192:195], v[102:105]
	v_mfma_f32_16x16x32_bf16 v[82:85], v[168:171], v[200:203], v[82:85]
	v_mfma_f32_16x16x32_bf16 v[74:77], v[176:179], v[200:203], v[74:77]
	v_mfma_f32_16x16x32_bf16 v[66:69], v[176:179], v[208:211], v[66:69]
	v_mfma_f32_16x16x32_bf16 v[70:73], v[168:171], v[208:211], v[70:73]
	v_mfma_f32_16x16x32_bf16 v[118:121], v[172:175], v[188:191], v[118:121]
	v_mfma_f32_16x16x32_bf16 v[114:117], v[180:183], v[188:191], v[114:117]
	v_mfma_f32_16x16x32_bf16 v[98:101], v[180:183], v[196:199], v[98:101]
	v_mfma_f32_16x16x32_bf16 v[102:105], v[172:175], v[196:199], v[102:105]
	v_mfma_f32_16x16x32_bf16 v[82:85], v[172:175], v[204:207], v[82:85]
	v_mfma_f32_16x16x32_bf16 v[74:77], v[180:183], v[204:207], v[74:77]
	v_mfma_f32_16x16x32_bf16 v[66:69], v[180:183], v[212:215], v[66:69]
	v_mfma_f32_16x16x32_bf16 v[70:73], v[172:175], v[212:215], v[70:73]
	s_setprio 0
	s_barrier
	s_add_u32 s48, s46, 0x4000
	s_addc_u32 s49, s47, 0
	s_add_i32 s65, s65, s52
	v_lshl_add_u64 v[220:221], s[48:49], 0, v[130:131]
	s_mov_b32 m0, s65
	ds_read_b128 v[184:187], v159 offset:49152
	ds_read_b128 v[188:191], v159 offset:50176
	ds_read_b128 v[192:195], v159 offset:51200
	ds_read_b128 v[196:199], v159 offset:52224
	ds_read_b128 v[200:203], v159 offset:53248
	ds_read_b128 v[204:207], v159 offset:54272
	ds_read_b128 v[208:211], v159 offset:55296
	ds_read_b128 v[212:215], v159 offset:56320
	global_load_lds_dwordx4 v[220:221], off
	s_add_i32 m0, s65, 0x2000
	s_add_u32 s46, s46, 0x104000
	v_lshl_add_u64 v[220:221], s[48:49], 0, v[134:135]
	s_addc_u32 s47, s47, 0
	s_add_i32 s48, s67, s52
	global_load_lds_dwordx4 v[220:221], off
	v_lshl_add_u64 v[220:221], s[46:47], 0, v[130:131]
	s_mov_b32 m0, s48
	v_lshl_add_u64 v[216:217], v[216:217], 0, s[20:21]
	global_load_lds_dwordx4 v[220:221], off
	v_lshl_add_u64 v[220:221], s[46:47], 0, v[134:135]
	s_add_i32 m0, s48, 0x2000
	s_nop 0
	global_load_lds_dwordx4 v[220:221], off
	s_mov_b32 m0, s57
	s_nop 0
	global_load_lds_dwordx4 v[216:217], off
	v_lshl_add_u64 v[216:217], v[218:219], 0, s[20:21]
	s_mov_b32 m0, s58
	s_nop 0
	global_load_lds_dwordx4 v[216:217], off
	s_waitcnt vmcnt(8)
	s_waitcnt lgkmcnt(0)
	s_barrier
	s_setprio 3
	s_waitcnt lgkmcnt(0)
	v_mfma_f32_16x16x32_bf16 v[62:65], v[148:151], v[184:187], v[62:65]
	v_mfma_f32_16x16x32_bf16 v[58:61], v[160:163], v[184:187], v[58:61]
	v_mfma_f32_16x16x32_bf16 v[42:45], v[160:163], v[192:195], v[42:45]
	v_mfma_f32_16x16x32_bf16 v[46:49], v[148:151], v[192:195], v[46:49]
	v_mfma_f32_16x16x32_bf16 v[30:33], v[148:151], v[200:203], v[30:33]
	v_mfma_f32_16x16x32_bf16 v[26:29], v[160:163], v[200:203], v[26:29]
	v_mfma_f32_16x16x32_bf16 v[10:13], v[160:163], v[208:211], v[10:13]
	v_mfma_f32_16x16x32_bf16 v[14:17], v[148:151], v[208:211], v[14:17]
	v_mfma_f32_16x16x32_bf16 v[62:65], v[152:155], v[188:191], v[62:65]
	v_mfma_f32_16x16x32_bf16 v[58:61], v[164:167], v[188:191], v[58:61]
	v_mfma_f32_16x16x32_bf16 v[42:45], v[164:167], v[196:199], v[42:45]
	v_mfma_f32_16x16x32_bf16 v[46:49], v[152:155], v[196:199], v[46:49]
	v_mfma_f32_16x16x32_bf16 v[30:33], v[152:155], v[204:207], v[30:33]
	v_mfma_f32_16x16x32_bf16 v[26:29], v[164:167], v[204:207], v[26:29]
	v_mfma_f32_16x16x32_bf16 v[10:13], v[164:167], v[212:215], v[10:13]
	v_mfma_f32_16x16x32_bf16 v[14:17], v[152:155], v[212:215], v[14:17]
	s_setprio 0
	s_setprio 3
	v_mfma_f32_16x16x32_bf16 v[54:57], v[168:171], v[184:187], v[54:57]
	v_mfma_f32_16x16x32_bf16 v[50:53], v[176:179], v[184:187], v[50:53]
	v_mfma_f32_16x16x32_bf16 v[34:37], v[176:179], v[192:195], v[34:37]
	v_mfma_f32_16x16x32_bf16 v[38:41], v[168:171], v[192:195], v[38:41]
	v_mfma_f32_16x16x32_bf16 v[22:25], v[168:171], v[200:203], v[22:25]
	v_mfma_f32_16x16x32_bf16 v[18:21], v[176:179], v[200:203], v[18:21]
	v_mfma_f32_16x16x32_bf16 v[2:5], v[176:179], v[208:211], v[2:5]
	v_mfma_f32_16x16x32_bf16 v[6:9], v[168:171], v[208:211], v[6:9]
	v_mfma_f32_16x16x32_bf16 v[54:57], v[172:175], v[188:191], v[54:57]
	v_mfma_f32_16x16x32_bf16 v[50:53], v[180:183], v[188:191], v[50:53]
	v_mfma_f32_16x16x32_bf16 v[34:37], v[180:183], v[196:199], v[34:37]
	v_mfma_f32_16x16x32_bf16 v[38:41], v[172:175], v[196:199], v[38:41]
	v_mfma_f32_16x16x32_bf16 v[22:25], v[172:175], v[204:207], v[22:25]
	v_mfma_f32_16x16x32_bf16 v[18:21], v[180:183], v[204:207], v[18:21]
	v_mfma_f32_16x16x32_bf16 v[2:5], v[180:183], v[212:215], v[2:5]
	v_mfma_f32_16x16x32_bf16 v[6:9], v[172:175], v[212:215], v[6:9]
	s_setprio 0
	s_barrier
	s_add_i32 s64, s64, 2
	s_add_u32 s39, s39, 0x8000
	s_addc_u32 s41, s41, 0
	s_add_u32 s0, s0, 0x100
	s_addc_u32 s1, s1, 0
	s_cmp_gt_u32 s64, 61
	s_cbranch_scc0 .LBB0_584
	s_and_b64 vcc, exec, s[24:25]
	s_cbranch_vccz .LBB0_587
	s_barrier

.Lzf_3_0:
	s_barrier
	s_setprio 3
	s_waitcnt lgkmcnt(0)
	v_mfma_f32_16x16x32_bf16 v[126:129], v[148:151], v[184:187], 0
	v_mfma_f32_16x16x32_bf16 v[122:125], v[160:163], v[184:187], 0
	v_mfma_f32_16x16x32_bf16 v[106:109], v[160:163], v[192:195], 0
	v_mfma_f32_16x16x32_bf16 v[110:113], v[148:151], v[192:195], 0
	v_mfma_f32_16x16x32_bf16 v[94:97], v[148:151], v[200:203], 0
	v_mfma_f32_16x16x32_bf16 v[90:93], v[160:163], v[200:203], 0
	v_mfma_f32_16x16x32_bf16 v[78:81], v[160:163], v[208:211], 0
	v_mfma_f32_16x16x32_bf16 v[86:89], v[148:151], v[208:211], 0
	v_mfma_f32_16x16x32_bf16 v[126:129], v[152:155], v[188:191], v[126:129]
	v_mfma_f32_16x16x32_bf16 v[122:125], v[164:167], v[188:191], v[122:125]
	v_mfma_f32_16x16x32_bf16 v[106:109], v[164:167], v[196:199], v[106:109]
	v_mfma_f32_16x16x32_bf16 v[110:113], v[152:155], v[196:199], v[110:113]
	v_mfma_f32_16x16x32_bf16 v[94:97], v[152:155], v[204:207], v[94:97]
	v_mfma_f32_16x16x32_bf16 v[90:93], v[164:167], v[204:207], v[90:93]
	v_mfma_f32_16x16x32_bf16 v[78:81], v[164:167], v[212:215], v[78:81]
	v_mfma_f32_16x16x32_bf16 v[86:89], v[152:155], v[212:215], v[86:89]
	s_setprio 0
	s_setprio 3
	v_mfma_f32_16x16x32_bf16 v[118:121], v[168:171], v[184:187], 0
	v_mfma_f32_16x16x32_bf16 v[114:117], v[176:179], v[184:187], 0
	v_mfma_f32_16x16x32_bf16 v[98:101], v[176:179], v[192:195], 0
	v_mfma_f32_16x16x32_bf16 v[102:105], v[168:171], v[192:195], 0
	v_mfma_f32_16x16x32_bf16 v[82:85], v[168:171], v[200:203], 0
	v_mfma_f32_16x16x32_bf16 v[74:77], v[176:179], v[200:203], 0
	v_mfma_f32_16x16x32_bf16 v[66:69], v[176:179], v[208:211], 0
	v_mfma_f32_16x16x32_bf16 v[70:73], v[168:171], v[208:211], 0
	v_mfma_f32_16x16x32_bf16 v[118:121], v[172:175], v[188:191], v[118:121]
	v_mfma_f32_16x16x32_bf16 v[114:117], v[180:183], v[188:191], v[114:117]
	v_mfma_f32_16x16x32_bf16 v[98:101], v[180:183], v[196:199], v[98:101]
	v_mfma_f32_16x16x32_bf16 v[102:105], v[172:175], v[196:199], v[102:105]
	v_mfma_f32_16x16x32_bf16 v[82:85], v[172:175], v[204:207], v[82:85]
	v_mfma_f32_16x16x32_bf16 v[74:77], v[180:183], v[204:207], v[74:77]
	v_mfma_f32_16x16x32_bf16 v[66:69], v[180:183], v[212:215], v[66:69]
	v_mfma_f32_16x16x32_bf16 v[70:73], v[172:175], v[212:215], v[70:73]
	s_setprio 0
	s_branch .Lzb_3_0
.Lzf_3_1:
	s_barrier
	s_setprio 3
	s_waitcnt lgkmcnt(0)
	v_mfma_f32_16x16x32_bf16 v[62:65], v[148:151], v[184:187], 0
	v_mfma_f32_16x16x32_bf16 v[58:61], v[160:163], v[184:187], 0
	v_mfma_f32_16x16x32_bf16 v[42:45], v[160:163], v[192:195], 0
	v_mfma_f32_16x16x32_bf16 v[46:49], v[148:151], v[192:195], 0
	v_mfma_f32_16x16x32_bf16 v[30:33], v[148:151], v[200:203], 0
	v_mfma_f32_16x16x32_bf16 v[26:29], v[160:163], v[200:203], 0
	v_mfma_f32_16x16x32_bf16 v[10:13], v[160:163], v[208:211], 0
	v_mfma_f32_16x16x32_bf16 v[14:17], v[148:151], v[208:211], 0
	v_mfma_f32_16x16x32_bf16 v[62:65], v[152:155], v[188:191], v[62:65]
	v_mfma_f32_16x16x32_bf16 v[58:61], v[164:167], v[188:191], v[58:61]
	v_mfma_f32_16x16x32_bf16 v[42:45], v[164:167], v[196:199], v[42:45]
	v_mfma_f32_16x16x32_bf16 v[46:49], v[152:155], v[196:199], v[46:49]
	v_mfma_f32_16x16x32_bf16 v[30:33], v[152:155], v[204:207], v[30:33]
	v_mfma_f32_16x16x32_bf16 v[26:29], v[164:167], v[204:207], v[26:29]
	v_mfma_f32_16x16x32_bf16 v[10:13], v[164:167], v[212:215], v[10:13]
	v_mfma_f32_16x16x32_bf16 v[14:17], v[152:155], v[212:215], v[14:17]
	s_setprio 0
	s_setprio 3
	v_mfma_f32_16x16x32_bf16 v[54:57], v[168:171], v[184:187], 0
	v_mfma_f32_16x16x32_bf16 v[50:53], v[176:179], v[184:187], 0
	v_mfma_f32_16x16x32_bf16 v[34:37], v[176:179], v[192:195], 0
	v_mfma_f32_16x16x32_bf16 v[38:41], v[168:171], v[192:195], 0
	v_mfma_f32_16x16x32_bf16 v[22:25], v[168:171], v[200:203], 0
	v_mfma_f32_16x16x32_bf16 v[18:21], v[176:179], v[200:203], 0
	v_mfma_f32_16x16x32_bf16 v[2:5], v[176:179], v[208:211], 0
	v_mfma_f32_16x16x32_bf16 v[6:9], v[168:171], v[208:211], 0
	v_mfma_f32_16x16x32_bf16 v[54:57], v[172:175], v[188:191], v[54:57]
	v_mfma_f32_16x16x32_bf16 v[50:53], v[180:183], v[188:191], v[50:53]
	v_mfma_f32_16x16x32_bf16 v[34:37], v[180:183], v[196:199], v[34:37]
	v_mfma_f32_16x16x32_bf16 v[38:41], v[172:175], v[196:199], v[38:41]
	v_mfma_f32_16x16x32_bf16 v[22:25], v[172:175], v[204:207], v[22:25]
	v_mfma_f32_16x16x32_bf16 v[18:21], v[180:183], v[204:207], v[18:21]
	v_mfma_f32_16x16x32_bf16 v[2:5], v[180:183], v[212:215], v[2:5]
	v_mfma_f32_16x16x32_bf16 v[6:9], v[172:175], v[212:215], v[6:9]
	s_setprio 0
	s_branch .Lzb_3_1

.LBB0_609:
	s_add_u32 s41, s50, 0x8000
	s_addc_u32 s43, s51, 0
	s_mov_b32 s68, -2
.LBB0_610:
	ds_read_b128 v[148:151], v163
	ds_read_b128 v[152:155], v163 offset:1024
	ds_read_b128 v[156:159], v163 offset:2048
	ds_read_b128 v[166:169], v163 offset:3072
	ds_read_b128 v[170:173], v164
	ds_read_b128 v[174:177], v164 offset:1024
	ds_read_b128 v[178:181], v164 offset:2048
	ds_read_b128 v[182:185], v164 offset:3072
	s_add_u32 s6, s0, 0x100
	s_addc_u32 s7, s1, 0
	s_cmp_eq_u32 s68, 28
	s_cselect_b32 s53, s45, s7
	s_cselect_b32 s52, s44, s6
	s_cselect_b32 s51, s47, s43
	s_cselect_b32 s50, s46, s41
	v_lshl_add_u64 v[160:161], s[0:1], 0, v[138:139]
	s_add_i32 m0, s49, 0xc000
	ds_read_b128 v[186:189], v165
	ds_read_b128 v[190:193], v165 offset:1024
	ds_read_b128 v[194:197], v165 offset:2048
	ds_read_b128 v[198:201], v165 offset:3072
	ds_read_b128 v[202:205], v165 offset:4096
	ds_read_b128 v[206:209], v165 offset:5120
	ds_read_b128 v[210:213], v165 offset:6144
	ds_read_b128 v[214:217], v165 offset:7168
	global_load_lds_dwordx4 v[160:161], off
	v_lshl_add_u64 v[160:161], s[0:1], 0, v[140:141]
	s_add_i32 m0, s49, 0xe000
	s_nop 0
	global_load_lds_dwordx4 v[160:161], off
	s_waitcnt vmcnt(8)
	s_waitcnt lgkmcnt(0)
	s_cmp_eq_i32 s68, -2
	s_cbranch_scc1 .Lzf_4_0
	s_barrier
	s_setprio 3
	s_waitcnt lgkmcnt(0)
	v_mfma_i32_16x16x64_i8 v[126:129], v[148:151], v[186:189], v[126:129]
	v_mfma_i32_16x16x64_i8 v[122:125], v[156:159], v[186:189], v[122:125]
	v_mfma_i32_16x16x64_i8 v[114:117], v[156:159], v[194:197], v[114:117]
	v_mfma_i32_16x16x64_i8 v[118:121], v[148:151], v[194:197], v[118:121]
	v_mfma_i32_16x16x64_i8 v[110:113], v[148:151], v[202:205], v[110:113]
	v_mfma_i32_16x16x64_i8 v[106:109], v[156:159], v[202:205], v[106:109]
	v_mfma_i32_16x16x64_i8 v[98:101], v[156:159], v[210:213], v[98:101]
	v_mfma_i32_16x16x64_i8 v[102:105], v[148:151], v[210:213], v[102:105]
	v_mfma_i32_16x16x64_i8 v[126:129], v[152:155], v[190:193], v[126:129]
	v_mfma_i32_16x16x64_i8 v[122:125], v[166:169], v[190:193], v[122:125]
	v_mfma_i32_16x16x64_i8 v[114:117], v[166:169], v[198:201], v[114:117]
	v_mfma_i32_16x16x64_i8 v[118:121], v[152:155], v[198:201], v[118:121]
	v_mfma_i32_16x16x64_i8 v[110:113], v[152:155], v[206:209], v[110:113]
	v_mfma_i32_16x16x64_i8 v[106:109], v[166:169], v[206:209], v[106:109]
	v_mfma_i32_16x16x64_i8 v[98:101], v[166:169], v[214:217], v[98:101]
	v_mfma_i32_16x16x64_i8 v[102:105], v[152:155], v[214:217], v[102:105]
	s_setprio 0
	s_setprio 3
	v_mfma_i32_16x16x64_i8 v[62:65], v[170:173], v[186:189], v[62:65]
	v_mfma_i32_16x16x64_i8 v[58:61], v[178:181], v[186:189], v[58:61]
	v_mfma_i32_16x16x64_i8 v[50:53], v[178:181], v[194:197], v[50:53]
	v_mfma_i32_16x16x64_i8 v[54:57], v[170:173], v[194:197], v[54:57]
	v_mfma_i32_16x16x64_i8 v[46:49], v[170:173], v[202:205], v[46:49]
	v_mfma_i32_16x16x64_i8 v[42:45], v[178:181], v[202:205], v[42:45]
	v_mfma_i32_16x16x64_i8 v[34:37], v[178:181], v[210:213], v[34:37]
	v_mfma_i32_16x16x64_i8 v[38:41], v[170:173], v[210:213], v[38:41]
	v_mfma_i32_16x16x64_i8 v[62:65], v[174:177], v[190:193], v[62:65]
	v_mfma_i32_16x16x64_i8 v[58:61], v[182:185], v[190:193], v[58:61]
	v_mfma_i32_16x16x64_i8 v[50:53], v[182:185], v[198:201], v[50:53]
	v_mfma_i32_16x16x64_i8 v[54:57], v[174:177], v[198:201], v[54:57]
	v_mfma_i32_16x16x64_i8 v[46:49], v[174:177], v[206:209], v[46:49]
	v_mfma_i32_16x16x64_i8 v[42:45], v[182:185], v[206:209], v[42:45]
	v_mfma_i32_16x16x64_i8 v[34:37], v[182:185], v[214:217], v[34:37]
	v_mfma_i32_16x16x64_i8 v[38:41], v[174:177], v[214:217], v[38:41]
	s_setprio 0
.Lzb_4_0:
	s_barrier
	s_add_i32 s0, s63, s55
	v_lshl_add_u64 v[160:161], s[50:51], 0, v[130:131]
	s_mov_b32 m0, s0
	ds_read_b128 v[186:189], v165 offset:16384
	ds_read_b128 v[190:193], v165 offset:17408
	ds_read_b128 v[194:197], v165 offset:18432
	ds_read_b128 v[198:201], v165 offset:19456
	ds_read_b128 v[202:205], v165 offset:20480
	ds_read_b128 v[206:209], v165 offset:21504
	ds_read_b128 v[210:213], v165 offset:22528
	ds_read_b128 v[214:217], v165 offset:23552
	global_load_lds_dwordx4 v[160:161], off
	s_add_i32 m0, s0, 0x2000
	s_add_u32 s0, s50, 0x80000
	v_lshl_add_u64 v[160:161], s[50:51], 0, v[134:135]
	s_addc_u32 s1, s51, 0
	s_add_i32 s69, s64, s55
	global_load_lds_dwordx4 v[160:161], off
	v_lshl_add_u64 v[160:161], s[0:1], 0, v[130:131]
	s_mov_b32 m0, s69
	v_lshl_add_u64 v[218:219], s[52:53], 0, v[136:137]
	global_load_lds_dwordx4 v[160:161], off
	v_lshl_add_u64 v[160:161], s[0:1], 0, v[134:135]
	s_add_i32 m0, s69, 0x2000
	s_nop 0
	global_load_lds_dwordx4 v[160:161], off
	v_lshl_add_u64 v[160:161], s[52:53], 0, v[132:133]
	s_mov_b32 m0, s49
	s_nop 0
	global_load_lds_dwordx4 v[160:161], off
	s_mov_b32 m0, s56
	s_nop 0
	global_load_lds_dwordx4 v[218:219], off
	s_waitcnt vmcnt(8)
	s_waitcnt lgkmcnt(0)
	s_cmp_eq_i32 s68, -2
	s_cbranch_scc1 .Lzf_4_1
	s_barrier
	s_setprio 3
	s_waitcnt lgkmcnt(0)
	v_mfma_i32_16x16x64_i8 v[94:97], v[148:151], v[186:189], v[94:97]
	v_mfma_i32_16x16x64_i8 v[90:93], v[156:159], v[186:189], v[90:93]
	v_mfma_i32_16x16x64_i8 v[82:85], v[156:159], v[194:197], v[82:85]
	v_mfma_i32_16x16x64_i8 v[86:89], v[148:151], v[194:197], v[86:89]
	v_mfma_i32_16x16x64_i8 v[78:81], v[148:151], v[202:205], v[78:81]
	v_mfma_i32_16x16x64_i8 v[74:77], v[156:159], v[202:205], v[74:77]
	v_mfma_i32_16x16x64_i8 v[66:69], v[156:159], v[210:213], v[66:69]
	v_mfma_i32_16x16x64_i8 v[70:73], v[148:151], v[210:213], v[70:73]
	v_mfma_i32_16x16x64_i8 v[94:97], v[152:155], v[190:193], v[94:97]
	v_mfma_i32_16x16x64_i8 v[90:93], v[166:169], v[190:193], v[90:93]
	v_mfma_i32_16x16x64_i8 v[82:85], v[166:169], v[198:201], v[82:85]
	v_mfma_i32_16x16x64_i8 v[86:89], v[152:155], v[198:201], v[86:89]
	v_mfma_i32_16x16x64_i8 v[78:81], v[152:155], v[206:209], v[78:81]
	v_mfma_i32_16x16x64_i8 v[74:77], v[166:169], v[206:209], v[74:77]
	v_mfma_i32_16x16x64_i8 v[66:69], v[166:169], v[214:217], v[66:69]
	v_mfma_i32_16x16x64_i8 v[70:73], v[152:155], v[214:217], v[70:73]
	s_setprio 0
	s_setprio 3
	v_mfma_i32_16x16x64_i8 v[30:33], v[170:173], v[186:189], v[30:33]
	v_mfma_i32_16x16x64_i8 v[26:29], v[178:181], v[186:189], v[26:29]
	v_mfma_i32_16x16x64_i8 v[18:21], v[178:181], v[194:197], v[18:21]
	v_mfma_i32_16x16x64_i8 v[22:25], v[170:173], v[194:197], v[22:25]
	v_mfma_i32_16x16x64_i8 v[14:17], v[170:173], v[202:205], v[14:17]
	v_mfma_i32_16x16x64_i8 v[10:13], v[178:181], v[202:205], v[10:13]
	v_mfma_i32_16x16x64_i8 v[2:5], v[178:181], v[210:213], v[2:5]
	v_mfma_i32_16x16x64_i8 v[6:9], v[170:173], v[210:213], v[6:9]
	v_mfma_i32_16x16x64_i8 v[30:33], v[174:177], v[190:193], v[30:33]
	v_mfma_i32_16x16x64_i8 v[26:29], v[182:185], v[190:193], v[26:29]
	v_mfma_i32_16x16x64_i8 v[18:21], v[182:185], v[198:201], v[18:21]
	v_mfma_i32_16x16x64_i8 v[22:25], v[174:177], v[198:201], v[22:25]
	v_mfma_i32_16x16x64_i8 v[14:17], v[174:177], v[206:209], v[14:17]
	v_mfma_i32_16x16x64_i8 v[10:13], v[182:185], v[206:209], v[10:13]
	v_mfma_i32_16x16x64_i8 v[2:5], v[182:185], v[214:217], v[2:5]
	v_mfma_i32_16x16x64_i8 v[6:9], v[174:177], v[214:217], v[6:9]
	s_setprio 0
.Lzb_4_1:
	s_barrier
	s_add_i32 s69, 0, 0x18000
	s_add_i32 s70, 0, 0x1c000
	v_add_u32_e32 v166, s69, v147
	v_add_u32_e32 v182, s70, v147
	ds_read_b128 v[148:151], v166
	ds_read_b128 v[152:155], v166 offset:1024
	ds_read_b128 v[156:159], v166 offset:2048
	ds_read_b128 v[166:169], v166 offset:3072
	ds_read_b128 v[170:173], v182
	ds_read_b128 v[174:177], v182 offset:1024
	ds_read_b128 v[178:181], v182 offset:2048
	ds_read_b128 v[182:185], v182 offset:3072
	s_add_u32 s0, s52, 0x80000
	s_addc_u32 s1, s53, 0
	s_mov_b32 m0, s57
	v_lshl_add_u64 v[220:221], s[0:1], 0, v[132:133]
	ds_read_b128 v[186:189], v165 offset:32768
	ds_read_b128 v[190:193], v165 offset:33792
	ds_read_b128 v[194:197], v165 offset:34816
	ds_read_b128 v[198:201], v165 offset:35840
	ds_read_b128 v[202:205], v165 offset:36864
	ds_read_b128 v[206:209], v165 offset:37888
	ds_read_b128 v[210:213], v165 offset:38912
	ds_read_b128 v[214:217], v165 offset:39936
	global_load_lds_dwordx4 v[220:221], off
	v_lshl_add_u64 v[220:221], s[0:1], 0, v[136:137]
	s_mov_b32 m0, s58
	s_nop 0
	global_load_lds_dwordx4 v[220:221], off
	s_waitcnt vmcnt(8)
	s_waitcnt lgkmcnt(0)
	s_barrier
	s_setprio 3
	s_waitcnt lgkmcnt(0)
	v_mfma_i32_16x16x64_i8 v[126:129], v[148:151], v[186:189], v[126:129]
	v_mfma_i32_16x16x64_i8 v[122:125], v[156:159], v[186:189], v[122:125]
	v_mfma_i32_16x16x64_i8 v[114:117], v[156:159], v[194:197], v[114:117]
	v_mfma_i32_16x16x64_i8 v[118:121], v[148:151], v[194:197], v[118:121]
	v_mfma_i32_16x16x64_i8 v[110:113], v[148:151], v[202:205], v[110:113]
	v_mfma_i32_16x16x64_i8 v[106:109], v[156:159], v[202:205], v[106:109]
	v_mfma_i32_16x16x64_i8 v[98:101], v[156:159], v[210:213], v[98:101]
	v_mfma_i32_16x16x64_i8 v[102:105], v[148:151], v[210:213], v[102:105]
	v_mfma_i32_16x16x64_i8 v[126:129], v[152:155], v[190:193], v[126:129]
	v_mfma_i32_16x16x64_i8 v[122:125], v[166:169], v[190:193], v[122:125]
	v_mfma_i32_16x16x64_i8 v[114:117], v[166:169], v[198:201], v[114:117]
	v_mfma_i32_16x16x64_i8 v[118:121], v[152:155], v[198:201], v[118:121]
	v_mfma_i32_16x16x64_i8 v[110:113], v[152:155], v[206:209], v[110:113]
	v_mfma_i32_16x16x64_i8 v[106:109], v[166:169], v[206:209], v[106:109]
	v_mfma_i32_16x16x64_i8 v[98:101], v[166:169], v[214:217], v[98:101]
	v_mfma_i32_16x16x64_i8 v[102:105], v[152:155], v[214:217], v[102:105]
	s_setprio 0
	s_setprio 3
	v_mfma_i32_16x16x64_i8 v[62:65], v[170:173], v[186:189], v[62:65]
	v_mfma_i32_16x16x64_i8 v[58:61], v[178:181], v[186:189], v[58:61]
	v_mfma_i32_16x16x64_i8 v[50:53], v[178:181], v[194:197], v[50:53]
	v_mfma_i32_16x16x64_i8 v[54:57], v[170:173], v[194:197], v[54:57]
	v_mfma_i32_16x16x64_i8 v[46:49], v[170:173], v[202:205], v[46:49]
	v_mfma_i32_16x16x64_i8 v[42:45], v[178:181], v[202:205], v[42:45]
	v_mfma_i32_16x16x64_i8 v[34:37], v[178:181], v[210:213], v[34:37]
	v_mfma_i32_16x16x64_i8 v[38:41], v[170:173], v[210:213], v[38:41]
	v_mfma_i32_16x16x64_i8 v[62:65], v[174:177], v[190:193], v[62:65]
	v_mfma_i32_16x16x64_i8 v[58:61], v[182:185], v[190:193], v[58:61]
	v_mfma_i32_16x16x64_i8 v[50:53], v[182:185], v[198:201], v[50:53]
	v_mfma_i32_16x16x64_i8 v[54:57], v[174:177], v[198:201], v[54:57]
	v_mfma_i32_16x16x64_i8 v[46:49], v[174:177], v[206:209], v[46:49]
	v_mfma_i32_16x16x64_i8 v[42:45], v[182:185], v[206:209], v[42:45]
	v_mfma_i32_16x16x64_i8 v[34:37], v[182:185], v[214:217], v[34:37]
	v_mfma_i32_16x16x64_i8 v[38:41], v[174:177], v[214:217], v[38:41]
	s_setprio 0
	s_barrier
	s_add_u32 s0, s50, 0x4000
	s_addc_u32 s1, s51, 0
	s_add_i32 s52, s69, s55
	v_lshl_add_u64 v[220:221], s[0:1], 0, v[130:131]
	s_mov_b32 m0, s52
	ds_read_b128 v[186:189], v165 offset:49152
	ds_read_b128 v[190:193], v165 offset:50176
	ds_read_b128 v[194:197], v165 offset:51200
	ds_read_b128 v[198:201], v165 offset:52224
	ds_read_b128 v[202:205], v165 offset:53248
	ds_read_b128 v[206:209], v165 offset:54272
	ds_read_b128 v[210:213], v165 offset:55296
	ds_read_b128 v[214:217], v165 offset:56320
	global_load_lds_dwordx4 v[220:221], off
	s_add_i32 m0, s52, 0x2000
	v_lshl_add_u64 v[220:221], s[0:1], 0, v[134:135]
	s_add_u32 s0, s50, 0x84000
	s_addc_u32 s1, s51, 0
	s_add_i32 s50, s70, s55
	global_load_lds_dwordx4 v[220:221], off
	v_lshl_add_u64 v[220:221], s[0:1], 0, v[130:131]
	s_mov_b32 m0, s50
	v_lshl_add_u64 v[160:161], v[160:161], 0, s[20:21]
	global_load_lds_dwordx4 v[220:221], off
	v_lshl_add_u64 v[220:221], s[0:1], 0, v[134:135]
	s_add_i32 m0, s50, 0x2000
	s_nop 0
	global_load_lds_dwordx4 v[220:221], off
	s_mov_b32 m0, s60
	s_nop 0
	global_load_lds_dwordx4 v[160:161], off
	v_lshl_add_u64 v[160:161], v[218:219], 0, s[20:21]
	s_mov_b32 m0, s61
	s_nop 0
	global_load_lds_dwordx4 v[160:161], off
	s_waitcnt vmcnt(8)
	s_waitcnt lgkmcnt(0)
	s_barrier
	s_setprio 3
	s_waitcnt lgkmcnt(0)
	v_mfma_i32_16x16x64_i8 v[94:97], v[148:151], v[186:189], v[94:97]
	v_mfma_i32_16x16x64_i8 v[90:93], v[156:159], v[186:189], v[90:93]
	v_mfma_i32_16x16x64_i8 v[82:85], v[156:159], v[194:197], v[82:85]
	v_mfma_i32_16x16x64_i8 v[86:89], v[148:151], v[194:197], v[86:89]
	v_mfma_i32_16x16x64_i8 v[78:81], v[148:151], v[202:205], v[78:81]
	v_mfma_i32_16x16x64_i8 v[74:77], v[156:159], v[202:205], v[74:77]
	v_mfma_i32_16x16x64_i8 v[66:69], v[156:159], v[210:213], v[66:69]
	v_mfma_i32_16x16x64_i8 v[70:73], v[148:151], v[210:213], v[70:73]
	v_mfma_i32_16x16x64_i8 v[94:97], v[152:155], v[190:193], v[94:97]
	v_mfma_i32_16x16x64_i8 v[90:93], v[166:169], v[190:193], v[90:93]
	v_mfma_i32_16x16x64_i8 v[82:85], v[166:169], v[198:201], v[82:85]
	v_mfma_i32_16x16x64_i8 v[86:89], v[152:155], v[198:201], v[86:89]
	v_mfma_i32_16x16x64_i8 v[78:81], v[152:155], v[206:209], v[78:81]
	v_mfma_i32_16x16x64_i8 v[74:77], v[166:169], v[206:209], v[74:77]
	v_mfma_i32_16x16x64_i8 v[66:69], v[166:169], v[214:217], v[66:69]
	v_mfma_i32_16x16x64_i8 v[70:73], v[152:155], v[214:217], v[70:73]
	s_setprio 0
	s_setprio 3
	v_mfma_i32_16x16x64_i8 v[30:33], v[170:173], v[186:189], v[30:33]
	v_mfma_i32_16x16x64_i8 v[26:29], v[178:181], v[186:189], v[26:29]
	v_mfma_i32_16x16x64_i8 v[18:21], v[178:181], v[194:197], v[18:21]
	v_mfma_i32_16x16x64_i8 v[22:25], v[170:173], v[194:197], v[22:25]
	v_mfma_i32_16x16x64_i8 v[14:17], v[170:173], v[202:205], v[14:17]
	v_mfma_i32_16x16x64_i8 v[10:13], v[178:181], v[202:205], v[10:13]
	v_mfma_i32_16x16x64_i8 v[2:5], v[178:181], v[210:213], v[2:5]
	v_mfma_i32_16x16x64_i8 v[6:9], v[170:173], v[210:213], v[6:9]
	v_mfma_i32_16x16x64_i8 v[30:33], v[174:177], v[190:193], v[30:33]
	v_mfma_i32_16x16x64_i8 v[26:29], v[182:185], v[190:193], v[26:29]
	v_mfma_i32_16x16x64_i8 v[18:21], v[182:185], v[198:201], v[18:21]
	v_mfma_i32_16x16x64_i8 v[22:25], v[174:177], v[198:201], v[22:25]
	v_mfma_i32_16x16x64_i8 v[14:17], v[174:177], v[206:209], v[14:17]
	v_mfma_i32_16x16x64_i8 v[10:13], v[182:185], v[206:209], v[10:13]
	v_mfma_i32_16x16x64_i8 v[2:5], v[182:185], v[214:217], v[2:5]
	v_mfma_i32_16x16x64_i8 v[6:9], v[174:177], v[214:217], v[6:9]
	s_setprio 0
	s_barrier
	s_add_i32 s68, s68, 2
	s_add_u32 s41, s41, 0x8000
	s_addc_u32 s43, s43, 0
	s_cmp_gt_u32 s68, 29
	s_mov_b64 s[0:1], s[6:7]
	s_cbranch_scc0 .LBB0_610
	s_and_b64 vcc, exec, s[24:25]
	s_cbranch_vccz .LBB0_613
	s_barrier

.Lzf_4_0:
	s_barrier
	s_setprio 3
	s_waitcnt lgkmcnt(0)
	v_mfma_i32_16x16x64_i8 v[126:129], v[148:151], v[186:189], 0
	v_mfma_i32_16x16x64_i8 v[122:125], v[156:159], v[186:189], 0
	v_mfma_i32_16x16x64_i8 v[114:117], v[156:159], v[194:197], 0
	v_mfma_i32_16x16x64_i8 v[118:121], v[148:151], v[194:197], 0
	v_mfma_i32_16x16x64_i8 v[110:113], v[148:151], v[202:205], 0
	v_mfma_i32_16x16x64_i8 v[106:109], v[156:159], v[202:205], 0
	v_mfma_i32_16x16x64_i8 v[98:101], v[156:159], v[210:213], 0
	v_mfma_i32_16x16x64_i8 v[102:105], v[148:151], v[210:213], 0
	v_mfma_i32_16x16x64_i8 v[126:129], v[152:155], v[190:193], v[126:129]
	v_mfma_i32_16x16x64_i8 v[122:125], v[166:169], v[190:193], v[122:125]
	v_mfma_i32_16x16x64_i8 v[114:117], v[166:169], v[198:201], v[114:117]
	v_mfma_i32_16x16x64_i8 v[118:121], v[152:155], v[198:201], v[118:121]
	v_mfma_i32_16x16x64_i8 v[110:113], v[152:155], v[206:209], v[110:113]
	v_mfma_i32_16x16x64_i8 v[106:109], v[166:169], v[206:209], v[106:109]
	v_mfma_i32_16x16x64_i8 v[98:101], v[166:169], v[214:217], v[98:101]
	v_mfma_i32_16x16x64_i8 v[102:105], v[152:155], v[214:217], v[102:105]
	s_setprio 0
	s_setprio 3
	v_mfma_i32_16x16x64_i8 v[62:65], v[170:173], v[186:189], 0
	v_mfma_i32_16x16x64_i8 v[58:61], v[178:181], v[186:189], 0
	v_mfma_i32_16x16x64_i8 v[50:53], v[178:181], v[194:197], 0
	v_mfma_i32_16x16x64_i8 v[54:57], v[170:173], v[194:197], 0
	v_mfma_i32_16x16x64_i8 v[46:49], v[170:173], v[202:205], 0
	v_mfma_i32_16x16x64_i8 v[42:45], v[178:181], v[202:205], 0
	v_mfma_i32_16x16x64_i8 v[34:37], v[178:181], v[210:213], 0
	v_mfma_i32_16x16x64_i8 v[38:41], v[170:173], v[210:213], 0
	v_mfma_i32_16x16x64_i8 v[62:65], v[174:177], v[190:193], v[62:65]
	v_mfma_i32_16x16x64_i8 v[58:61], v[182:185], v[190:193], v[58:61]
	v_mfma_i32_16x16x64_i8 v[50:53], v[182:185], v[198:201], v[50:53]
	v_mfma_i32_16x16x64_i8 v[54:57], v[174:177], v[198:201], v[54:57]
	v_mfma_i32_16x16x64_i8 v[46:49], v[174:177], v[206:209], v[46:49]
	v_mfma_i32_16x16x64_i8 v[42:45], v[182:185], v[206:209], v[42:45]
	v_mfma_i32_16x16x64_i8 v[34:37], v[182:185], v[214:217], v[34:37]
	v_mfma_i32_16x16x64_i8 v[38:41], v[174:177], v[214:217], v[38:41]
	s_setprio 0
	s_branch .Lzb_4_0
.Lzf_4_1:
	s_barrier
	s_setprio 3
	s_waitcnt lgkmcnt(0)
	v_mfma_i32_16x16x64_i8 v[94:97], v[148:151], v[186:189], 0
	v_mfma_i32_16x16x64_i8 v[90:93], v[156:159], v[186:189], 0
	v_mfma_i32_16x16x64_i8 v[82:85], v[156:159], v[194:197], 0
	v_mfma_i32_16x16x64_i8 v[86:89], v[148:151], v[194:197], 0
	v_mfma_i32_16x16x64_i8 v[78:81], v[148:151], v[202:205], 0
	v_mfma_i32_16x16x64_i8 v[74:77], v[156:159], v[202:205], 0
	v_mfma_i32_16x16x64_i8 v[66:69], v[156:159], v[210:213], 0
	v_mfma_i32_16x16x64_i8 v[70:73], v[148:151], v[210:213], 0
	v_mfma_i32_16x16x64_i8 v[94:97], v[152:155], v[190:193], v[94:97]
	v_mfma_i32_16x16x64_i8 v[90:93], v[166:169], v[190:193], v[90:93]
	v_mfma_i32_16x16x64_i8 v[82:85], v[166:169], v[198:201], v[82:85]
	v_mfma_i32_16x16x64_i8 v[86:89], v[152:155], v[198:201], v[86:89]
	v_mfma_i32_16x16x64_i8 v[78:81], v[152:155], v[206:209], v[78:81]
	v_mfma_i32_16x16x64_i8 v[74:77], v[166:169], v[206:209], v[74:77]
	v_mfma_i32_16x16x64_i8 v[66:69], v[166:169], v[214:217], v[66:69]
	v_mfma_i32_16x16x64_i8 v[70:73], v[152:155], v[214:217], v[70:73]
	s_setprio 0
	s_setprio 3
	v_mfma_i32_16x16x64_i8 v[30:33], v[170:173], v[186:189], 0
	v_mfma_i32_16x16x64_i8 v[26:29], v[178:181], v[186:189], 0
	v_mfma_i32_16x16x64_i8 v[18:21], v[178:181], v[194:197], 0
	v_mfma_i32_16x16x64_i8 v[22:25], v[170:173], v[194:197], 0
	v_mfma_i32_16x16x64_i8 v[14:17], v[170:173], v[202:205], 0
	v_mfma_i32_16x16x64_i8 v[10:13], v[178:181], v[202:205], 0
	v_mfma_i32_16x16x64_i8 v[2:5], v[178:181], v[210:213], 0
	v_mfma_i32_16x16x64_i8 v[6:9], v[170:173], v[210:213], 0
	v_mfma_i32_16x16x64_i8 v[30:33], v[174:177], v[190:193], v[30:33]
	v_mfma_i32_16x16x64_i8 v[26:29], v[182:185], v[190:193], v[26:29]
	v_mfma_i32_16x16x64_i8 v[18:21], v[182:185], v[198:201], v[18:21]
	v_mfma_i32_16x16x64_i8 v[22:25], v[174:177], v[198:201], v[22:25]
	v_mfma_i32_16x16x64_i8 v[14:17], v[174:177], v[206:209], v[14:17]
	v_mfma_i32_16x16x64_i8 v[10:13], v[182:185], v[206:209], v[10:13]
	v_mfma_i32_16x16x64_i8 v[2:5], v[182:185], v[214:217], v[2:5]
	v_mfma_i32_16x16x64_i8 v[6:9], v[174:177], v[214:217], v[6:9]
	s_setprio 0
	s_branch .Lzb_4_1

.LBB0_1270:
	s_add_u32 s45, s0, 0x8000
	s_addc_u32 s47, s1, 0
	s_add_u32 s0, s52, 0x100080
	s_addc_u32 s1, s53, 0
	s_mov_b32 s73, -2
.LBB0_1271:
	ds_read_b128 v[154:157], v151
	ds_read_b128 v[158:161], v151 offset:1024
	ds_read_b128 v[162:165], v151 offset:2048
	ds_read_b128 v[166:169], v151 offset:3072
	ds_read_b128 v[170:173], v152
	ds_read_b128 v[174:177], v152 offset:1024
	ds_read_b128 v[178:181], v152 offset:2048
	ds_read_b128 v[182:185], v152 offset:3072
	s_add_u32 s52, s0, 0xfff00080
	s_addc_u32 s53, s1, -1
	s_cmp_eq_u32 s73, 60
	s_cselect_b32 s55, s7, s53
	s_cselect_b32 s54, s6, s52
	s_cselect_b32 s53, s49, s47
	s_cselect_b32 s52, s48, s45
	v_lshl_add_u64 v[148:149], s[0:1], 0, v[138:139]
	s_add_i32 m0, s51, 0xc000
	ds_read_b128 v[186:189], v153
	ds_read_b128 v[190:193], v153 offset:1024
	ds_read_b128 v[194:197], v153 offset:2048
	ds_read_b128 v[198:201], v153 offset:3072
	ds_read_b128 v[202:205], v153 offset:4096
	ds_read_b128 v[206:209], v153 offset:5120
	ds_read_b128 v[210:213], v153 offset:6144
	ds_read_b128 v[214:217], v153 offset:7168
	global_load_lds_dwordx4 v[148:149], off
	v_lshl_add_u64 v[148:149], s[0:1], 0, v[140:141]
	s_add_i32 m0, s51, 0xe000
	s_nop 0
	global_load_lds_dwordx4 v[148:149], off
	s_waitcnt vmcnt(8)
	s_waitcnt lgkmcnt(0)
	s_cmp_eq_i32 s73, -2
	s_cbranch_scc1 .Lzf_7_0
	s_barrier
	s_setprio 3
	s_waitcnt lgkmcnt(0)
	v_mfma_f32_16x16x32_bf16 v[126:129], v[154:157], v[186:189], v[126:129]
	v_mfma_f32_16x16x32_bf16 v[122:125], v[162:165], v[186:189], v[122:125]
	v_mfma_f32_16x16x32_bf16 v[110:113], v[162:165], v[194:197], v[110:113]
	v_mfma_f32_16x16x32_bf16 v[118:121], v[154:157], v[194:197], v[118:121]
	v_mfma_f32_16x16x32_bf16 v[102:105], v[154:157], v[202:205], v[102:105]
	v_mfma_f32_16x16x32_bf16 v[94:97], v[162:165], v[202:205], v[94:97]
	v_mfma_f32_16x16x32_bf16 v[78:81], v[162:165], v[210:213], v[78:81]
	v_mfma_f32_16x16x32_bf16 v[86:89], v[154:157], v[210:213], v[86:89]
	v_mfma_f32_16x16x32_bf16 v[126:129], v[158:161], v[190:193], v[126:129]
	v_mfma_f32_16x16x32_bf16 v[122:125], v[166:169], v[190:193], v[122:125]
	v_mfma_f32_16x16x32_bf16 v[110:113], v[166:169], v[198:201], v[110:113]
	v_mfma_f32_16x16x32_bf16 v[118:121], v[158:161], v[198:201], v[118:121]
	v_mfma_f32_16x16x32_bf16 v[102:105], v[158:161], v[206:209], v[102:105]
	v_mfma_f32_16x16x32_bf16 v[94:97], v[166:169], v[206:209], v[94:97]
	v_mfma_f32_16x16x32_bf16 v[78:81], v[166:169], v[214:217], v[78:81]
	v_mfma_f32_16x16x32_bf16 v[86:89], v[158:161], v[214:217], v[86:89]
	s_setprio 0
	s_setprio 3
	v_mfma_f32_16x16x32_bf16 v[114:117], v[170:173], v[186:189], v[114:117]
	v_mfma_f32_16x16x32_bf16 v[106:109], v[178:181], v[186:189], v[106:109]
	v_mfma_f32_16x16x32_bf16 v[90:93], v[178:181], v[194:197], v[90:93]
	v_mfma_f32_16x16x32_bf16 v[98:101], v[170:173], v[194:197], v[98:101]
	v_mfma_f32_16x16x32_bf16 v[82:85], v[170:173], v[202:205], v[82:85]
	v_mfma_f32_16x16x32_bf16 v[74:77], v[178:181], v[202:205], v[74:77]
	v_mfma_f32_16x16x32_bf16 v[66:69], v[178:181], v[210:213], v[66:69]
	v_mfma_f32_16x16x32_bf16 v[70:73], v[170:173], v[210:213], v[70:73]
	v_mfma_f32_16x16x32_bf16 v[114:117], v[174:177], v[190:193], v[114:117]
	v_mfma_f32_16x16x32_bf16 v[106:109], v[182:185], v[190:193], v[106:109]
	v_mfma_f32_16x16x32_bf16 v[90:93], v[182:185], v[198:201], v[90:93]
	v_mfma_f32_16x16x32_bf16 v[98:101], v[174:177], v[198:201], v[98:101]
	v_mfma_f32_16x16x32_bf16 v[82:85], v[174:177], v[206:209], v[82:85]
	v_mfma_f32_16x16x32_bf16 v[74:77], v[182:185], v[206:209], v[74:77]
	v_mfma_f32_16x16x32_bf16 v[66:69], v[182:185], v[214:217], v[66:69]
	v_mfma_f32_16x16x32_bf16 v[70:73], v[174:177], v[214:217], v[70:73]
	s_setprio 0
.Lzb_7_0:
	s_barrier
	s_add_i32 s74, s66, s58
	v_lshl_add_u64 v[148:149], s[52:53], 0, v[130:131]
	s_mov_b32 m0, s74
	ds_read_b128 v[186:189], v153 offset:16384
	ds_read_b128 v[190:193], v153 offset:17408
	ds_read_b128 v[194:197], v153 offset:18432
	ds_read_b128 v[198:201], v153 offset:19456
	ds_read_b128 v[202:205], v153 offset:20480
	ds_read_b128 v[206:209], v153 offset:21504
	ds_read_b128 v[210:213], v153 offset:22528
	ds_read_b128 v[214:217], v153 offset:23552
	global_load_lds_dwordx4 v[148:149], off
	s_add_i32 m0, s74, 0x2000
	s_add_u32 s74, s52, 0x100000
	v_lshl_add_u64 v[148:149], s[52:53], 0, v[134:135]
	s_addc_u32 s75, s53, 0
	s_add_i32 s76, s67, s58
	global_load_lds_dwordx4 v[148:149], off
	v_lshl_add_u64 v[148:149], s[74:75], 0, v[130:131]
	s_mov_b32 m0, s76
	v_lshl_add_u64 v[218:219], s[54:55], 0, v[136:137]
	global_load_lds_dwordx4 v[148:149], off
	v_lshl_add_u64 v[148:149], s[74:75], 0, v[134:135]
	s_add_i32 m0, s76, 0x2000
	s_nop 0
	global_load_lds_dwordx4 v[148:149], off
	v_lshl_add_u64 v[148:149], s[54:55], 0, v[132:133]
	s_mov_b32 m0, s51
	s_nop 0
	global_load_lds_dwordx4 v[148:149], off
	s_mov_b32 m0, s59
	s_nop 0
	global_load_lds_dwordx4 v[218:219], off
	s_waitcnt vmcnt(8)
	s_waitcnt lgkmcnt(0)
	s_cmp_eq_i32 s73, -2
	s_cbranch_scc1 .Lzf_7_1
	s_barrier
	s_setprio 3
	s_waitcnt lgkmcnt(0)
	v_mfma_f32_16x16x32_bf16 v[62:65], v[154:157], v[186:189], v[62:65]
	v_mfma_f32_16x16x32_bf16 v[58:61], v[162:165], v[186:189], v[58:61]
	v_mfma_f32_16x16x32_bf16 v[46:49], v[162:165], v[194:197], v[46:49]
	v_mfma_f32_16x16x32_bf16 v[54:57], v[154:157], v[194:197], v[54:57]
	v_mfma_f32_16x16x32_bf16 v[38:41], v[154:157], v[202:205], v[38:41]
	v_mfma_f32_16x16x32_bf16 v[30:33], v[162:165], v[202:205], v[30:33]
	v_mfma_f32_16x16x32_bf16 v[14:17], v[162:165], v[210:213], v[14:17]
	v_mfma_f32_16x16x32_bf16 v[22:25], v[154:157], v[210:213], v[22:25]
	v_mfma_f32_16x16x32_bf16 v[62:65], v[158:161], v[190:193], v[62:65]
	v_mfma_f32_16x16x32_bf16 v[58:61], v[166:169], v[190:193], v[58:61]
	v_mfma_f32_16x16x32_bf16 v[46:49], v[166:169], v[198:201], v[46:49]
	v_mfma_f32_16x16x32_bf16 v[54:57], v[158:161], v[198:201], v[54:57]
	v_mfma_f32_16x16x32_bf16 v[38:41], v[158:161], v[206:209], v[38:41]
	v_mfma_f32_16x16x32_bf16 v[30:33], v[166:169], v[206:209], v[30:33]
	v_mfma_f32_16x16x32_bf16 v[14:17], v[166:169], v[214:217], v[14:17]
	v_mfma_f32_16x16x32_bf16 v[22:25], v[158:161], v[214:217], v[22:25]
	s_setprio 0
	s_setprio 3
	v_mfma_f32_16x16x32_bf16 v[50:53], v[170:173], v[186:189], v[50:53]
	v_mfma_f32_16x16x32_bf16 v[42:45], v[178:181], v[186:189], v[42:45]
	v_mfma_f32_16x16x32_bf16 v[26:29], v[178:181], v[194:197], v[26:29]
	v_mfma_f32_16x16x32_bf16 v[34:37], v[170:173], v[194:197], v[34:37]
	v_mfma_f32_16x16x32_bf16 v[18:21], v[170:173], v[202:205], v[18:21]
	v_mfma_f32_16x16x32_bf16 v[10:13], v[178:181], v[202:205], v[10:13]
	v_mfma_f32_16x16x32_bf16 v[2:5], v[178:181], v[210:213], v[2:5]
	v_mfma_f32_16x16x32_bf16 v[6:9], v[170:173], v[210:213], v[6:9]
	v_mfma_f32_16x16x32_bf16 v[50:53], v[174:177], v[190:193], v[50:53]
	v_mfma_f32_16x16x32_bf16 v[42:45], v[182:185], v[190:193], v[42:45]
	v_mfma_f32_16x16x32_bf16 v[26:29], v[182:185], v[198:201], v[26:29]
	v_mfma_f32_16x16x32_bf16 v[34:37], v[174:177], v[198:201], v[34:37]
	v_mfma_f32_16x16x32_bf16 v[18:21], v[174:177], v[206:209], v[18:21]
	v_mfma_f32_16x16x32_bf16 v[10:13], v[182:185], v[206:209], v[10:13]
	v_mfma_f32_16x16x32_bf16 v[2:5], v[182:185], v[214:217], v[2:5]
	v_mfma_f32_16x16x32_bf16 v[6:9], v[174:177], v[214:217], v[6:9]
	s_setprio 0
.Lzb_7_1:
	s_barrier
	s_add_i32 s74, 0, 0x18000
	s_add_i32 s75, 0, 0x1c000
	v_add_u32_e32 v166, s74, v147
	v_add_u32_e32 v182, s75, v147
	ds_read_b128 v[154:157], v166
	ds_read_b128 v[158:161], v166 offset:1024
	ds_read_b128 v[162:165], v166 offset:2048
	ds_read_b128 v[166:169], v166 offset:3072
	ds_read_b128 v[170:173], v182
	ds_read_b128 v[174:177], v182 offset:1024
	ds_read_b128 v[178:181], v182 offset:2048
	ds_read_b128 v[182:185], v182 offset:3072
	s_add_u32 s54, s54, 0x100000
	s_addc_u32 s55, s55, 0
	s_mov_b32 m0, s60
	v_lshl_add_u64 v[220:221], s[54:55], 0, v[132:133]
	ds_read_b128 v[186:189], v153 offset:32768
	ds_read_b128 v[190:193], v153 offset:33792
	ds_read_b128 v[194:197], v153 offset:34816
	ds_read_b128 v[198:201], v153 offset:35840
	ds_read_b128 v[202:205], v153 offset:36864
	ds_read_b128 v[206:209], v153 offset:37888
	ds_read_b128 v[210:213], v153 offset:38912
	ds_read_b128 v[214:217], v153 offset:39936
	global_load_lds_dwordx4 v[220:221], off
	v_lshl_add_u64 v[220:221], s[54:55], 0, v[136:137]
	s_mov_b32 m0, s61
	s_nop 0
	global_load_lds_dwordx4 v[220:221], off
	s_waitcnt vmcnt(8)
	s_waitcnt lgkmcnt(0)
	s_barrier
	s_setprio 3
	s_waitcnt lgkmcnt(0)
	v_mfma_f32_16x16x32_bf16 v[126:129], v[154:157], v[186:189], v[126:129]
	v_mfma_f32_16x16x32_bf16 v[122:125], v[162:165], v[186:189], v[122:125]
	v_mfma_f32_16x16x32_bf16 v[110:113], v[162:165], v[194:197], v[110:113]
	v_mfma_f32_16x16x32_bf16 v[118:121], v[154:157], v[194:197], v[118:121]
	v_mfma_f32_16x16x32_bf16 v[102:105], v[154:157], v[202:205], v[102:105]
	v_mfma_f32_16x16x32_bf16 v[94:97], v[162:165], v[202:205], v[94:97]
	v_mfma_f32_16x16x32_bf16 v[78:81], v[162:165], v[210:213], v[78:81]
	v_mfma_f32_16x16x32_bf16 v[86:89], v[154:157], v[210:213], v[86:89]
	v_mfma_f32_16x16x32_bf16 v[126:129], v[158:161], v[190:193], v[126:129]
	v_mfma_f32_16x16x32_bf16 v[122:125], v[166:169], v[190:193], v[122:125]
	v_mfma_f32_16x16x32_bf16 v[110:113], v[166:169], v[198:201], v[110:113]
	v_mfma_f32_16x16x32_bf16 v[118:121], v[158:161], v[198:201], v[118:121]
	v_mfma_f32_16x16x32_bf16 v[102:105], v[158:161], v[206:209], v[102:105]
	v_mfma_f32_16x16x32_bf16 v[94:97], v[166:169], v[206:209], v[94:97]
	v_mfma_f32_16x16x32_bf16 v[78:81], v[166:169], v[214:217], v[78:81]
	v_mfma_f32_16x16x32_bf16 v[86:89], v[158:161], v[214:217], v[86:89]
	s_setprio 0
	s_setprio 3
	v_mfma_f32_16x16x32_bf16 v[114:117], v[170:173], v[186:189], v[114:117]
	v_mfma_f32_16x16x32_bf16 v[106:109], v[178:181], v[186:189], v[106:109]
	v_mfma_f32_16x16x32_bf16 v[90:93], v[178:181], v[194:197], v[90:93]
	v_mfma_f32_16x16x32_bf16 v[98:101], v[170:173], v[194:197], v[98:101]
	v_mfma_f32_16x16x32_bf16 v[82:85], v[170:173], v[202:205], v[82:85]
	v_mfma_f32_16x16x32_bf16 v[74:77], v[178:181], v[202:205], v[74:77]
	v_mfma_f32_16x16x32_bf16 v[66:69], v[178:181], v[210:213], v[66:69]
	v_mfma_f32_16x16x32_bf16 v[70:73], v[170:173], v[210:213], v[70:73]
	v_mfma_f32_16x16x32_bf16 v[114:117], v[174:177], v[190:193], v[114:117]
	v_mfma_f32_16x16x32_bf16 v[106:109], v[182:185], v[190:193], v[106:109]
	v_mfma_f32_16x16x32_bf16 v[90:93], v[182:185], v[198:201], v[90:93]
	v_mfma_f32_16x16x32_bf16 v[98:101], v[174:177], v[198:201], v[98:101]
	v_mfma_f32_16x16x32_bf16 v[82:85], v[174:177], v[206:209], v[82:85]
	v_mfma_f32_16x16x32_bf16 v[74:77], v[182:185], v[206:209], v[74:77]
	v_mfma_f32_16x16x32_bf16 v[66:69], v[182:185], v[214:217], v[66:69]
	v_mfma_f32_16x16x32_bf16 v[70:73], v[174:177], v[214:217], v[70:73]
	s_setprio 0
	s_barrier
	s_add_u32 s54, s52, 0x4000
	s_addc_u32 s55, s53, 0
	s_add_i32 s74, s74, s58
	v_lshl_add_u64 v[220:221], s[54:55], 0, v[130:131]
	s_mov_b32 m0, s74
	ds_read_b128 v[186:189], v153 offset:49152
	ds_read_b128 v[190:193], v153 offset:50176
	ds_read_b128 v[194:197], v153 offset:51200
	ds_read_b128 v[198:201], v153 offset:52224
	ds_read_b128 v[202:205], v153 offset:53248
	ds_read_b128 v[206:209], v153 offset:54272
	ds_read_b128 v[210:213], v153 offset:55296
	ds_read_b128 v[214:217], v153 offset:56320
	global_load_lds_dwordx4 v[220:221], off
	s_add_i32 m0, s74, 0x2000
	s_add_u32 s52, s52, 0x104000
	v_lshl_add_u64 v[220:221], s[54:55], 0, v[134:135]
	s_addc_u32 s53, s53, 0
	s_add_i32 s54, s75, s58
	global_load_lds_dwordx4 v[220:221], off
	v_lshl_add_u64 v[220:221], s[52:53], 0, v[130:131]
	s_mov_b32 m0, s54
	v_lshl_add_u64 v[148:149], v[148:149], 0, s[18:19]
	global_load_lds_dwordx4 v[220:221], off
	v_lshl_add_u64 v[220:221], s[52:53], 0, v[134:135]
	s_add_i32 m0, s54, 0x2000
	s_nop 0
	global_load_lds_dwordx4 v[220:221], off
	s_mov_b32 m0, s63
	s_nop 0
	global_load_lds_dwordx4 v[148:149], off
	v_lshl_add_u64 v[148:149], v[218:219], 0, s[18:19]
	s_mov_b32 m0, s64
	s_nop 0
	global_load_lds_dwordx4 v[148:149], off
	s_waitcnt vmcnt(8)
	s_waitcnt lgkmcnt(0)
	s_barrier
	s_setprio 3
	s_waitcnt lgkmcnt(0)
	v_mfma_f32_16x16x32_bf16 v[62:65], v[154:157], v[186:189], v[62:65]
	v_mfma_f32_16x16x32_bf16 v[58:61], v[162:165], v[186:189], v[58:61]
	v_mfma_f32_16x16x32_bf16 v[46:49], v[162:165], v[194:197], v[46:49]
	v_mfma_f32_16x16x32_bf16 v[54:57], v[154:157], v[194:197], v[54:57]
	v_mfma_f32_16x16x32_bf16 v[38:41], v[154:157], v[202:205], v[38:41]
	v_mfma_f32_16x16x32_bf16 v[30:33], v[162:165], v[202:205], v[30:33]
	v_mfma_f32_16x16x32_bf16 v[14:17], v[162:165], v[210:213], v[14:17]
	v_mfma_f32_16x16x32_bf16 v[22:25], v[154:157], v[210:213], v[22:25]
	v_mfma_f32_16x16x32_bf16 v[62:65], v[158:161], v[190:193], v[62:65]
	v_mfma_f32_16x16x32_bf16 v[58:61], v[166:169], v[190:193], v[58:61]
	v_mfma_f32_16x16x32_bf16 v[46:49], v[166:169], v[198:201], v[46:49]
	v_mfma_f32_16x16x32_bf16 v[54:57], v[158:161], v[198:201], v[54:57]
	v_mfma_f32_16x16x32_bf16 v[38:41], v[158:161], v[206:209], v[38:41]
	v_mfma_f32_16x16x32_bf16 v[30:33], v[166:169], v[206:209], v[30:33]
	v_mfma_f32_16x16x32_bf16 v[14:17], v[166:169], v[214:217], v[14:17]
	v_mfma_f32_16x16x32_bf16 v[22:25], v[158:161], v[214:217], v[22:25]
	s_setprio 0
	s_setprio 3
	v_mfma_f32_16x16x32_bf16 v[50:53], v[170:173], v[186:189], v[50:53]
	v_mfma_f32_16x16x32_bf16 v[42:45], v[178:181], v[186:189], v[42:45]
	v_mfma_f32_16x16x32_bf16 v[26:29], v[178:181], v[194:197], v[26:29]
	v_mfma_f32_16x16x32_bf16 v[34:37], v[170:173], v[194:197], v[34:37]
	v_mfma_f32_16x16x32_bf16 v[18:21], v[170:173], v[202:205], v[18:21]
	v_mfma_f32_16x16x32_bf16 v[10:13], v[178:181], v[202:205], v[10:13]
	v_mfma_f32_16x16x32_bf16 v[2:5], v[178:181], v[210:213], v[2:5]
	v_mfma_f32_16x16x32_bf16 v[6:9], v[170:173], v[210:213], v[6:9]
	v_mfma_f32_16x16x32_bf16 v[50:53], v[174:177], v[190:193], v[50:53]
	v_mfma_f32_16x16x32_bf16 v[42:45], v[182:185], v[190:193], v[42:45]
	v_mfma_f32_16x16x32_bf16 v[26:29], v[182:185], v[198:201], v[26:29]
	v_mfma_f32_16x16x32_bf16 v[34:37], v[174:177], v[198:201], v[34:37]
	v_mfma_f32_16x16x32_bf16 v[18:21], v[174:177], v[206:209], v[18:21]
	v_mfma_f32_16x16x32_bf16 v[10:13], v[182:185], v[206:209], v[10:13]
	v_mfma_f32_16x16x32_bf16 v[2:5], v[182:185], v[214:217], v[2:5]
	v_mfma_f32_16x16x32_bf16 v[6:9], v[174:177], v[214:217], v[6:9]
	s_setprio 0
	s_barrier
	s_add_i32 s73, s73, 2
	s_add_u32 s45, s45, 0x8000
	s_addc_u32 s47, s47, 0
	s_add_u32 s0, s0, 0x100
	s_addc_u32 s1, s1, 0
	s_cmp_gt_u32 s73, 61
	s_cbranch_scc0 .LBB0_1271
	s_and_b64 vcc, exec, s[20:21]
	s_cbranch_vccz .LBB0_1274
	s_barrier

.Lzf_7_0:
	s_barrier
	s_setprio 3
	s_waitcnt lgkmcnt(0)
	v_mfma_f32_16x16x32_bf16 v[126:129], v[154:157], v[186:189], 0
	v_mfma_f32_16x16x32_bf16 v[122:125], v[162:165], v[186:189], 0
	v_mfma_f32_16x16x32_bf16 v[110:113], v[162:165], v[194:197], 0
	v_mfma_f32_16x16x32_bf16 v[118:121], v[154:157], v[194:197], 0
	v_mfma_f32_16x16x32_bf16 v[102:105], v[154:157], v[202:205], 0
	v_mfma_f32_16x16x32_bf16 v[94:97], v[162:165], v[202:205], 0
	v_mfma_f32_16x16x32_bf16 v[78:81], v[162:165], v[210:213], 0
	v_mfma_f32_16x16x32_bf16 v[86:89], v[154:157], v[210:213], 0
	v_mfma_f32_16x16x32_bf16 v[126:129], v[158:161], v[190:193], v[126:129]
	v_mfma_f32_16x16x32_bf16 v[122:125], v[166:169], v[190:193], v[122:125]
	v_mfma_f32_16x16x32_bf16 v[110:113], v[166:169], v[198:201], v[110:113]
	v_mfma_f32_16x16x32_bf16 v[118:121], v[158:161], v[198:201], v[118:121]
	v_mfma_f32_16x16x32_bf16 v[102:105], v[158:161], v[206:209], v[102:105]
	v_mfma_f32_16x16x32_bf16 v[94:97], v[166:169], v[206:209], v[94:97]
	v_mfma_f32_16x16x32_bf16 v[78:81], v[166:169], v[214:217], v[78:81]
	v_mfma_f32_16x16x32_bf16 v[86:89], v[158:161], v[214:217], v[86:89]
	s_setprio 0
	s_setprio 3
	v_mfma_f32_16x16x32_bf16 v[114:117], v[170:173], v[186:189], 0
	v_mfma_f32_16x16x32_bf16 v[106:109], v[178:181], v[186:189], 0
	v_mfma_f32_16x16x32_bf16 v[90:93], v[178:181], v[194:197], 0
	v_mfma_f32_16x16x32_bf16 v[98:101], v[170:173], v[194:197], 0
	v_mfma_f32_16x16x32_bf16 v[82:85], v[170:173], v[202:205], 0
	v_mfma_f32_16x16x32_bf16 v[74:77], v[178:181], v[202:205], 0
	v_mfma_f32_16x16x32_bf16 v[66:69], v[178:181], v[210:213], 0
	v_mfma_f32_16x16x32_bf16 v[70:73], v[170:173], v[210:213], 0
	v_mfma_f32_16x16x32_bf16 v[114:117], v[174:177], v[190:193], v[114:117]
	v_mfma_f32_16x16x32_bf16 v[106:109], v[182:185], v[190:193], v[106:109]
	v_mfma_f32_16x16x32_bf16 v[90:93], v[182:185], v[198:201], v[90:93]
	v_mfma_f32_16x16x32_bf16 v[98:101], v[174:177], v[198:201], v[98:101]
	v_mfma_f32_16x16x32_bf16 v[82:85], v[174:177], v[206:209], v[82:85]
	v_mfma_f32_16x16x32_bf16 v[74:77], v[182:185], v[206:209], v[74:77]
	v_mfma_f32_16x16x32_bf16 v[66:69], v[182:185], v[214:217], v[66:69]
	v_mfma_f32_16x16x32_bf16 v[70:73], v[174:177], v[214:217], v[70:73]
	s_setprio 0
	s_branch .Lzb_7_0
.Lzf_7_1:
	s_barrier
	s_setprio 3
	s_waitcnt lgkmcnt(0)
	v_mfma_f32_16x16x32_bf16 v[62:65], v[154:157], v[186:189], 0
	v_mfma_f32_16x16x32_bf16 v[58:61], v[162:165], v[186:189], 0
	v_mfma_f32_16x16x32_bf16 v[46:49], v[162:165], v[194:197], 0
	v_mfma_f32_16x16x32_bf16 v[54:57], v[154:157], v[194:197], 0
	v_mfma_f32_16x16x32_bf16 v[38:41], v[154:157], v[202:205], 0
	v_mfma_f32_16x16x32_bf16 v[30:33], v[162:165], v[202:205], 0
	v_mfma_f32_16x16x32_bf16 v[14:17], v[162:165], v[210:213], 0
	v_mfma_f32_16x16x32_bf16 v[22:25], v[154:157], v[210:213], 0
	v_mfma_f32_16x16x32_bf16 v[62:65], v[158:161], v[190:193], v[62:65]
	v_mfma_f32_16x16x32_bf16 v[58:61], v[166:169], v[190:193], v[58:61]
	v_mfma_f32_16x16x32_bf16 v[46:49], v[166:169], v[198:201], v[46:49]
	v_mfma_f32_16x16x32_bf16 v[54:57], v[158:161], v[198:201], v[54:57]
	v_mfma_f32_16x16x32_bf16 v[38:41], v[158:161], v[206:209], v[38:41]
	v_mfma_f32_16x16x32_bf16 v[30:33], v[166:169], v[206:209], v[30:33]
	v_mfma_f32_16x16x32_bf16 v[14:17], v[166:169], v[214:217], v[14:17]
	v_mfma_f32_16x16x32_bf16 v[22:25], v[158:161], v[214:217], v[22:25]
	s_setprio 0
	s_setprio 3
	v_mfma_f32_16x16x32_bf16 v[50:53], v[170:173], v[186:189], 0
	v_mfma_f32_16x16x32_bf16 v[42:45], v[178:181], v[186:189], 0
	v_mfma_f32_16x16x32_bf16 v[26:29], v[178:181], v[194:197], 0
	v_mfma_f32_16x16x32_bf16 v[34:37], v[170:173], v[194:197], 0
	v_mfma_f32_16x16x32_bf16 v[18:21], v[170:173], v[202:205], 0
	v_mfma_f32_16x16x32_bf16 v[10:13], v[178:181], v[202:205], 0
	v_mfma_f32_16x16x32_bf16 v[2:5], v[178:181], v[210:213], 0
	v_mfma_f32_16x16x32_bf16 v[6:9], v[170:173], v[210:213], 0
	v_mfma_f32_16x16x32_bf16 v[50:53], v[174:177], v[190:193], v[50:53]
	v_mfma_f32_16x16x32_bf16 v[42:45], v[182:185], v[190:193], v[42:45]
	v_mfma_f32_16x16x32_bf16 v[26:29], v[182:185], v[198:201], v[26:29]
	v_mfma_f32_16x16x32_bf16 v[34:37], v[174:177], v[198:201], v[34:37]
	v_mfma_f32_16x16x32_bf16 v[18:21], v[174:177], v[206:209], v[18:21]
	v_mfma_f32_16x16x32_bf16 v[10:13], v[182:185], v[206:209], v[10:13]
	v_mfma_f32_16x16x32_bf16 v[2:5], v[182:185], v[214:217], v[2:5]
	v_mfma_f32_16x16x32_bf16 v[6:9], v[174:177], v[214:217], v[6:9]
	s_setprio 0
	s_branch .Lzb_7_1

.LBB0_1426:
	s_add_u32 s78, s10, 0x8000
	s_addc_u32 s79, s11, 0
	s_add_u32 s54, s16, 0x80080
	s_addc_u32 s55, s17, 0
	s_mov_b32 s80, -2
	s_mov_b64 s[10:11], s[58:59]
	s_mov_b64 s[16:17], s[56:57]
	s_branch .LBB0_1428
.LBB0_1427:
	v_add_u32_e32 v162, s74, v147
	v_add_u32_e32 v178, s75, v147
	ds_read_b128 v[148:151], v162
	ds_read_b128 v[152:155], v162 offset:1024
	ds_read_b128 v[158:161], v162 offset:2048
	ds_read_b128 v[162:165], v162 offset:3072
	ds_read_b128 v[166:169], v178
	ds_read_b128 v[170:173], v178 offset:1024
	ds_read_b128 v[174:177], v178 offset:2048
	ds_read_b128 v[178:181], v178 offset:3072
	s_add_u32 s49, s54, 0xfff80080
	s_addc_u32 s51, s55, -1
	s_and_b64 s[56:57], s[56:57], exec
	s_cselect_b32 s59, s17, s51
	s_cselect_b32 s58, s16, s49
	s_cselect_b32 s57, s11, s79
	s_cselect_b32 s56, s10, s78
	v_lshl_add_u64 v[214:215], s[54:55], 0, v[138:139]
	s_add_i32 m0, s53, 0xc000
	ds_read_b128 v[182:185], v157
	ds_read_b128 v[186:189], v157 offset:1024
	ds_read_b128 v[190:193], v157 offset:2048
	ds_read_b128 v[194:197], v157 offset:3072
	ds_read_b128 v[198:201], v157 offset:4096
	ds_read_b128 v[202:205], v157 offset:5120
	ds_read_b128 v[206:209], v157 offset:6144
	ds_read_b128 v[210:213], v157 offset:7168
	global_load_lds_dwordx4 v[214:215], off
	v_lshl_add_u64 v[214:215], s[54:55], 0, v[140:141]
	s_add_i32 m0, s53, 0xe000
	s_nop 0
	global_load_lds_dwordx4 v[214:215], off
	s_waitcnt vmcnt(8)
	s_waitcnt lgkmcnt(0)
	s_cmp_eq_i32 s80, -2
	s_cbranch_scc1 .Lzf_8_0
	s_barrier
	s_setprio 3
	s_waitcnt lgkmcnt(0)
	v_mfma_i32_16x16x64_i8 v[126:129], v[148:151], v[182:185], v[126:129]
	v_mfma_i32_16x16x64_i8 v[118:121], v[158:161], v[182:185], v[118:121]
	v_mfma_i32_16x16x64_i8 v[102:105], v[158:161], v[190:193], v[102:105]
	v_mfma_i32_16x16x64_i8 v[110:113], v[148:151], v[190:193], v[110:113]
	v_mfma_i32_16x16x64_i8 v[94:97], v[148:151], v[198:201], v[94:97]
	v_mfma_i32_16x16x64_i8 v[86:89], v[158:161], v[198:201], v[86:89]
	v_mfma_i32_16x16x64_i8 v[70:73], v[158:161], v[206:209], v[70:73]
	v_mfma_i32_16x16x64_i8 v[78:81], v[148:151], v[206:209], v[78:81]
	v_mfma_i32_16x16x64_i8 v[126:129], v[152:155], v[186:189], v[126:129]
	v_mfma_i32_16x16x64_i8 v[118:121], v[162:165], v[186:189], v[118:121]
	v_mfma_i32_16x16x64_i8 v[102:105], v[162:165], v[194:197], v[102:105]
	v_mfma_i32_16x16x64_i8 v[110:113], v[152:155], v[194:197], v[110:113]
	v_mfma_i32_16x16x64_i8 v[94:97], v[152:155], v[202:205], v[94:97]
	v_mfma_i32_16x16x64_i8 v[86:89], v[162:165], v[202:205], v[86:89]
	v_mfma_i32_16x16x64_i8 v[70:73], v[162:165], v[210:213], v[70:73]
	v_mfma_i32_16x16x64_i8 v[78:81], v[152:155], v[210:213], v[78:81]
	s_setprio 0
	s_setprio 3
	v_mfma_i32_16x16x64_i8 v[122:125], v[166:169], v[182:185], v[122:125]
	v_mfma_i32_16x16x64_i8 v[114:117], v[174:177], v[182:185], v[114:117]
	v_mfma_i32_16x16x64_i8 v[98:101], v[174:177], v[190:193], v[98:101]
	v_mfma_i32_16x16x64_i8 v[106:109], v[166:169], v[190:193], v[106:109]
	v_mfma_i32_16x16x64_i8 v[90:93], v[166:169], v[198:201], v[90:93]
	v_mfma_i32_16x16x64_i8 v[82:85], v[174:177], v[198:201], v[82:85]
	v_mfma_i32_16x16x64_i8 v[66:69], v[174:177], v[206:209], v[66:69]
	v_mfma_i32_16x16x64_i8 v[74:77], v[166:169], v[206:209], v[74:77]
	v_mfma_i32_16x16x64_i8 v[122:125], v[170:173], v[186:189], v[122:125]
	v_mfma_i32_16x16x64_i8 v[114:117], v[178:181], v[186:189], v[114:117]
	v_mfma_i32_16x16x64_i8 v[98:101], v[178:181], v[194:197], v[98:101]
	v_mfma_i32_16x16x64_i8 v[106:109], v[170:173], v[194:197], v[106:109]
	v_mfma_i32_16x16x64_i8 v[90:93], v[170:173], v[202:205], v[90:93]
	v_mfma_i32_16x16x64_i8 v[82:85], v[178:181], v[202:205], v[82:85]
	v_mfma_i32_16x16x64_i8 v[66:69], v[178:181], v[210:213], v[66:69]
	v_mfma_i32_16x16x64_i8 v[74:77], v[170:173], v[210:213], v[74:77]
	s_setprio 0
.Lzb_8_0:
	s_barrier
	s_add_i32 s49, s74, s61
	v_lshl_add_u64 v[214:215], s[56:57], 0, v[130:131]
	s_mov_b32 m0, s49
	ds_read_b128 v[182:185], v157 offset:16384
	ds_read_b128 v[186:189], v157 offset:17408
	ds_read_b128 v[190:193], v157 offset:18432
	ds_read_b128 v[194:197], v157 offset:19456
	ds_read_b128 v[198:201], v157 offset:20480
	ds_read_b128 v[202:205], v157 offset:21504
	ds_read_b128 v[206:209], v157 offset:22528
	ds_read_b128 v[210:213], v157 offset:23552
	global_load_lds_dwordx4 v[214:215], off
	s_add_i32 m0, s49, 0x2000
	s_add_u32 s82, s56, 0x80000
	v_lshl_add_u64 v[214:215], s[56:57], 0, v[132:133]
	s_addc_u32 s83, s57, 0
	s_add_i32 s49, s75, s61
	global_load_lds_dwordx4 v[214:215], off
	v_lshl_add_u64 v[214:215], s[82:83], 0, v[130:131]
	s_mov_b32 m0, s49
	v_lshl_add_u64 v[216:217], s[58:59], 0, v[134:135]
	global_load_lds_dwordx4 v[214:215], off
	v_lshl_add_u64 v[214:215], s[82:83], 0, v[132:133]
	s_add_i32 m0, s49, 0x2000
	s_nop 0
	global_load_lds_dwordx4 v[214:215], off
	v_lshl_add_u64 v[214:215], s[58:59], 0, v[136:137]
	s_mov_b32 m0, s53
	s_nop 0
	global_load_lds_dwordx4 v[214:215], off
	s_mov_b32 m0, s64
	s_nop 0
	global_load_lds_dwordx4 v[216:217], off
	s_waitcnt vmcnt(8)
	s_waitcnt lgkmcnt(0)
	s_cmp_eq_i32 s80, -2
	s_cbranch_scc1 .Lzf_8_1
	s_barrier
	s_setprio 3
	s_waitcnt lgkmcnt(0)
	v_mfma_i32_16x16x64_i8 v[62:65], v[148:151], v[182:185], v[62:65]
	v_mfma_i32_16x16x64_i8 v[54:57], v[158:161], v[182:185], v[54:57]
	v_mfma_i32_16x16x64_i8 v[38:41], v[158:161], v[190:193], v[38:41]
	v_mfma_i32_16x16x64_i8 v[46:49], v[148:151], v[190:193], v[46:49]
	v_mfma_i32_16x16x64_i8 v[30:33], v[148:151], v[198:201], v[30:33]
	v_mfma_i32_16x16x64_i8 v[22:25], v[158:161], v[198:201], v[22:25]
	v_mfma_i32_16x16x64_i8 v[6:9], v[158:161], v[206:209], v[6:9]
	v_mfma_i32_16x16x64_i8 v[14:17], v[148:151], v[206:209], v[14:17]
	v_mfma_i32_16x16x64_i8 v[62:65], v[152:155], v[186:189], v[62:65]
	v_mfma_i32_16x16x64_i8 v[54:57], v[162:165], v[186:189], v[54:57]
	v_mfma_i32_16x16x64_i8 v[38:41], v[162:165], v[194:197], v[38:41]
	v_mfma_i32_16x16x64_i8 v[46:49], v[152:155], v[194:197], v[46:49]
	v_mfma_i32_16x16x64_i8 v[30:33], v[152:155], v[202:205], v[30:33]
	v_mfma_i32_16x16x64_i8 v[22:25], v[162:165], v[202:205], v[22:25]
	v_mfma_i32_16x16x64_i8 v[6:9], v[162:165], v[210:213], v[6:9]
	v_mfma_i32_16x16x64_i8 v[14:17], v[152:155], v[210:213], v[14:17]
	s_setprio 0
	s_setprio 3
	v_mfma_i32_16x16x64_i8 v[58:61], v[166:169], v[182:185], v[58:61]
	v_mfma_i32_16x16x64_i8 v[50:53], v[174:177], v[182:185], v[50:53]
	v_mfma_i32_16x16x64_i8 v[34:37], v[174:177], v[190:193], v[34:37]
	v_mfma_i32_16x16x64_i8 v[42:45], v[166:169], v[190:193], v[42:45]
	v_mfma_i32_16x16x64_i8 v[26:29], v[166:169], v[198:201], v[26:29]
	v_mfma_i32_16x16x64_i8 v[18:21], v[174:177], v[198:201], v[18:21]
	v_mfma_i32_16x16x64_i8 v[2:5], v[174:177], v[206:209], v[2:5]
	v_mfma_i32_16x16x64_i8 v[10:13], v[166:169], v[206:209], v[10:13]
	v_mfma_i32_16x16x64_i8 v[58:61], v[170:173], v[186:189], v[58:61]
	v_mfma_i32_16x16x64_i8 v[50:53], v[178:181], v[186:189], v[50:53]
	v_mfma_i32_16x16x64_i8 v[34:37], v[178:181], v[194:197], v[34:37]
	v_mfma_i32_16x16x64_i8 v[42:45], v[170:173], v[194:197], v[42:45]
	v_mfma_i32_16x16x64_i8 v[26:29], v[170:173], v[202:205], v[26:29]
	v_mfma_i32_16x16x64_i8 v[18:21], v[178:181], v[202:205], v[18:21]
	v_mfma_i32_16x16x64_i8 v[2:5], v[178:181], v[210:213], v[2:5]
	v_mfma_i32_16x16x64_i8 v[10:13], v[170:173], v[210:213], v[10:13]
	s_setprio 0
.Lzb_8_1:
	s_barrier
	s_add_i32 s49, 0, 0x18000
	s_add_i32 s51, 0, 0x1c000
	v_add_u32_e32 v162, s49, v147
	v_add_u32_e32 v178, s51, v147
	ds_read_b128 v[148:151], v162
	ds_read_b128 v[152:155], v162 offset:1024
	ds_read_b128 v[158:161], v162 offset:2048
	ds_read_b128 v[162:165], v162 offset:3072
	ds_read_b128 v[166:169], v178
	ds_read_b128 v[170:173], v178 offset:1024
	ds_read_b128 v[174:177], v178 offset:2048
	ds_read_b128 v[178:181], v178 offset:3072
	s_add_u32 s58, s58, 0x80000
	s_addc_u32 s59, s59, 0
	s_mov_b32 m0, s65
	v_lshl_add_u64 v[218:219], s[58:59], 0, v[136:137]
	ds_read_b128 v[182:185], v157 offset:32768
	ds_read_b128 v[186:189], v157 offset:33792
	ds_read_b128 v[190:193], v157 offset:34816
	ds_read_b128 v[194:197], v157 offset:35840
	ds_read_b128 v[198:201], v157 offset:36864
	ds_read_b128 v[202:205], v157 offset:37888
	ds_read_b128 v[206:209], v157 offset:38912
	ds_read_b128 v[210:213], v157 offset:39936
	global_load_lds_dwordx4 v[218:219], off
	v_lshl_add_u64 v[218:219], s[58:59], 0, v[134:135]
	s_mov_b32 m0, s66
	s_nop 0
	global_load_lds_dwordx4 v[218:219], off
	s_waitcnt vmcnt(8)
	s_waitcnt lgkmcnt(0)
	s_barrier
	s_setprio 3
	s_waitcnt lgkmcnt(0)
	v_mfma_i32_16x16x64_i8 v[126:129], v[148:151], v[182:185], v[126:129]
	v_mfma_i32_16x16x64_i8 v[118:121], v[158:161], v[182:185], v[118:121]
	v_mfma_i32_16x16x64_i8 v[102:105], v[158:161], v[190:193], v[102:105]
	v_mfma_i32_16x16x64_i8 v[110:113], v[148:151], v[190:193], v[110:113]
	v_mfma_i32_16x16x64_i8 v[94:97], v[148:151], v[198:201], v[94:97]
	v_mfma_i32_16x16x64_i8 v[86:89], v[158:161], v[198:201], v[86:89]
	v_mfma_i32_16x16x64_i8 v[70:73], v[158:161], v[206:209], v[70:73]
	v_mfma_i32_16x16x64_i8 v[78:81], v[148:151], v[206:209], v[78:81]
	v_mfma_i32_16x16x64_i8 v[126:129], v[152:155], v[186:189], v[126:129]
	v_mfma_i32_16x16x64_i8 v[118:121], v[162:165], v[186:189], v[118:121]
	v_mfma_i32_16x16x64_i8 v[102:105], v[162:165], v[194:197], v[102:105]
	v_mfma_i32_16x16x64_i8 v[110:113], v[152:155], v[194:197], v[110:113]
	v_mfma_i32_16x16x64_i8 v[94:97], v[152:155], v[202:205], v[94:97]
	v_mfma_i32_16x16x64_i8 v[86:89], v[162:165], v[202:205], v[86:89]
	v_mfma_i32_16x16x64_i8 v[70:73], v[162:165], v[210:213], v[70:73]
	v_mfma_i32_16x16x64_i8 v[78:81], v[152:155], v[210:213], v[78:81]
	s_setprio 0
	s_setprio 3
	v_mfma_i32_16x16x64_i8 v[122:125], v[166:169], v[182:185], v[122:125]
	v_mfma_i32_16x16x64_i8 v[114:117], v[174:177], v[182:185], v[114:117]
	v_mfma_i32_16x16x64_i8 v[98:101], v[174:177], v[190:193], v[98:101]
	v_mfma_i32_16x16x64_i8 v[106:109], v[166:169], v[190:193], v[106:109]
	v_mfma_i32_16x16x64_i8 v[90:93], v[166:169], v[198:201], v[90:93]
	v_mfma_i32_16x16x64_i8 v[82:85], v[174:177], v[198:201], v[82:85]
	v_mfma_i32_16x16x64_i8 v[66:69], v[174:177], v[206:209], v[66:69]
	v_mfma_i32_16x16x64_i8 v[74:77], v[166:169], v[206:209], v[74:77]
	v_mfma_i32_16x16x64_i8 v[122:125], v[170:173], v[186:189], v[122:125]
	v_mfma_i32_16x16x64_i8 v[114:117], v[178:181], v[186:189], v[114:117]
	v_mfma_i32_16x16x64_i8 v[98:101], v[178:181], v[194:197], v[98:101]
	v_mfma_i32_16x16x64_i8 v[106:109], v[170:173], v[194:197], v[106:109]
	v_mfma_i32_16x16x64_i8 v[90:93], v[170:173], v[202:205], v[90:93]
	v_mfma_i32_16x16x64_i8 v[82:85], v[178:181], v[202:205], v[82:85]
	v_mfma_i32_16x16x64_i8 v[66:69], v[178:181], v[210:213], v[66:69]
	v_mfma_i32_16x16x64_i8 v[74:77], v[170:173], v[210:213], v[74:77]
	s_setprio 0
	s_barrier
	s_add_u32 s58, s56, 0x4000
	s_addc_u32 s59, s57, 0
	s_add_i32 s49, s49, s61
	v_lshl_add_u64 v[218:219], s[58:59], 0, v[130:131]
	s_mov_b32 m0, s49
	ds_read_b128 v[182:185], v157 offset:49152
	ds_read_b128 v[186:189], v157 offset:50176
	ds_read_b128 v[190:193], v157 offset:51200
	ds_read_b128 v[194:197], v157 offset:52224
	ds_read_b128 v[198:201], v157 offset:53248
	ds_read_b128 v[202:205], v157 offset:54272
	ds_read_b128 v[206:209], v157 offset:55296
	ds_read_b128 v[210:213], v157 offset:56320
	global_load_lds_dwordx4 v[218:219], off
	s_add_i32 m0, s49, 0x2000
	s_add_u32 s56, s56, 0x84000
	v_lshl_add_u64 v[218:219], s[58:59], 0, v[132:133]
	s_addc_u32 s57, s57, 0
	s_add_i32 s49, s51, s61
	global_load_lds_dwordx4 v[218:219], off
	v_lshl_add_u64 v[218:219], s[56:57], 0, v[130:131]
	s_mov_b32 m0, s49
	v_lshl_add_u64 v[214:215], v[214:215], 0, s[42:43]
	global_load_lds_dwordx4 v[218:219], off
	v_lshl_add_u64 v[218:219], s[56:57], 0, v[132:133]
	s_add_i32 m0, s49, 0x2000
	s_nop 0
	global_load_lds_dwordx4 v[218:219], off
	s_mov_b32 m0, s70
	s_nop 0
	global_load_lds_dwordx4 v[214:215], off
	v_lshl_add_u64 v[214:215], v[216:217], 0, s[42:43]
	s_mov_b32 m0, s71
	s_nop 0
	global_load_lds_dwordx4 v[214:215], off
	s_waitcnt vmcnt(8)
	s_waitcnt lgkmcnt(0)
	s_barrier
	s_setprio 3
	s_waitcnt lgkmcnt(0)
	v_mfma_i32_16x16x64_i8 v[62:65], v[148:151], v[182:185], v[62:65]
	v_mfma_i32_16x16x64_i8 v[54:57], v[158:161], v[182:185], v[54:57]
	v_mfma_i32_16x16x64_i8 v[38:41], v[158:161], v[190:193], v[38:41]
	v_mfma_i32_16x16x64_i8 v[46:49], v[148:151], v[190:193], v[46:49]
	v_mfma_i32_16x16x64_i8 v[30:33], v[148:151], v[198:201], v[30:33]
	v_mfma_i32_16x16x64_i8 v[22:25], v[158:161], v[198:201], v[22:25]
	v_mfma_i32_16x16x64_i8 v[6:9], v[158:161], v[206:209], v[6:9]
	v_mfma_i32_16x16x64_i8 v[14:17], v[148:151], v[206:209], v[14:17]
	v_mfma_i32_16x16x64_i8 v[62:65], v[152:155], v[186:189], v[62:65]
	v_mfma_i32_16x16x64_i8 v[54:57], v[162:165], v[186:189], v[54:57]
	v_mfma_i32_16x16x64_i8 v[38:41], v[162:165], v[194:197], v[38:41]
	v_mfma_i32_16x16x64_i8 v[46:49], v[152:155], v[194:197], v[46:49]
	v_mfma_i32_16x16x64_i8 v[30:33], v[152:155], v[202:205], v[30:33]
	v_mfma_i32_16x16x64_i8 v[22:25], v[162:165], v[202:205], v[22:25]
	v_mfma_i32_16x16x64_i8 v[6:9], v[162:165], v[210:213], v[6:9]
	v_mfma_i32_16x16x64_i8 v[14:17], v[152:155], v[210:213], v[14:17]
	s_setprio 0
	s_setprio 3
	v_mfma_i32_16x16x64_i8 v[58:61], v[166:169], v[182:185], v[58:61]
	v_mfma_i32_16x16x64_i8 v[50:53], v[174:177], v[182:185], v[50:53]
	v_mfma_i32_16x16x64_i8 v[34:37], v[174:177], v[190:193], v[34:37]
	v_mfma_i32_16x16x64_i8 v[42:45], v[166:169], v[190:193], v[42:45]
	v_mfma_i32_16x16x64_i8 v[26:29], v[166:169], v[198:201], v[26:29]
	v_mfma_i32_16x16x64_i8 v[18:21], v[174:177], v[198:201], v[18:21]
	v_mfma_i32_16x16x64_i8 v[2:5], v[174:177], v[206:209], v[2:5]
	v_mfma_i32_16x16x64_i8 v[10:13], v[166:169], v[206:209], v[10:13]
	v_mfma_i32_16x16x64_i8 v[58:61], v[170:173], v[186:189], v[58:61]
	v_mfma_i32_16x16x64_i8 v[50:53], v[178:181], v[186:189], v[50:53]
	v_mfma_i32_16x16x64_i8 v[34:37], v[178:181], v[194:197], v[34:37]
	v_mfma_i32_16x16x64_i8 v[42:45], v[170:173], v[194:197], v[42:45]
	v_mfma_i32_16x16x64_i8 v[26:29], v[170:173], v[202:205], v[26:29]
	v_mfma_i32_16x16x64_i8 v[18:21], v[178:181], v[202:205], v[18:21]
	v_mfma_i32_16x16x64_i8 v[2:5], v[178:181], v[210:213], v[2:5]
	v_mfma_i32_16x16x64_i8 v[10:13], v[170:173], v[210:213], v[10:13]
	s_setprio 0
	s_barrier
	s_add_i32 s80, s80, 2
	s_add_u32 s78, s78, 0x8000
	s_addc_u32 s79, s79, 0
	s_add_u32 s54, s54, 0x100
	s_addc_u32 s55, s55, 0
	s_cmp_gt_u32 s80, 29
	s_cbranch_scc1 .LBB0_1433

.LBB0_1599:
	s_add_u32 s68, s42, 0x8000
	s_addc_u32 s69, s43, 0
	s_mov_b32 s70, -2
.LBB0_1600:
	ds_read_b128 v[146:149], v156
	ds_read_b128 v[150:153], v156 offset:1024
	ds_read_b128 v[160:163], v156 offset:2048
	ds_read_b128 v[164:167], v156 offset:3072
	ds_read_b128 v[168:171], v157
	ds_read_b128 v[172:175], v157 offset:1024
	ds_read_b128 v[176:179], v157 offset:2048
	ds_read_b128 v[180:183], v157 offset:3072
	s_add_u32 s42, s0, 0x100
	s_addc_u32 s43, s1, 0
	s_cmpk_eq_i32 s70, 0x52
	s_cselect_b32 s47, s7, s43
	s_cselect_b32 s46, s6, s42
	s_cselect_b32 s45, s41, s69
	s_cselect_b32 s44, s40, s68
	v_lshl_add_u64 v[216:217], s[0:1], 0, v[138:139]
	s_add_i32 m0, s49, 0xc000
	ds_read_b128 v[184:187], v158
	ds_read_b128 v[188:191], v158 offset:1024
	ds_read_b128 v[192:195], v158 offset:2048
	ds_read_b128 v[196:199], v158 offset:3072
	ds_read_b128 v[200:203], v158 offset:4096
	ds_read_b128 v[204:207], v158 offset:5120
	ds_read_b128 v[208:211], v158 offset:6144
	ds_read_b128 v[212:215], v158 offset:7168
	global_load_lds_dwordx4 v[216:217], off
	v_lshl_add_u64 v[216:217], s[0:1], 0, v[140:141]
	s_add_i32 m0, s49, 0xe000
	s_nop 0
	global_load_lds_dwordx4 v[216:217], off
	s_waitcnt vmcnt(8)
	s_waitcnt lgkmcnt(0)
	s_cmp_eq_i32 s70, -2
	s_cbranch_scc1 .Lzf_9_0
	s_barrier
	s_setprio 3
	s_waitcnt lgkmcnt(0)
	v_mfma_i32_16x16x64_i8 v[126:129], v[146:149], v[184:187], v[126:129]
	v_mfma_i32_16x16x64_i8 v[122:125], v[160:163], v[184:187], v[122:125]
	v_mfma_i32_16x16x64_i8 v[114:117], v[160:163], v[192:195], v[114:117]
	v_mfma_i32_16x16x64_i8 v[118:121], v[146:149], v[192:195], v[118:121]
	v_mfma_i32_16x16x64_i8 v[110:113], v[146:149], v[200:203], v[110:113]
	v_mfma_i32_16x16x64_i8 v[106:109], v[160:163], v[200:203], v[106:109]
	v_mfma_i32_16x16x64_i8 v[98:101], v[160:163], v[208:211], v[98:101]
	v_mfma_i32_16x16x64_i8 v[102:105], v[146:149], v[208:211], v[102:105]
	v_mfma_i32_16x16x64_i8 v[126:129], v[150:153], v[188:191], v[126:129]
	v_mfma_i32_16x16x64_i8 v[122:125], v[164:167], v[188:191], v[122:125]
	v_mfma_i32_16x16x64_i8 v[114:117], v[164:167], v[196:199], v[114:117]
	v_mfma_i32_16x16x64_i8 v[118:121], v[150:153], v[196:199], v[118:121]
	v_mfma_i32_16x16x64_i8 v[110:113], v[150:153], v[204:207], v[110:113]
	v_mfma_i32_16x16x64_i8 v[106:109], v[164:167], v[204:207], v[106:109]
	v_mfma_i32_16x16x64_i8 v[98:101], v[164:167], v[212:215], v[98:101]
	v_mfma_i32_16x16x64_i8 v[102:105], v[150:153], v[212:215], v[102:105]
	s_setprio 0
	s_setprio 3
	v_mfma_i32_16x16x64_i8 v[62:65], v[168:171], v[184:187], v[62:65]
	v_mfma_i32_16x16x64_i8 v[58:61], v[176:179], v[184:187], v[58:61]
	v_mfma_i32_16x16x64_i8 v[50:53], v[176:179], v[192:195], v[50:53]
	v_mfma_i32_16x16x64_i8 v[54:57], v[168:171], v[192:195], v[54:57]
	v_mfma_i32_16x16x64_i8 v[46:49], v[168:171], v[200:203], v[46:49]
	v_mfma_i32_16x16x64_i8 v[42:45], v[176:179], v[200:203], v[42:45]
	v_mfma_i32_16x16x64_i8 v[34:37], v[176:179], v[208:211], v[34:37]
	v_mfma_i32_16x16x64_i8 v[38:41], v[168:171], v[208:211], v[38:41]
	v_mfma_i32_16x16x64_i8 v[62:65], v[172:175], v[188:191], v[62:65]
	v_mfma_i32_16x16x64_i8 v[58:61], v[180:183], v[188:191], v[58:61]
	v_mfma_i32_16x16x64_i8 v[50:53], v[180:183], v[196:199], v[50:53]
	v_mfma_i32_16x16x64_i8 v[54:57], v[172:175], v[196:199], v[54:57]
	v_mfma_i32_16x16x64_i8 v[46:49], v[172:175], v[204:207], v[46:49]
	v_mfma_i32_16x16x64_i8 v[42:45], v[180:183], v[204:207], v[42:45]
	v_mfma_i32_16x16x64_i8 v[34:37], v[180:183], v[212:215], v[34:37]
	v_mfma_i32_16x16x64_i8 v[38:41], v[172:175], v[212:215], v[38:41]
	s_setprio 0
.Lzb_9_0:
	s_barrier
	s_add_i32 s0, s57, s48
	v_lshl_add_u64 v[216:217], s[44:45], 0, v[130:131]
	s_mov_b32 m0, s0
	ds_read_b128 v[184:187], v158 offset:16384
	ds_read_b128 v[188:191], v158 offset:17408
	ds_read_b128 v[192:195], v158 offset:18432
	ds_read_b128 v[196:199], v158 offset:19456
	ds_read_b128 v[200:203], v158 offset:20480
	ds_read_b128 v[204:207], v158 offset:21504
	ds_read_b128 v[208:211], v158 offset:22528
	ds_read_b128 v[212:215], v158 offset:23552
	global_load_lds_dwordx4 v[216:217], off
	s_add_i32 m0, s0, 0x2000
	s_add_u32 s0, s44, 0x158000
	v_lshl_add_u64 v[216:217], s[44:45], 0, v[134:135]
	s_addc_u32 s1, s45, 0
	s_add_i32 s71, s58, s48
	global_load_lds_dwordx4 v[216:217], off
	v_lshl_add_u64 v[216:217], s[0:1], 0, v[130:131]
	s_mov_b32 m0, s71
	v_lshl_add_u64 v[218:219], s[46:47], 0, v[136:137]
	global_load_lds_dwordx4 v[216:217], off
	v_lshl_add_u64 v[216:217], s[0:1], 0, v[134:135]
	s_add_i32 m0, s71, 0x2000
	s_nop 0
	global_load_lds_dwordx4 v[216:217], off
	v_lshl_add_u64 v[216:217], s[46:47], 0, v[132:133]
	s_mov_b32 m0, s49
	s_nop 0
	global_load_lds_dwordx4 v[216:217], off
	s_mov_b32 m0, s50
	s_nop 0
	global_load_lds_dwordx4 v[218:219], off
	s_waitcnt vmcnt(8)
	s_waitcnt lgkmcnt(0)
	s_cmp_eq_i32 s70, -2
	s_cbranch_scc1 .Lzf_9_1
	s_barrier
	s_setprio 3
	s_waitcnt lgkmcnt(0)
	v_mfma_i32_16x16x64_i8 v[94:97], v[146:149], v[184:187], v[94:97]
	v_mfma_i32_16x16x64_i8 v[90:93], v[160:163], v[184:187], v[90:93]
	v_mfma_i32_16x16x64_i8 v[82:85], v[160:163], v[192:195], v[82:85]
	v_mfma_i32_16x16x64_i8 v[86:89], v[146:149], v[192:195], v[86:89]
	v_mfma_i32_16x16x64_i8 v[78:81], v[146:149], v[200:203], v[78:81]
	v_mfma_i32_16x16x64_i8 v[74:77], v[160:163], v[200:203], v[74:77]
	v_mfma_i32_16x16x64_i8 v[66:69], v[160:163], v[208:211], v[66:69]
	v_mfma_i32_16x16x64_i8 v[70:73], v[146:149], v[208:211], v[70:73]
	v_mfma_i32_16x16x64_i8 v[94:97], v[150:153], v[188:191], v[94:97]
	v_mfma_i32_16x16x64_i8 v[90:93], v[164:167], v[188:191], v[90:93]
	v_mfma_i32_16x16x64_i8 v[82:85], v[164:167], v[196:199], v[82:85]
	v_mfma_i32_16x16x64_i8 v[86:89], v[150:153], v[196:199], v[86:89]
	v_mfma_i32_16x16x64_i8 v[78:81], v[150:153], v[204:207], v[78:81]
	v_mfma_i32_16x16x64_i8 v[74:77], v[164:167], v[204:207], v[74:77]
	v_mfma_i32_16x16x64_i8 v[66:69], v[164:167], v[212:215], v[66:69]
	v_mfma_i32_16x16x64_i8 v[70:73], v[150:153], v[212:215], v[70:73]
	s_setprio 0
	s_setprio 3
	v_mfma_i32_16x16x64_i8 v[30:33], v[168:171], v[184:187], v[30:33]
	v_mfma_i32_16x16x64_i8 v[26:29], v[176:179], v[184:187], v[26:29]
	v_mfma_i32_16x16x64_i8 v[18:21], v[176:179], v[192:195], v[18:21]
	v_mfma_i32_16x16x64_i8 v[22:25], v[168:171], v[192:195], v[22:25]
	v_mfma_i32_16x16x64_i8 v[14:17], v[168:171], v[200:203], v[14:17]
	v_mfma_i32_16x16x64_i8 v[10:13], v[176:179], v[200:203], v[10:13]
	v_mfma_i32_16x16x64_i8 v[2:5], v[176:179], v[208:211], v[2:5]
	v_mfma_i32_16x16x64_i8 v[6:9], v[168:171], v[208:211], v[6:9]
	v_mfma_i32_16x16x64_i8 v[30:33], v[172:175], v[188:191], v[30:33]
	v_mfma_i32_16x16x64_i8 v[26:29], v[180:183], v[188:191], v[26:29]
	v_mfma_i32_16x16x64_i8 v[18:21], v[180:183], v[196:199], v[18:21]
	v_mfma_i32_16x16x64_i8 v[22:25], v[172:175], v[196:199], v[22:25]
	v_mfma_i32_16x16x64_i8 v[14:17], v[172:175], v[204:207], v[14:17]
	v_mfma_i32_16x16x64_i8 v[10:13], v[180:183], v[204:207], v[10:13]
	v_mfma_i32_16x16x64_i8 v[2:5], v[180:183], v[212:215], v[2:5]
	v_mfma_i32_16x16x64_i8 v[6:9], v[172:175], v[212:215], v[6:9]
	s_setprio 0
.Lzb_9_1:
	s_barrier
	s_add_i32 s71, 0, 0x18000
	v_add_u32_e32 v159, s71, v154
	s_add_i32 s72, 0, 0x1c000
	ds_read_b128 v[146:149], v159
	ds_read_b128 v[150:153], v159 offset:1024
	ds_read_b128 v[160:163], v159 offset:2048
	ds_read_b128 v[164:167], v159 offset:3072
	v_add_u32_e32 v159, s72, v154
	ds_read_b128 v[168:171], v159
	ds_read_b128 v[172:175], v159 offset:1024
	ds_read_b128 v[176:179], v159 offset:2048
	ds_read_b128 v[180:183], v159 offset:3072
	s_add_u32 s0, s46, 0x158000
	s_addc_u32 s1, s47, 0
	s_mov_b32 m0, s51
	v_lshl_add_u64 v[220:221], s[0:1], 0, v[132:133]
	ds_read_b128 v[184:187], v158 offset:32768
	ds_read_b128 v[188:191], v158 offset:33792
	ds_read_b128 v[192:195], v158 offset:34816
	ds_read_b128 v[196:199], v158 offset:35840
	ds_read_b128 v[200:203], v158 offset:36864
	ds_read_b128 v[204:207], v158 offset:37888
	ds_read_b128 v[208:211], v158 offset:38912
	ds_read_b128 v[212:215], v158 offset:39936
	global_load_lds_dwordx4 v[220:221], off
	v_lshl_add_u64 v[220:221], s[0:1], 0, v[136:137]
	s_mov_b32 m0, s52
	s_nop 0
	global_load_lds_dwordx4 v[220:221], off
	s_waitcnt vmcnt(8)
	s_waitcnt lgkmcnt(0)
	s_barrier
	s_setprio 3
	s_waitcnt lgkmcnt(0)
	v_mfma_i32_16x16x64_i8 v[126:129], v[146:149], v[184:187], v[126:129]
	v_mfma_i32_16x16x64_i8 v[122:125], v[160:163], v[184:187], v[122:125]
	v_mfma_i32_16x16x64_i8 v[114:117], v[160:163], v[192:195], v[114:117]
	v_mfma_i32_16x16x64_i8 v[118:121], v[146:149], v[192:195], v[118:121]
	v_mfma_i32_16x16x64_i8 v[110:113], v[146:149], v[200:203], v[110:113]
	v_mfma_i32_16x16x64_i8 v[106:109], v[160:163], v[200:203], v[106:109]
	v_mfma_i32_16x16x64_i8 v[98:101], v[160:163], v[208:211], v[98:101]
	v_mfma_i32_16x16x64_i8 v[102:105], v[146:149], v[208:211], v[102:105]
	v_mfma_i32_16x16x64_i8 v[126:129], v[150:153], v[188:191], v[126:129]
	v_mfma_i32_16x16x64_i8 v[122:125], v[164:167], v[188:191], v[122:125]
	v_mfma_i32_16x16x64_i8 v[114:117], v[164:167], v[196:199], v[114:117]
	v_mfma_i32_16x16x64_i8 v[118:121], v[150:153], v[196:199], v[118:121]
	v_mfma_i32_16x16x64_i8 v[110:113], v[150:153], v[204:207], v[110:113]
	v_mfma_i32_16x16x64_i8 v[106:109], v[164:167], v[204:207], v[106:109]
	v_mfma_i32_16x16x64_i8 v[98:101], v[164:167], v[212:215], v[98:101]
	v_mfma_i32_16x16x64_i8 v[102:105], v[150:153], v[212:215], v[102:105]
	s_setprio 0
	s_setprio 3
	v_mfma_i32_16x16x64_i8 v[62:65], v[168:171], v[184:187], v[62:65]
	v_mfma_i32_16x16x64_i8 v[58:61], v[176:179], v[184:187], v[58:61]
	v_mfma_i32_16x16x64_i8 v[50:53], v[176:179], v[192:195], v[50:53]
	v_mfma_i32_16x16x64_i8 v[54:57], v[168:171], v[192:195], v[54:57]
	v_mfma_i32_16x16x64_i8 v[46:49], v[168:171], v[200:203], v[46:49]
	v_mfma_i32_16x16x64_i8 v[42:45], v[176:179], v[200:203], v[42:45]
	v_mfma_i32_16x16x64_i8 v[34:37], v[176:179], v[208:211], v[34:37]
	v_mfma_i32_16x16x64_i8 v[38:41], v[168:171], v[208:211], v[38:41]
	v_mfma_i32_16x16x64_i8 v[62:65], v[172:175], v[188:191], v[62:65]
	v_mfma_i32_16x16x64_i8 v[58:61], v[180:183], v[188:191], v[58:61]
	v_mfma_i32_16x16x64_i8 v[50:53], v[180:183], v[196:199], v[50:53]
	v_mfma_i32_16x16x64_i8 v[54:57], v[172:175], v[196:199], v[54:57]
	v_mfma_i32_16x16x64_i8 v[46:49], v[172:175], v[204:207], v[46:49]
	v_mfma_i32_16x16x64_i8 v[42:45], v[180:183], v[204:207], v[42:45]
	v_mfma_i32_16x16x64_i8 v[34:37], v[180:183], v[212:215], v[34:37]
	v_mfma_i32_16x16x64_i8 v[38:41], v[172:175], v[212:215], v[38:41]
	s_setprio 0
	s_barrier
	s_add_u32 s0, s44, 0x4000
	s_addc_u32 s1, s45, 0
	s_add_i32 s46, s71, s48
	v_lshl_add_u64 v[220:221], s[0:1], 0, v[130:131]
	s_mov_b32 m0, s46
	ds_read_b128 v[184:187], v158 offset:49152
	ds_read_b128 v[188:191], v158 offset:50176
	ds_read_b128 v[192:195], v158 offset:51200
	ds_read_b128 v[196:199], v158 offset:52224
	ds_read_b128 v[200:203], v158 offset:53248
	ds_read_b128 v[204:207], v158 offset:54272
	ds_read_b128 v[208:211], v158 offset:55296
	ds_read_b128 v[212:215], v158 offset:56320
	global_load_lds_dwordx4 v[220:221], off
	s_add_i32 m0, s46, 0x2000
	v_lshl_add_u64 v[220:221], s[0:1], 0, v[134:135]
	s_add_u32 s0, s44, 0x15c000
	s_addc_u32 s1, s45, 0
	s_add_i32 s44, s72, s48
	global_load_lds_dwordx4 v[220:221], off
	v_lshl_add_u64 v[220:221], s[0:1], 0, v[130:131]
	s_mov_b32 m0, s44
	v_lshl_add_u64 v[216:217], v[216:217], 0, s[18:19]
	global_load_lds_dwordx4 v[220:221], off
	v_lshl_add_u64 v[220:221], s[0:1], 0, v[134:135]
	s_add_i32 m0, s44, 0x2000
	s_nop 0
	global_load_lds_dwordx4 v[220:221], off
	s_mov_b32 m0, s54
	s_nop 0
	global_load_lds_dwordx4 v[216:217], off
	v_lshl_add_u64 v[216:217], v[218:219], 0, s[18:19]
	s_mov_b32 m0, s55
	s_nop 0
	global_load_lds_dwordx4 v[216:217], off
	s_waitcnt vmcnt(8)
	s_waitcnt lgkmcnt(0)
	s_barrier
	s_setprio 3
	s_waitcnt lgkmcnt(0)
	v_mfma_i32_16x16x64_i8 v[94:97], v[146:149], v[184:187], v[94:97]
	v_mfma_i32_16x16x64_i8 v[90:93], v[160:163], v[184:187], v[90:93]
	v_mfma_i32_16x16x64_i8 v[82:85], v[160:163], v[192:195], v[82:85]
	v_mfma_i32_16x16x64_i8 v[86:89], v[146:149], v[192:195], v[86:89]
	v_mfma_i32_16x16x64_i8 v[78:81], v[146:149], v[200:203], v[78:81]
	v_mfma_i32_16x16x64_i8 v[74:77], v[160:163], v[200:203], v[74:77]
	v_mfma_i32_16x16x64_i8 v[66:69], v[160:163], v[208:211], v[66:69]
	v_mfma_i32_16x16x64_i8 v[70:73], v[146:149], v[208:211], v[70:73]
	v_mfma_i32_16x16x64_i8 v[94:97], v[150:153], v[188:191], v[94:97]
	v_mfma_i32_16x16x64_i8 v[90:93], v[164:167], v[188:191], v[90:93]
	v_mfma_i32_16x16x64_i8 v[82:85], v[164:167], v[196:199], v[82:85]
	v_mfma_i32_16x16x64_i8 v[86:89], v[150:153], v[196:199], v[86:89]
	v_mfma_i32_16x16x64_i8 v[78:81], v[150:153], v[204:207], v[78:81]
	v_mfma_i32_16x16x64_i8 v[74:77], v[164:167], v[204:207], v[74:77]
	v_mfma_i32_16x16x64_i8 v[66:69], v[164:167], v[212:215], v[66:69]
	v_mfma_i32_16x16x64_i8 v[70:73], v[150:153], v[212:215], v[70:73]
	s_setprio 0
	s_setprio 3
	v_mfma_i32_16x16x64_i8 v[30:33], v[168:171], v[184:187], v[30:33]
	v_mfma_i32_16x16x64_i8 v[26:29], v[176:179], v[184:187], v[26:29]
	v_mfma_i32_16x16x64_i8 v[18:21], v[176:179], v[192:195], v[18:21]
	v_mfma_i32_16x16x64_i8 v[22:25], v[168:171], v[192:195], v[22:25]
	v_mfma_i32_16x16x64_i8 v[14:17], v[168:171], v[200:203], v[14:17]
	v_mfma_i32_16x16x64_i8 v[10:13], v[176:179], v[200:203], v[10:13]
	v_mfma_i32_16x16x64_i8 v[2:5], v[176:179], v[208:211], v[2:5]
	v_mfma_i32_16x16x64_i8 v[6:9], v[168:171], v[208:211], v[6:9]
	v_mfma_i32_16x16x64_i8 v[30:33], v[172:175], v[188:191], v[30:33]
	v_mfma_i32_16x16x64_i8 v[26:29], v[180:183], v[188:191], v[26:29]
	v_mfma_i32_16x16x64_i8 v[18:21], v[180:183], v[196:199], v[18:21]
	v_mfma_i32_16x16x64_i8 v[22:25], v[172:175], v[196:199], v[22:25]
	v_mfma_i32_16x16x64_i8 v[14:17], v[172:175], v[204:207], v[14:17]
	v_mfma_i32_16x16x64_i8 v[10:13], v[180:183], v[204:207], v[10:13]
	v_mfma_i32_16x16x64_i8 v[2:5], v[180:183], v[212:215], v[2:5]
	v_mfma_i32_16x16x64_i8 v[6:9], v[172:175], v[212:215], v[6:9]
	s_setprio 0
	s_barrier
	s_add_i32 s70, s70, 2
	s_add_u32 s68, s68, 0x8000
	s_addc_u32 s69, s69, 0
	s_cmpk_gt_u32 s70, 0x53
	s_mov_b64 s[0:1], s[42:43]
	s_cbranch_scc0 .LBB0_1600
	s_and_b64 vcc, exec, s[20:21]
	s_cbranch_vccz .LBB0_1603
	s_barrier

.Lzf_9_0:
	s_barrier
	s_setprio 3
	s_waitcnt lgkmcnt(0)
	v_mfma_i32_16x16x64_i8 v[126:129], v[146:149], v[184:187], 0
	v_mfma_i32_16x16x64_i8 v[122:125], v[160:163], v[184:187], 0
	v_mfma_i32_16x16x64_i8 v[114:117], v[160:163], v[192:195], 0
	v_mfma_i32_16x16x64_i8 v[118:121], v[146:149], v[192:195], 0
	v_mfma_i32_16x16x64_i8 v[110:113], v[146:149], v[200:203], 0
	v_mfma_i32_16x16x64_i8 v[106:109], v[160:163], v[200:203], 0
	v_mfma_i32_16x16x64_i8 v[98:101], v[160:163], v[208:211], 0
	v_mfma_i32_16x16x64_i8 v[102:105], v[146:149], v[208:211], 0
	v_mfma_i32_16x16x64_i8 v[126:129], v[150:153], v[188:191], v[126:129]
	v_mfma_i32_16x16x64_i8 v[122:125], v[164:167], v[188:191], v[122:125]
	v_mfma_i32_16x16x64_i8 v[114:117], v[164:167], v[196:199], v[114:117]
	v_mfma_i32_16x16x64_i8 v[118:121], v[150:153], v[196:199], v[118:121]
	v_mfma_i32_16x16x64_i8 v[110:113], v[150:153], v[204:207], v[110:113]
	v_mfma_i32_16x16x64_i8 v[106:109], v[164:167], v[204:207], v[106:109]
	v_mfma_i32_16x16x64_i8 v[98:101], v[164:167], v[212:215], v[98:101]
	v_mfma_i32_16x16x64_i8 v[102:105], v[150:153], v[212:215], v[102:105]
	s_setprio 0
	s_setprio 3
	v_mfma_i32_16x16x64_i8 v[62:65], v[168:171], v[184:187], 0
	v_mfma_i32_16x16x64_i8 v[58:61], v[176:179], v[184:187], 0
	v_mfma_i32_16x16x64_i8 v[50:53], v[176:179], v[192:195], 0
	v_mfma_i32_16x16x64_i8 v[54:57], v[168:171], v[192:195], 0
	v_mfma_i32_16x16x64_i8 v[46:49], v[168:171], v[200:203], 0
	v_mfma_i32_16x16x64_i8 v[42:45], v[176:179], v[200:203], 0
	v_mfma_i32_16x16x64_i8 v[34:37], v[176:179], v[208:211], 0
	v_mfma_i32_16x16x64_i8 v[38:41], v[168:171], v[208:211], 0
	v_mfma_i32_16x16x64_i8 v[62:65], v[172:175], v[188:191], v[62:65]
	v_mfma_i32_16x16x64_i8 v[58:61], v[180:183], v[188:191], v[58:61]
	v_mfma_i32_16x16x64_i8 v[50:53], v[180:183], v[196:199], v[50:53]
	v_mfma_i32_16x16x64_i8 v[54:57], v[172:175], v[196:199], v[54:57]
	v_mfma_i32_16x16x64_i8 v[46:49], v[172:175], v[204:207], v[46:49]
	v_mfma_i32_16x16x64_i8 v[42:45], v[180:183], v[204:207], v[42:45]
	v_mfma_i32_16x16x64_i8 v[34:37], v[180:183], v[212:215], v[34:37]
	v_mfma_i32_16x16x64_i8 v[38:41], v[172:175], v[212:215], v[38:41]
	s_setprio 0
	s_branch .Lzb_9_0
.Lzf_9_1:
	s_barrier
	s_setprio 3
	s_waitcnt lgkmcnt(0)
	v_mfma_i32_16x16x64_i8 v[94:97], v[146:149], v[184:187], 0
	v_mfma_i32_16x16x64_i8 v[90:93], v[160:163], v[184:187], 0
	v_mfma_i32_16x16x64_i8 v[82:85], v[160:163], v[192:195], 0
	v_mfma_i32_16x16x64_i8 v[86:89], v[146:149], v[192:195], 0
	v_mfma_i32_16x16x64_i8 v[78:81], v[146:149], v[200:203], 0
	v_mfma_i32_16x16x64_i8 v[74:77], v[160:163], v[200:203], 0
	v_mfma_i32_16x16x64_i8 v[66:69], v[160:163], v[208:211], 0
	v_mfma_i32_16x16x64_i8 v[70:73], v[146:149], v[208:211], 0
	v_mfma_i32_16x16x64_i8 v[94:97], v[150:153], v[188:191], v[94:97]
	v_mfma_i32_16x16x64_i8 v[90:93], v[164:167], v[188:191], v[90:93]
	v_mfma_i32_16x16x64_i8 v[82:85], v[164:167], v[196:199], v[82:85]
	v_mfma_i32_16x16x64_i8 v[86:89], v[150:153], v[196:199], v[86:89]
	v_mfma_i32_16x16x64_i8 v[78:81], v[150:153], v[204:207], v[78:81]
	v_mfma_i32_16x16x64_i8 v[74:77], v[164:167], v[204:207], v[74:77]
	v_mfma_i32_16x16x64_i8 v[66:69], v[164:167], v[212:215], v[66:69]
	v_mfma_i32_16x16x64_i8 v[70:73], v[150:153], v[212:215], v[70:73]
	s_setprio 0
	s_setprio 3
	v_mfma_i32_16x16x64_i8 v[30:33], v[168:171], v[184:187], 0
	v_mfma_i32_16x16x64_i8 v[26:29], v[176:179], v[184:187], 0
	v_mfma_i32_16x16x64_i8 v[18:21], v[176:179], v[192:195], 0
	v_mfma_i32_16x16x64_i8 v[22:25], v[168:171], v[192:195], 0
	v_mfma_i32_16x16x64_i8 v[14:17], v[168:171], v[200:203], 0
	v_mfma_i32_16x16x64_i8 v[10:13], v[176:179], v[200:203], 0
	v_mfma_i32_16x16x64_i8 v[2:5], v[176:179], v[208:211], 0
	v_mfma_i32_16x16x64_i8 v[6:9], v[168:171], v[208:211], 0
	v_mfma_i32_16x16x64_i8 v[30:33], v[172:175], v[188:191], v[30:33]
	v_mfma_i32_16x16x64_i8 v[26:29], v[180:183], v[188:191], v[26:29]
	v_mfma_i32_16x16x64_i8 v[18:21], v[180:183], v[196:199], v[18:21]
	v_mfma_i32_16x16x64_i8 v[22:25], v[172:175], v[196:199], v[22:25]
	v_mfma_i32_16x16x64_i8 v[14:17], v[172:175], v[204:207], v[14:17]
	v_mfma_i32_16x16x64_i8 v[10:13], v[180:183], v[204:207], v[10:13]
	v_mfma_i32_16x16x64_i8 v[2:5], v[180:183], v[212:215], v[2:5]
	v_mfma_i32_16x16x64_i8 v[6:9], v[172:175], v[212:215], v[6:9]
	s_setprio 0
	s_branch .Lzb_9_1
